# merge epilogue rewritten by hand: v_rcp sigmoid with packed f32 ops, stash and MM loads pipelined 6-12 blocks ahead
# speedup vs baseline: 1.0199x; 1.0199x over previous
; __device__ __forceinline__ float sigmoidf_(float x) { return 1.f / (1.f + __expf(-x)); }
; __device__ __forceinline__ pg8::u32x4 pack8(const f32x4 a, const f32x4 b) { pg8::u32x4 w; w.x = pg8::cvt_pk_bf16(a[0], a[1]); w.y = pg8::cvt_pk_bf16(a[2], a[3]); w.z = pg8::cvt_pk_bf16(b[0], b[1]); w.w = pg8::cvt_pk_bf16(b[2], b[3]); return w; }
; #define EPI_FOREACH(...) _Pragma("unroll") for (int ai = 0; ai < 2; ++ai) _Pragma("unroll") for (int m = 0; m < 4; ++m) _Pragma("unroll") for (int bj = 0; bj < 2; ++bj) { \
;         const int row = u.pm * 256 + ai * 128 + wr * 64 + m * 16 + fr, col = u.pn * 256 + bj * 128 + wc * 32 + 8 * fq; const f32x4 v0 = acc[ai][bj][m][0], v1 = acc[ai][bj][m][1]; (void)row; (void)col; __VA_ARGS__ }
;     __device__ __forceinline__ void operator()(const f32x4 (&acc)[2][2][4][2], const pg8::Unit& u, int wr, int wc, int fr, int fq) const {
;     ...
;         else { EPI_FOREACH( f32x4 y0, y1; unpack8(stash[((ai * 4 + m) * 2 + bj) * NT + tid], y0, y1); f32x4 t0, t1;
;                 _Pragma("unroll") for (int q = 0; q < 4; ++q) { t0[q] = sigmoidf_(v0[q]) * y0[q]; t1[q] = sigmoidf_(v1[q]) * y1[q]; }
;                 pg8::u32x4* mp = (pg8::u32x4*)((u.kind == 2 && u.aux != 0 ? PMp + (size_t)(u.aux - 1) * RC * DM - (size_t)RL * DM : MMp) + (size_t)row * DM + col);
;                 if (u.kind == 1 && u.aux != 0) { f32x4 p0, p1; unpack8(*mp, p0, p1); t0 += p0; t1 += p1; }
;                 *mp = pack8(t0, t1); ) }
.LBB0_1356:
	v_mov_b32_e32 v136, v0
	s_cmp_lg_u32 s85, 0
	v_ashrrev_i32_e32 v137, 31, v136
	s_cbranch_scc0 .LBB0_1394
	s_lshl_b32 s30, s4, 8
	v_lshlrev_b32_e32 v138, 4, v136
	v_add_u32_e32 v139, s30, v154
	v_lshl_or_b32 v132, s84, 8, v163
	v_lshlrev_b32_e32 v139, 11, v139
	v_lshl_add_u32 v139, v132, 1, v139
	s_sub_u32 s6, s86, 1
	s_ashr_i32 s7, s6, 31
	s_lshl_b64 s[6:7], s[6:7], 22
	s_add_u32 s6, s65, s6
	s_addc_u32 s7, s66, s7
	s_add_u32 s6, s6, 0xfe000000
	s_addc_u32 s7, s7, -1
	s_cmp_lg_u32 s86, 0
	s_cselect_b32 s5, 1, 0
	s_cmp_eq_u32 s85, 2
	s_cselect_b32 s8, s5, 0
	s_cmp_lg_u32 s8, 0
	s_cselect_b32 s98, s6, s44
	s_cselect_b32 s99, s7, s45
	s_cmp_eq_u32 s85, 1
	s_cselect_b32 s8, s5, 0
	s_mov_b32 s4, 0xbfb8aa3b
	s_cmp_lg_u32 s8, 0
	s_cbranch_scc0 .Lmrg0_plain
	s_add_u32 s10, s16, 0x0
	s_addc_u32 s11, s17, 0
	global_load_dwordx4 v[180:183], v138, s[10:11]
	s_add_u32 s6, s98, 0x0
	s_addc_u32 s7, s99, 0
	global_load_dwordx4 v[184:187], v139, s[6:7]
	s_add_u32 s10, s16, 0x2000
	s_addc_u32 s11, s17, 0
	global_load_dwordx4 v[188:191], v138, s[10:11]
	s_add_u32 s6, s98, 0x0
	s_addc_u32 s7, s99, 0
	global_load_dwordx4 v[192:195], v139, s[6:7] offset:256
	s_add_u32 s10, s16, 0x4000
	s_addc_u32 s11, s17, 0
	global_load_dwordx4 v[196:199], v138, s[10:11]
	s_add_u32 s6, s98, 0x8000
	s_addc_u32 s7, s99, 0
	global_load_dwordx4 v[200:203], v139, s[6:7]
	s_add_u32 s10, s16, 0x6000
	s_addc_u32 s11, s17, 0
	global_load_dwordx4 v[204:207], v138, s[10:11]
	s_add_u32 s6, s98, 0x8000
	s_addc_u32 s7, s99, 0
	global_load_dwordx4 v[208:211], v139, s[6:7] offset:256
	s_add_u32 s10, s16, 0x8000
	s_addc_u32 s11, s17, 0
	global_load_dwordx4 v[212:215], v138, s[10:11]
	s_add_u32 s6, s98, 0x10000
	s_addc_u32 s7, s99, 0
	global_load_dwordx4 v[216:219], v139, s[6:7]
	s_add_u32 s10, s16, 0xa000
	s_addc_u32 s11, s17, 0
	global_load_dwordx4 v[220:223], v138, s[10:11]
	s_add_u32 s6, s98, 0x10000
	s_addc_u32 s7, s99, 0
	global_load_dwordx4 v[224:227], v139, s[6:7] offset:256
	v_pk_mul_f32 v[140:141], v[126:127], s[4:5] op_sel_hi:[1,0]
	v_pk_mul_f32 v[142:143], v[128:129], s[4:5] op_sel_hi:[1,0]
	v_pk_mul_f32 v[144:145], v[122:123], s[4:5] op_sel_hi:[1,0]
	v_pk_mul_f32 v[146:147], v[124:125], s[4:5] op_sel_hi:[1,0]
	v_exp_f32_e32 v140, v140
	v_exp_f32_e32 v141, v141
	v_exp_f32_e32 v142, v142
	v_exp_f32_e32 v143, v143
	v_exp_f32_e32 v144, v144
	v_exp_f32_e32 v145, v145
	v_exp_f32_e32 v146, v146
	v_exp_f32_e32 v147, v147
	v_pk_add_f32 v[140:141], v[140:141], 1.0 op_sel_hi:[1,0]
	v_pk_add_f32 v[142:143], v[142:143], 1.0 op_sel_hi:[1,0]
	v_pk_add_f32 v[144:145], v[144:145], 1.0 op_sel_hi:[1,0]
	v_pk_add_f32 v[146:147], v[146:147], 1.0 op_sel_hi:[1,0]
	v_rcp_f32_e32 v140, v140
	v_rcp_f32_e32 v141, v141
	v_rcp_f32_e32 v142, v142
	v_rcp_f32_e32 v143, v143
	v_rcp_f32_e32 v144, v144
	v_rcp_f32_e32 v145, v145
	v_rcp_f32_e32 v146, v146
	v_rcp_f32_e32 v147, v147
	s_waitcnt vmcnt(10)
	v_lshlrev_b32_e32 v148, 16, v180
	v_and_b32_e32 v149, 0xffff0000, v180
	v_lshlrev_b32_e32 v150, 16, v181
	v_and_b32_e32 v151, 0xffff0000, v181
	v_lshlrev_b32_e32 v168, 16, v182
	v_and_b32_e32 v169, 0xffff0000, v182
	v_lshlrev_b32_e32 v170, 16, v183
	v_and_b32_e32 v171, 0xffff0000, v183
	v_pk_mul_f32 v[140:141], v[140:141], v[148:149]
	v_pk_mul_f32 v[142:143], v[142:143], v[150:151]
	v_pk_mul_f32 v[144:145], v[144:145], v[168:169]
	v_pk_mul_f32 v[146:147], v[146:147], v[170:171]
	v_lshlrev_b32_e32 v148, 16, v184
	v_and_b32_e32 v149, 0xffff0000, v184
	v_lshlrev_b32_e32 v150, 16, v185
	v_and_b32_e32 v151, 0xffff0000, v185
	v_lshlrev_b32_e32 v168, 16, v186
	v_and_b32_e32 v169, 0xffff0000, v186
	v_lshlrev_b32_e32 v170, 16, v187
	v_and_b32_e32 v171, 0xffff0000, v187
	v_pk_add_f32 v[140:141], v[140:141], v[148:149]
	v_pk_add_f32 v[142:143], v[142:143], v[150:151]
	v_pk_add_f32 v[144:145], v[144:145], v[168:169]
	v_pk_add_f32 v[146:147], v[146:147], v[170:171]
	v_cvt_pk_bf16_f32 v172, v140, v141
	v_cvt_pk_bf16_f32 v173, v142, v143
	v_cvt_pk_bf16_f32 v174, v144, v145
	v_cvt_pk_bf16_f32 v175, v146, v147
	s_add_u32 s10, s16, 0xc000
	s_addc_u32 s11, s17, 0
	global_load_dwordx4 v[180:183], v138, s[10:11]
	s_add_u32 s6, s98, 0x18000
	s_addc_u32 s7, s99, 0
	global_load_dwordx4 v[184:187], v139, s[6:7]
	s_add_u32 s8, s98, 0x0
	s_addc_u32 s9, s99, 0
	global_store_dwordx4 v139, v[172:175], s[8:9]
	v_pk_mul_f32 v[140:141], v[114:115], s[4:5] op_sel_hi:[1,0]
	v_pk_mul_f32 v[142:143], v[116:117], s[4:5] op_sel_hi:[1,0]
	v_pk_mul_f32 v[144:145], v[106:107], s[4:5] op_sel_hi:[1,0]
	v_pk_mul_f32 v[146:147], v[108:109], s[4:5] op_sel_hi:[1,0]
	v_exp_f32_e32 v140, v140
	v_exp_f32_e32 v141, v141
	v_exp_f32_e32 v142, v142
	v_exp_f32_e32 v143, v143
	v_exp_f32_e32 v144, v144
	v_exp_f32_e32 v145, v145
	v_exp_f32_e32 v146, v146
	v_exp_f32_e32 v147, v147
	v_pk_add_f32 v[140:141], v[140:141], 1.0 op_sel_hi:[1,0]
	v_pk_add_f32 v[142:143], v[142:143], 1.0 op_sel_hi:[1,0]
	v_pk_add_f32 v[144:145], v[144:145], 1.0 op_sel_hi:[1,0]
	v_pk_add_f32 v[146:147], v[146:147], 1.0 op_sel_hi:[1,0]
	v_rcp_f32_e32 v140, v140
	v_rcp_f32_e32 v141, v141
	v_rcp_f32_e32 v142, v142
	v_rcp_f32_e32 v143, v143
	v_rcp_f32_e32 v144, v144
	v_rcp_f32_e32 v145, v145
	v_rcp_f32_e32 v146, v146
	v_rcp_f32_e32 v147, v147
	s_waitcnt vmcnt(11)
; __device__ __forceinline__ float sigmoidf_(float x) { return 1.f / (1.f + __expf(-x)); }
; __device__ __forceinline__ pg8::u32x4 pack8(const f32x4 a, const f32x4 b) { pg8::u32x4 w; w.x = pg8::cvt_pk_bf16(a[0], a[1]); w.y = pg8::cvt_pk_bf16(a[2], a[3]); w.z = pg8::cvt_pk_bf16(b[0], b[1]); w.w = pg8::cvt_pk_bf16(b[2], b[3]); return w; }
; #define EPI_FOREACH(...) _Pragma("unroll") for (int ai = 0; ai < 2; ++ai) _Pragma("unroll") for (int m = 0; m < 4; ++m) _Pragma("unroll") for (int bj = 0; bj < 2; ++bj) { \
;         const int row = u.pm * 256 + ai * 128 + wr * 64 + m * 16 + fr, col = u.pn * 256 + bj * 128 + wc * 32 + 8 * fq; const f32x4 v0 = acc[ai][bj][m][0], v1 = acc[ai][bj][m][1]; (void)row; (void)col; __VA_ARGS__ }
;     __device__ __forceinline__ void operator()(const f32x4 (&acc)[2][2][4][2], const pg8::Unit& u, int wr, int wc, int fr, int fq) const {
;     ...
;         else { EPI_FOREACH( f32x4 y0, y1; unpack8(stash[((ai * 4 + m) * 2 + bj) * NT + tid], y0, y1); f32x4 t0, t1;
;                 _Pragma("unroll") for (int q = 0; q < 4; ++q) { t0[q] = sigmoidf_(v0[q]) * y0[q]; t1[q] = sigmoidf_(v1[q]) * y1[q]; }
;                 pg8::u32x4* mp = (pg8::u32x4*)((u.kind == 2 && u.aux != 0 ? PMp + (size_t)(u.aux - 1) * RC * DM - (size_t)RL * DM : MMp) + (size_t)row * DM + col);
;                 if (u.kind == 1 && u.aux != 0) { f32x4 p0, p1; unpack8(*mp, p0, p1); t0 += p0; t1 += p1; }
;                 *mp = pack8(t0, t1); ) }
	v_lshlrev_b32_e32 v148, 16, v188
	v_and_b32_e32 v149, 0xffff0000, v188
	v_lshlrev_b32_e32 v150, 16, v189
	v_and_b32_e32 v151, 0xffff0000, v189
	v_lshlrev_b32_e32 v168, 16, v190
	v_and_b32_e32 v169, 0xffff0000, v190
	v_lshlrev_b32_e32 v170, 16, v191
	v_and_b32_e32 v171, 0xffff0000, v191
	v_pk_mul_f32 v[140:141], v[140:141], v[148:149]
	v_pk_mul_f32 v[142:143], v[142:143], v[150:151]
	v_pk_mul_f32 v[144:145], v[144:145], v[168:169]
	v_pk_mul_f32 v[146:147], v[146:147], v[170:171]
	v_lshlrev_b32_e32 v148, 16, v192
	v_and_b32_e32 v149, 0xffff0000, v192
	v_lshlrev_b32_e32 v150, 16, v193
	v_and_b32_e32 v151, 0xffff0000, v193
	v_lshlrev_b32_e32 v168, 16, v194
	v_and_b32_e32 v169, 0xffff0000, v194
	v_lshlrev_b32_e32 v170, 16, v195
	v_and_b32_e32 v171, 0xffff0000, v195
	v_pk_add_f32 v[140:141], v[140:141], v[148:149]
	v_pk_add_f32 v[142:143], v[142:143], v[150:151]
	v_pk_add_f32 v[144:145], v[144:145], v[168:169]
	v_pk_add_f32 v[146:147], v[146:147], v[170:171]
	v_cvt_pk_bf16_f32 v176, v140, v141
	v_cvt_pk_bf16_f32 v177, v142, v143
	v_cvt_pk_bf16_f32 v178, v144, v145
	v_cvt_pk_bf16_f32 v179, v146, v147
	s_add_u32 s10, s16, 0xe000
	s_addc_u32 s11, s17, 0
	global_load_dwordx4 v[188:191], v138, s[10:11]
	s_add_u32 s6, s98, 0x18000
	s_addc_u32 s7, s99, 0
	global_load_dwordx4 v[192:195], v139, s[6:7] offset:256
	s_add_u32 s8, s98, 0x0
	s_addc_u32 s9, s99, 0
	global_store_dwordx4 v139, v[176:179], s[8:9] offset:256
	v_pk_mul_f32 v[140:141], v[118:119], s[4:5] op_sel_hi:[1,0]
	v_pk_mul_f32 v[142:143], v[120:121], s[4:5] op_sel_hi:[1,0]
	v_pk_mul_f32 v[144:145], v[110:111], s[4:5] op_sel_hi:[1,0]
	v_pk_mul_f32 v[146:147], v[112:113], s[4:5] op_sel_hi:[1,0]
	v_exp_f32_e32 v140, v140
	v_exp_f32_e32 v141, v141
	v_exp_f32_e32 v142, v142
	v_exp_f32_e32 v143, v143
	v_exp_f32_e32 v144, v144
	v_exp_f32_e32 v145, v145
	v_exp_f32_e32 v146, v146
	v_exp_f32_e32 v147, v147
	v_pk_add_f32 v[140:141], v[140:141], 1.0 op_sel_hi:[1,0]
	v_pk_add_f32 v[142:143], v[142:143], 1.0 op_sel_hi:[1,0]
	v_pk_add_f32 v[144:145], v[144:145], 1.0 op_sel_hi:[1,0]
	v_pk_add_f32 v[146:147], v[146:147], 1.0 op_sel_hi:[1,0]
	v_rcp_f32_e32 v140, v140
	v_rcp_f32_e32 v141, v141
	v_rcp_f32_e32 v142, v142
	v_rcp_f32_e32 v143, v143
	v_rcp_f32_e32 v144, v144
	v_rcp_f32_e32 v145, v145
	v_rcp_f32_e32 v146, v146
	v_rcp_f32_e32 v147, v147
	s_waitcnt vmcnt(12)
	v_lshlrev_b32_e32 v148, 16, v196
	v_and_b32_e32 v149, 0xffff0000, v196
	v_lshlrev_b32_e32 v150, 16, v197
	v_and_b32_e32 v151, 0xffff0000, v197
	v_lshlrev_b32_e32 v168, 16, v198
	v_and_b32_e32 v169, 0xffff0000, v198
	v_lshlrev_b32_e32 v170, 16, v199
	v_and_b32_e32 v171, 0xffff0000, v199
	v_pk_mul_f32 v[140:141], v[140:141], v[148:149]
	v_pk_mul_f32 v[142:143], v[142:143], v[150:151]
	v_pk_mul_f32 v[144:145], v[144:145], v[168:169]
	v_pk_mul_f32 v[146:147], v[146:147], v[170:171]
	v_lshlrev_b32_e32 v148, 16, v200
	v_and_b32_e32 v149, 0xffff0000, v200
	v_lshlrev_b32_e32 v150, 16, v201
	v_and_b32_e32 v151, 0xffff0000, v201
	v_lshlrev_b32_e32 v168, 16, v202
	v_and_b32_e32 v169, 0xffff0000, v202
	v_lshlrev_b32_e32 v170, 16, v203
	v_and_b32_e32 v171, 0xffff0000, v203
	v_pk_add_f32 v[140:141], v[140:141], v[148:149]
	v_pk_add_f32 v[142:143], v[142:143], v[150:151]
	v_pk_add_f32 v[144:145], v[144:145], v[168:169]
	v_pk_add_f32 v[146:147], v[146:147], v[170:171]
	v_cvt_pk_bf16_f32 v172, v140, v141
	v_cvt_pk_bf16_f32 v173, v142, v143
	v_cvt_pk_bf16_f32 v174, v144, v145
	v_cvt_pk_bf16_f32 v175, v146, v147
	s_add_u32 s10, s16, 0x10000
	s_addc_u32 s11, s17, 0
	global_load_dwordx4 v[196:199], v138, s[10:11]
	s_add_u32 s6, s98, 0x40000
	s_addc_u32 s7, s99, 0
	global_load_dwordx4 v[200:203], v139, s[6:7]
	s_add_u32 s8, s98, 0x8000
	s_addc_u32 s9, s99, 0
	global_store_dwordx4 v139, v[172:175], s[8:9]
	v_pk_mul_f32 v[140:141], v[98:99], s[4:5] op_sel_hi:[1,0]
	v_pk_mul_f32 v[142:143], v[100:101], s[4:5] op_sel_hi:[1,0]
	v_pk_mul_f32 v[144:145], v[90:91], s[4:5] op_sel_hi:[1,0]
	v_pk_mul_f32 v[146:147], v[92:93], s[4:5] op_sel_hi:[1,0]
	v_exp_f32_e32 v140, v140
	v_exp_f32_e32 v141, v141
	v_exp_f32_e32 v142, v142
	v_exp_f32_e32 v143, v143
	v_exp_f32_e32 v144, v144
	v_exp_f32_e32 v145, v145
	v_exp_f32_e32 v146, v146
	v_exp_f32_e32 v147, v147
	v_pk_add_f32 v[140:141], v[140:141], 1.0 op_sel_hi:[1,0]
	v_pk_add_f32 v[142:143], v[142:143], 1.0 op_sel_hi:[1,0]
	v_pk_add_f32 v[144:145], v[144:145], 1.0 op_sel_hi:[1,0]
	v_pk_add_f32 v[146:147], v[146:147], 1.0 op_sel_hi:[1,0]
	v_rcp_f32_e32 v140, v140
	v_rcp_f32_e32 v141, v141
	v_rcp_f32_e32 v142, v142
	v_rcp_f32_e32 v143, v143
	v_rcp_f32_e32 v144, v144
	v_rcp_f32_e32 v145, v145
	v_rcp_f32_e32 v146, v146
	v_rcp_f32_e32 v147, v147
	s_waitcnt vmcnt(13)
; __device__ __forceinline__ float sigmoidf_(float x) { return 1.f / (1.f + __expf(-x)); }
; __device__ __forceinline__ pg8::u32x4 pack8(const f32x4 a, const f32x4 b) { pg8::u32x4 w; w.x = pg8::cvt_pk_bf16(a[0], a[1]); w.y = pg8::cvt_pk_bf16(a[2], a[3]); w.z = pg8::cvt_pk_bf16(b[0], b[1]); w.w = pg8::cvt_pk_bf16(b[2], b[3]); return w; }
; #define EPI_FOREACH(...) _Pragma("unroll") for (int ai = 0; ai < 2; ++ai) _Pragma("unroll") for (int m = 0; m < 4; ++m) _Pragma("unroll") for (int bj = 0; bj < 2; ++bj) { \
;         const int row = u.pm * 256 + ai * 128 + wr * 64 + m * 16 + fr, col = u.pn * 256 + bj * 128 + wc * 32 + 8 * fq; const f32x4 v0 = acc[ai][bj][m][0], v1 = acc[ai][bj][m][1]; (void)row; (void)col; __VA_ARGS__ }
;     __device__ __forceinline__ void operator()(const f32x4 (&acc)[2][2][4][2], const pg8::Unit& u, int wr, int wc, int fr, int fq) const {
;     ...
;         else { EPI_FOREACH( f32x4 y0, y1; unpack8(stash[((ai * 4 + m) * 2 + bj) * NT + tid], y0, y1); f32x4 t0, t1;
;                 _Pragma("unroll") for (int q = 0; q < 4; ++q) { t0[q] = sigmoidf_(v0[q]) * y0[q]; t1[q] = sigmoidf_(v1[q]) * y1[q]; }
;                 pg8::u32x4* mp = (pg8::u32x4*)((u.kind == 2 && u.aux != 0 ? PMp + (size_t)(u.aux - 1) * RC * DM - (size_t)RL * DM : MMp) + (size_t)row * DM + col);
;                 if (u.kind == 1 && u.aux != 0) { f32x4 p0, p1; unpack8(*mp, p0, p1); t0 += p0; t1 += p1; }
;                 *mp = pack8(t0, t1); ) }
	v_lshlrev_b32_e32 v148, 16, v204
	v_and_b32_e32 v149, 0xffff0000, v204
	v_lshlrev_b32_e32 v150, 16, v205
	v_and_b32_e32 v151, 0xffff0000, v205
	v_lshlrev_b32_e32 v168, 16, v206
	v_and_b32_e32 v169, 0xffff0000, v206
	v_lshlrev_b32_e32 v170, 16, v207
	v_and_b32_e32 v171, 0xffff0000, v207
	v_pk_mul_f32 v[140:141], v[140:141], v[148:149]
	v_pk_mul_f32 v[142:143], v[142:143], v[150:151]
	v_pk_mul_f32 v[144:145], v[144:145], v[168:169]
	v_pk_mul_f32 v[146:147], v[146:147], v[170:171]
	v_lshlrev_b32_e32 v148, 16, v208
	v_and_b32_e32 v149, 0xffff0000, v208
	v_lshlrev_b32_e32 v150, 16, v209
	v_and_b32_e32 v151, 0xffff0000, v209
	v_lshlrev_b32_e32 v168, 16, v210
	v_and_b32_e32 v169, 0xffff0000, v210
	v_lshlrev_b32_e32 v170, 16, v211
	v_and_b32_e32 v171, 0xffff0000, v211
	v_pk_add_f32 v[140:141], v[140:141], v[148:149]
	v_pk_add_f32 v[142:143], v[142:143], v[150:151]
	v_pk_add_f32 v[144:145], v[144:145], v[168:169]
	v_pk_add_f32 v[146:147], v[146:147], v[170:171]
	v_cvt_pk_bf16_f32 v176, v140, v141
	v_cvt_pk_bf16_f32 v177, v142, v143
	v_cvt_pk_bf16_f32 v178, v144, v145
	v_cvt_pk_bf16_f32 v179, v146, v147
	s_add_u32 s10, s16, 0x12000
	s_addc_u32 s11, s17, 0
	global_load_dwordx4 v[204:207], v138, s[10:11]
	s_add_u32 s6, s98, 0x40000
	s_addc_u32 s7, s99, 0
	global_load_dwordx4 v[208:211], v139, s[6:7] offset:256
	s_add_u32 s8, s98, 0x8000
	s_addc_u32 s9, s99, 0
	global_store_dwordx4 v139, v[176:179], s[8:9] offset:256
	v_pk_mul_f32 v[140:141], v[102:103], s[4:5] op_sel_hi:[1,0]
	v_pk_mul_f32 v[142:143], v[104:105], s[4:5] op_sel_hi:[1,0]
	v_pk_mul_f32 v[144:145], v[94:95], s[4:5] op_sel_hi:[1,0]
	v_pk_mul_f32 v[146:147], v[96:97], s[4:5] op_sel_hi:[1,0]
	v_exp_f32_e32 v140, v140
	v_exp_f32_e32 v141, v141
	v_exp_f32_e32 v142, v142
	v_exp_f32_e32 v143, v143
	v_exp_f32_e32 v144, v144
	v_exp_f32_e32 v145, v145
	v_exp_f32_e32 v146, v146
	v_exp_f32_e32 v147, v147
	v_pk_add_f32 v[140:141], v[140:141], 1.0 op_sel_hi:[1,0]
	v_pk_add_f32 v[142:143], v[142:143], 1.0 op_sel_hi:[1,0]
	v_pk_add_f32 v[144:145], v[144:145], 1.0 op_sel_hi:[1,0]
	v_pk_add_f32 v[146:147], v[146:147], 1.0 op_sel_hi:[1,0]
	v_rcp_f32_e32 v140, v140
	v_rcp_f32_e32 v141, v141
	v_rcp_f32_e32 v142, v142
	v_rcp_f32_e32 v143, v143
	v_rcp_f32_e32 v144, v144
	v_rcp_f32_e32 v145, v145
	v_rcp_f32_e32 v146, v146
	v_rcp_f32_e32 v147, v147
	s_waitcnt vmcnt(14)
	v_lshlrev_b32_e32 v148, 16, v212
	v_and_b32_e32 v149, 0xffff0000, v212
	v_lshlrev_b32_e32 v150, 16, v213
	v_and_b32_e32 v151, 0xffff0000, v213
	v_lshlrev_b32_e32 v168, 16, v214
	v_and_b32_e32 v169, 0xffff0000, v214
	v_lshlrev_b32_e32 v170, 16, v215
	v_and_b32_e32 v171, 0xffff0000, v215
	v_pk_mul_f32 v[140:141], v[140:141], v[148:149]
	v_pk_mul_f32 v[142:143], v[142:143], v[150:151]
	v_pk_mul_f32 v[144:145], v[144:145], v[168:169]
	v_pk_mul_f32 v[146:147], v[146:147], v[170:171]
	v_lshlrev_b32_e32 v148, 16, v216
	v_and_b32_e32 v149, 0xffff0000, v216
	v_lshlrev_b32_e32 v150, 16, v217
	v_and_b32_e32 v151, 0xffff0000, v217
	v_lshlrev_b32_e32 v168, 16, v218
	v_and_b32_e32 v169, 0xffff0000, v218
	v_lshlrev_b32_e32 v170, 16, v219
	v_and_b32_e32 v171, 0xffff0000, v219
	v_pk_add_f32 v[140:141], v[140:141], v[148:149]
	v_pk_add_f32 v[142:143], v[142:143], v[150:151]
	v_pk_add_f32 v[144:145], v[144:145], v[168:169]
	v_pk_add_f32 v[146:147], v[146:147], v[170:171]
	v_cvt_pk_bf16_f32 v172, v140, v141
	v_cvt_pk_bf16_f32 v173, v142, v143
	v_cvt_pk_bf16_f32 v174, v144, v145
	v_cvt_pk_bf16_f32 v175, v146, v147
	s_add_u32 s10, s16, 0x14000
	s_addc_u32 s11, s17, 0
	global_load_dwordx4 v[212:215], v138, s[10:11]
	s_add_u32 s6, s98, 0x48000
	s_addc_u32 s7, s99, 0
	global_load_dwordx4 v[216:219], v139, s[6:7]
	s_add_u32 s8, s98, 0x10000
	s_addc_u32 s9, s99, 0
	global_store_dwordx4 v139, v[172:175], s[8:9]
	v_pk_mul_f32 v[140:141], v[82:83], s[4:5] op_sel_hi:[1,0]
	v_pk_mul_f32 v[142:143], v[84:85], s[4:5] op_sel_hi:[1,0]
	v_pk_mul_f32 v[144:145], v[74:75], s[4:5] op_sel_hi:[1,0]
	v_pk_mul_f32 v[146:147], v[76:77], s[4:5] op_sel_hi:[1,0]
	v_exp_f32_e32 v140, v140
	v_exp_f32_e32 v141, v141
	v_exp_f32_e32 v142, v142
	v_exp_f32_e32 v143, v143
	v_exp_f32_e32 v144, v144
	v_exp_f32_e32 v145, v145
	v_exp_f32_e32 v146, v146
	v_exp_f32_e32 v147, v147
	v_pk_add_f32 v[140:141], v[140:141], 1.0 op_sel_hi:[1,0]
	v_pk_add_f32 v[142:143], v[142:143], 1.0 op_sel_hi:[1,0]
	v_pk_add_f32 v[144:145], v[144:145], 1.0 op_sel_hi:[1,0]
	v_pk_add_f32 v[146:147], v[146:147], 1.0 op_sel_hi:[1,0]
	v_rcp_f32_e32 v140, v140
	v_rcp_f32_e32 v141, v141
	v_rcp_f32_e32 v142, v142
	v_rcp_f32_e32 v143, v143
	v_rcp_f32_e32 v144, v144
	v_rcp_f32_e32 v145, v145
	v_rcp_f32_e32 v146, v146
	v_rcp_f32_e32 v147, v147
	s_waitcnt vmcnt(15)
; __device__ __forceinline__ float sigmoidf_(float x) { return 1.f / (1.f + __expf(-x)); }
; __device__ __forceinline__ pg8::u32x4 pack8(const f32x4 a, const f32x4 b) { pg8::u32x4 w; w.x = pg8::cvt_pk_bf16(a[0], a[1]); w.y = pg8::cvt_pk_bf16(a[2], a[3]); w.z = pg8::cvt_pk_bf16(b[0], b[1]); w.w = pg8::cvt_pk_bf16(b[2], b[3]); return w; }
; #define EPI_FOREACH(...) _Pragma("unroll") for (int ai = 0; ai < 2; ++ai) _Pragma("unroll") for (int m = 0; m < 4; ++m) _Pragma("unroll") for (int bj = 0; bj < 2; ++bj) { \
;         const int row = u.pm * 256 + ai * 128 + wr * 64 + m * 16 + fr, col = u.pn * 256 + bj * 128 + wc * 32 + 8 * fq; const f32x4 v0 = acc[ai][bj][m][0], v1 = acc[ai][bj][m][1]; (void)row; (void)col; __VA_ARGS__ }
;     __device__ __forceinline__ void operator()(const f32x4 (&acc)[2][2][4][2], const pg8::Unit& u, int wr, int wc, int fr, int fq) const {
;     ...
;         else { EPI_FOREACH( f32x4 y0, y1; unpack8(stash[((ai * 4 + m) * 2 + bj) * NT + tid], y0, y1); f32x4 t0, t1;
;                 _Pragma("unroll") for (int q = 0; q < 4; ++q) { t0[q] = sigmoidf_(v0[q]) * y0[q]; t1[q] = sigmoidf_(v1[q]) * y1[q]; }
;                 pg8::u32x4* mp = (pg8::u32x4*)((u.kind == 2 && u.aux != 0 ? PMp + (size_t)(u.aux - 1) * RC * DM - (size_t)RL * DM : MMp) + (size_t)row * DM + col);
;                 if (u.kind == 1 && u.aux != 0) { f32x4 p0, p1; unpack8(*mp, p0, p1); t0 += p0; t1 += p1; }
;                 *mp = pack8(t0, t1); ) }
	v_lshlrev_b32_e32 v148, 16, v220
	v_and_b32_e32 v149, 0xffff0000, v220
	v_lshlrev_b32_e32 v150, 16, v221
	v_and_b32_e32 v151, 0xffff0000, v221
	v_lshlrev_b32_e32 v168, 16, v222
	v_and_b32_e32 v169, 0xffff0000, v222
	v_lshlrev_b32_e32 v170, 16, v223
	v_and_b32_e32 v171, 0xffff0000, v223
	v_pk_mul_f32 v[140:141], v[140:141], v[148:149]
	v_pk_mul_f32 v[142:143], v[142:143], v[150:151]
	v_pk_mul_f32 v[144:145], v[144:145], v[168:169]
	v_pk_mul_f32 v[146:147], v[146:147], v[170:171]
	v_lshlrev_b32_e32 v148, 16, v224
	v_and_b32_e32 v149, 0xffff0000, v224
	v_lshlrev_b32_e32 v150, 16, v225
	v_and_b32_e32 v151, 0xffff0000, v225
	v_lshlrev_b32_e32 v168, 16, v226
	v_and_b32_e32 v169, 0xffff0000, v226
	v_lshlrev_b32_e32 v170, 16, v227
	v_and_b32_e32 v171, 0xffff0000, v227
	v_pk_add_f32 v[140:141], v[140:141], v[148:149]
	v_pk_add_f32 v[142:143], v[142:143], v[150:151]
	v_pk_add_f32 v[144:145], v[144:145], v[168:169]
	v_pk_add_f32 v[146:147], v[146:147], v[170:171]
	v_cvt_pk_bf16_f32 v176, v140, v141
	v_cvt_pk_bf16_f32 v177, v142, v143
	v_cvt_pk_bf16_f32 v178, v144, v145
	v_cvt_pk_bf16_f32 v179, v146, v147
	s_add_u32 s10, s16, 0x16000
	s_addc_u32 s11, s17, 0
	global_load_dwordx4 v[220:223], v138, s[10:11]
	s_add_u32 s6, s98, 0x48000
	s_addc_u32 s7, s99, 0
	global_load_dwordx4 v[224:227], v139, s[6:7] offset:256
	s_add_u32 s8, s98, 0x10000
	s_addc_u32 s9, s99, 0
	global_store_dwordx4 v139, v[176:179], s[8:9] offset:256
	v_pk_mul_f32 v[140:141], v[86:87], s[4:5] op_sel_hi:[1,0]
	v_pk_mul_f32 v[142:143], v[88:89], s[4:5] op_sel_hi:[1,0]
	v_pk_mul_f32 v[144:145], v[78:79], s[4:5] op_sel_hi:[1,0]
	v_pk_mul_f32 v[146:147], v[80:81], s[4:5] op_sel_hi:[1,0]
	v_exp_f32_e32 v140, v140
	v_exp_f32_e32 v141, v141
	v_exp_f32_e32 v142, v142
	v_exp_f32_e32 v143, v143
	v_exp_f32_e32 v144, v144
	v_exp_f32_e32 v145, v145
	v_exp_f32_e32 v146, v146
	v_exp_f32_e32 v147, v147
	v_pk_add_f32 v[140:141], v[140:141], 1.0 op_sel_hi:[1,0]
	v_pk_add_f32 v[142:143], v[142:143], 1.0 op_sel_hi:[1,0]
	v_pk_add_f32 v[144:145], v[144:145], 1.0 op_sel_hi:[1,0]
	v_pk_add_f32 v[146:147], v[146:147], 1.0 op_sel_hi:[1,0]
	v_rcp_f32_e32 v140, v140
	v_rcp_f32_e32 v141, v141
	v_rcp_f32_e32 v142, v142
	v_rcp_f32_e32 v143, v143
	v_rcp_f32_e32 v144, v144
	v_rcp_f32_e32 v145, v145
	v_rcp_f32_e32 v146, v146
	v_rcp_f32_e32 v147, v147
	s_waitcnt vmcnt(16)
	v_lshlrev_b32_e32 v148, 16, v180
	v_and_b32_e32 v149, 0xffff0000, v180
	v_lshlrev_b32_e32 v150, 16, v181
	v_and_b32_e32 v151, 0xffff0000, v181
	v_lshlrev_b32_e32 v168, 16, v182
	v_and_b32_e32 v169, 0xffff0000, v182
	v_lshlrev_b32_e32 v170, 16, v183
	v_and_b32_e32 v171, 0xffff0000, v183
	v_pk_mul_f32 v[140:141], v[140:141], v[148:149]
	v_pk_mul_f32 v[142:143], v[142:143], v[150:151]
	v_pk_mul_f32 v[144:145], v[144:145], v[168:169]
	v_pk_mul_f32 v[146:147], v[146:147], v[170:171]
	v_lshlrev_b32_e32 v148, 16, v184
	v_and_b32_e32 v149, 0xffff0000, v184
	v_lshlrev_b32_e32 v150, 16, v185
	v_and_b32_e32 v151, 0xffff0000, v185
	v_lshlrev_b32_e32 v168, 16, v186
	v_and_b32_e32 v169, 0xffff0000, v186
	v_lshlrev_b32_e32 v170, 16, v187
	v_and_b32_e32 v171, 0xffff0000, v187
	v_pk_add_f32 v[140:141], v[140:141], v[148:149]
	v_pk_add_f32 v[142:143], v[142:143], v[150:151]
	v_pk_add_f32 v[144:145], v[144:145], v[168:169]
	v_pk_add_f32 v[146:147], v[146:147], v[170:171]
	v_cvt_pk_bf16_f32 v172, v140, v141
	v_cvt_pk_bf16_f32 v173, v142, v143
	v_cvt_pk_bf16_f32 v174, v144, v145
	v_cvt_pk_bf16_f32 v175, v146, v147
	s_add_u32 s10, s16, 0x18000
	s_addc_u32 s11, s17, 0
	global_load_dwordx4 v[180:183], v138, s[10:11]
	s_add_u32 s6, s98, 0x50000
	s_addc_u32 s7, s99, 0
	global_load_dwordx4 v[184:187], v139, s[6:7]
	s_add_u32 s8, s98, 0x18000
	s_addc_u32 s9, s99, 0
	global_store_dwordx4 v139, v[172:175], s[8:9]
	v_pk_mul_f32 v[140:141], v[70:71], s[4:5] op_sel_hi:[1,0]
	v_pk_mul_f32 v[142:143], v[72:73], s[4:5] op_sel_hi:[1,0]
	v_pk_mul_f32 v[144:145], v[66:67], s[4:5] op_sel_hi:[1,0]
	v_pk_mul_f32 v[146:147], v[68:69], s[4:5] op_sel_hi:[1,0]
	v_exp_f32_e32 v140, v140
	v_exp_f32_e32 v141, v141
	v_exp_f32_e32 v142, v142
	v_exp_f32_e32 v143, v143
	v_exp_f32_e32 v144, v144
	v_exp_f32_e32 v145, v145
	v_exp_f32_e32 v146, v146
	v_exp_f32_e32 v147, v147
	v_pk_add_f32 v[140:141], v[140:141], 1.0 op_sel_hi:[1,0]
	v_pk_add_f32 v[142:143], v[142:143], 1.0 op_sel_hi:[1,0]
	v_pk_add_f32 v[144:145], v[144:145], 1.0 op_sel_hi:[1,0]
	v_pk_add_f32 v[146:147], v[146:147], 1.0 op_sel_hi:[1,0]
	v_rcp_f32_e32 v140, v140
	v_rcp_f32_e32 v141, v141
	v_rcp_f32_e32 v142, v142
	v_rcp_f32_e32 v143, v143
	v_rcp_f32_e32 v144, v144
	v_rcp_f32_e32 v145, v145
	v_rcp_f32_e32 v146, v146
	v_rcp_f32_e32 v147, v147
	s_waitcnt vmcnt(16)
; __device__ __forceinline__ float sigmoidf_(float x) { return 1.f / (1.f + __expf(-x)); }
; __device__ __forceinline__ pg8::u32x4 pack8(const f32x4 a, const f32x4 b) { pg8::u32x4 w; w.x = pg8::cvt_pk_bf16(a[0], a[1]); w.y = pg8::cvt_pk_bf16(a[2], a[3]); w.z = pg8::cvt_pk_bf16(b[0], b[1]); w.w = pg8::cvt_pk_bf16(b[2], b[3]); return w; }
; #define EPI_FOREACH(...) _Pragma("unroll") for (int ai = 0; ai < 2; ++ai) _Pragma("unroll") for (int m = 0; m < 4; ++m) _Pragma("unroll") for (int bj = 0; bj < 2; ++bj) { \
;         const int row = u.pm * 256 + ai * 128 + wr * 64 + m * 16 + fr, col = u.pn * 256 + bj * 128 + wc * 32 + 8 * fq; const f32x4 v0 = acc[ai][bj][m][0], v1 = acc[ai][bj][m][1]; (void)row; (void)col; __VA_ARGS__ }
;     __device__ __forceinline__ void operator()(const f32x4 (&acc)[2][2][4][2], const pg8::Unit& u, int wr, int wc, int fr, int fq) const {
;     ...
;         else { EPI_FOREACH( f32x4 y0, y1; unpack8(stash[((ai * 4 + m) * 2 + bj) * NT + tid], y0, y1); f32x4 t0, t1;
;                 _Pragma("unroll") for (int q = 0; q < 4; ++q) { t0[q] = sigmoidf_(v0[q]) * y0[q]; t1[q] = sigmoidf_(v1[q]) * y1[q]; }
;                 pg8::u32x4* mp = (pg8::u32x4*)((u.kind == 2 && u.aux != 0 ? PMp + (size_t)(u.aux - 1) * RC * DM - (size_t)RL * DM : MMp) + (size_t)row * DM + col);
;                 if (u.kind == 1 && u.aux != 0) { f32x4 p0, p1; unpack8(*mp, p0, p1); t0 += p0; t1 += p1; }
;                 *mp = pack8(t0, t1); ) }
	v_lshlrev_b32_e32 v148, 16, v188
	v_and_b32_e32 v149, 0xffff0000, v188
	v_lshlrev_b32_e32 v150, 16, v189
	v_and_b32_e32 v151, 0xffff0000, v189
	v_lshlrev_b32_e32 v168, 16, v190
	v_and_b32_e32 v169, 0xffff0000, v190
	v_lshlrev_b32_e32 v170, 16, v191
	v_and_b32_e32 v171, 0xffff0000, v191
	v_pk_mul_f32 v[140:141], v[140:141], v[148:149]
	v_pk_mul_f32 v[142:143], v[142:143], v[150:151]
	v_pk_mul_f32 v[144:145], v[144:145], v[168:169]
	v_pk_mul_f32 v[146:147], v[146:147], v[170:171]
	v_lshlrev_b32_e32 v148, 16, v192
	v_and_b32_e32 v149, 0xffff0000, v192
	v_lshlrev_b32_e32 v150, 16, v193
	v_and_b32_e32 v151, 0xffff0000, v193
	v_lshlrev_b32_e32 v168, 16, v194
	v_and_b32_e32 v169, 0xffff0000, v194
	v_lshlrev_b32_e32 v170, 16, v195
	v_and_b32_e32 v171, 0xffff0000, v195
	v_pk_add_f32 v[140:141], v[140:141], v[148:149]
	v_pk_add_f32 v[142:143], v[142:143], v[150:151]
	v_pk_add_f32 v[144:145], v[144:145], v[168:169]
	v_pk_add_f32 v[146:147], v[146:147], v[170:171]
	v_cvt_pk_bf16_f32 v176, v140, v141
	v_cvt_pk_bf16_f32 v177, v142, v143
	v_cvt_pk_bf16_f32 v178, v144, v145
	v_cvt_pk_bf16_f32 v179, v146, v147
	s_add_u32 s10, s16, 0x1a000
	s_addc_u32 s11, s17, 0
	global_load_dwordx4 v[188:191], v138, s[10:11]
	s_add_u32 s6, s98, 0x50000
	s_addc_u32 s7, s99, 0
	global_load_dwordx4 v[192:195], v139, s[6:7] offset:256
	s_add_u32 s8, s98, 0x18000
	s_addc_u32 s9, s99, 0
	global_store_dwordx4 v139, v[176:179], s[8:9] offset:256
	v_pk_mul_f32 v[140:141], v[62:63], s[4:5] op_sel_hi:[1,0]
	v_pk_mul_f32 v[142:143], v[64:65], s[4:5] op_sel_hi:[1,0]
	v_pk_mul_f32 v[144:145], v[58:59], s[4:5] op_sel_hi:[1,0]
	v_pk_mul_f32 v[146:147], v[60:61], s[4:5] op_sel_hi:[1,0]
	v_exp_f32_e32 v140, v140
	v_exp_f32_e32 v141, v141
	v_exp_f32_e32 v142, v142
	v_exp_f32_e32 v143, v143
	v_exp_f32_e32 v144, v144
	v_exp_f32_e32 v145, v145
	v_exp_f32_e32 v146, v146
	v_exp_f32_e32 v147, v147
	v_pk_add_f32 v[140:141], v[140:141], 1.0 op_sel_hi:[1,0]
	v_pk_add_f32 v[142:143], v[142:143], 1.0 op_sel_hi:[1,0]
	v_pk_add_f32 v[144:145], v[144:145], 1.0 op_sel_hi:[1,0]
	v_pk_add_f32 v[146:147], v[146:147], 1.0 op_sel_hi:[1,0]
	v_rcp_f32_e32 v140, v140
	v_rcp_f32_e32 v141, v141
	v_rcp_f32_e32 v142, v142
	v_rcp_f32_e32 v143, v143
	v_rcp_f32_e32 v144, v144
	v_rcp_f32_e32 v145, v145
	v_rcp_f32_e32 v146, v146
	v_rcp_f32_e32 v147, v147
	s_waitcnt vmcnt(16)
	v_lshlrev_b32_e32 v148, 16, v196
	v_and_b32_e32 v149, 0xffff0000, v196
	v_lshlrev_b32_e32 v150, 16, v197
	v_and_b32_e32 v151, 0xffff0000, v197
	v_lshlrev_b32_e32 v168, 16, v198
	v_and_b32_e32 v169, 0xffff0000, v198
	v_lshlrev_b32_e32 v170, 16, v199
	v_and_b32_e32 v171, 0xffff0000, v199
	v_pk_mul_f32 v[140:141], v[140:141], v[148:149]
	v_pk_mul_f32 v[142:143], v[142:143], v[150:151]
	v_pk_mul_f32 v[144:145], v[144:145], v[168:169]
	v_pk_mul_f32 v[146:147], v[146:147], v[170:171]
	v_lshlrev_b32_e32 v148, 16, v200
	v_and_b32_e32 v149, 0xffff0000, v200
	v_lshlrev_b32_e32 v150, 16, v201
	v_and_b32_e32 v151, 0xffff0000, v201
	v_lshlrev_b32_e32 v168, 16, v202
	v_and_b32_e32 v169, 0xffff0000, v202
	v_lshlrev_b32_e32 v170, 16, v203
	v_and_b32_e32 v171, 0xffff0000, v203
	v_pk_add_f32 v[140:141], v[140:141], v[148:149]
	v_pk_add_f32 v[142:143], v[142:143], v[150:151]
	v_pk_add_f32 v[144:145], v[144:145], v[168:169]
	v_pk_add_f32 v[146:147], v[146:147], v[170:171]
	v_cvt_pk_bf16_f32 v172, v140, v141
	v_cvt_pk_bf16_f32 v173, v142, v143
	v_cvt_pk_bf16_f32 v174, v144, v145
	v_cvt_pk_bf16_f32 v175, v146, v147
	s_add_u32 s10, s16, 0x1c000
	s_addc_u32 s11, s17, 0
	global_load_dwordx4 v[196:199], v138, s[10:11]
	s_add_u32 s6, s98, 0x58000
	s_addc_u32 s7, s99, 0
	global_load_dwordx4 v[200:203], v139, s[6:7]
	s_add_u32 s8, s98, 0x40000
	s_addc_u32 s9, s99, 0
	global_store_dwordx4 v139, v[172:175], s[8:9]
	v_pk_mul_f32 v[140:141], v[50:51], s[4:5] op_sel_hi:[1,0]
	v_pk_mul_f32 v[142:143], v[52:53], s[4:5] op_sel_hi:[1,0]
	v_pk_mul_f32 v[144:145], v[42:43], s[4:5] op_sel_hi:[1,0]
	v_pk_mul_f32 v[146:147], v[44:45], s[4:5] op_sel_hi:[1,0]
	v_exp_f32_e32 v140, v140
	v_exp_f32_e32 v141, v141
	v_exp_f32_e32 v142, v142
	v_exp_f32_e32 v143, v143
	v_exp_f32_e32 v144, v144
	v_exp_f32_e32 v145, v145
	v_exp_f32_e32 v146, v146
	v_exp_f32_e32 v147, v147
	v_pk_add_f32 v[140:141], v[140:141], 1.0 op_sel_hi:[1,0]
	v_pk_add_f32 v[142:143], v[142:143], 1.0 op_sel_hi:[1,0]
	v_pk_add_f32 v[144:145], v[144:145], 1.0 op_sel_hi:[1,0]
	v_pk_add_f32 v[146:147], v[146:147], 1.0 op_sel_hi:[1,0]
	v_rcp_f32_e32 v140, v140
	v_rcp_f32_e32 v141, v141
	v_rcp_f32_e32 v142, v142
	v_rcp_f32_e32 v143, v143
	v_rcp_f32_e32 v144, v144
	v_rcp_f32_e32 v145, v145
	v_rcp_f32_e32 v146, v146
	v_rcp_f32_e32 v147, v147
	s_waitcnt vmcnt(16)
; __device__ __forceinline__ float sigmoidf_(float x) { return 1.f / (1.f + __expf(-x)); }
; __device__ __forceinline__ pg8::u32x4 pack8(const f32x4 a, const f32x4 b) { pg8::u32x4 w; w.x = pg8::cvt_pk_bf16(a[0], a[1]); w.y = pg8::cvt_pk_bf16(a[2], a[3]); w.z = pg8::cvt_pk_bf16(b[0], b[1]); w.w = pg8::cvt_pk_bf16(b[2], b[3]); return w; }
; #define EPI_FOREACH(...) _Pragma("unroll") for (int ai = 0; ai < 2; ++ai) _Pragma("unroll") for (int m = 0; m < 4; ++m) _Pragma("unroll") for (int bj = 0; bj < 2; ++bj) { \
;         const int row = u.pm * 256 + ai * 128 + wr * 64 + m * 16 + fr, col = u.pn * 256 + bj * 128 + wc * 32 + 8 * fq; const f32x4 v0 = acc[ai][bj][m][0], v1 = acc[ai][bj][m][1]; (void)row; (void)col; __VA_ARGS__ }
;     __device__ __forceinline__ void operator()(const f32x4 (&acc)[2][2][4][2], const pg8::Unit& u, int wr, int wc, int fr, int fq) const {
;     ...
;         else { EPI_FOREACH( f32x4 y0, y1; unpack8(stash[((ai * 4 + m) * 2 + bj) * NT + tid], y0, y1); f32x4 t0, t1;
;                 _Pragma("unroll") for (int q = 0; q < 4; ++q) { t0[q] = sigmoidf_(v0[q]) * y0[q]; t1[q] = sigmoidf_(v1[q]) * y1[q]; }
;                 pg8::u32x4* mp = (pg8::u32x4*)((u.kind == 2 && u.aux != 0 ? PMp + (size_t)(u.aux - 1) * RC * DM - (size_t)RL * DM : MMp) + (size_t)row * DM + col);
;                 if (u.kind == 1 && u.aux != 0) { f32x4 p0, p1; unpack8(*mp, p0, p1); t0 += p0; t1 += p1; }
;                 *mp = pack8(t0, t1); ) }
	v_lshlrev_b32_e32 v148, 16, v204
	v_and_b32_e32 v149, 0xffff0000, v204
	v_lshlrev_b32_e32 v150, 16, v205
	v_and_b32_e32 v151, 0xffff0000, v205
	v_lshlrev_b32_e32 v168, 16, v206
	v_and_b32_e32 v169, 0xffff0000, v206
	v_lshlrev_b32_e32 v170, 16, v207
	v_and_b32_e32 v171, 0xffff0000, v207
	v_pk_mul_f32 v[140:141], v[140:141], v[148:149]
	v_pk_mul_f32 v[142:143], v[142:143], v[150:151]
	v_pk_mul_f32 v[144:145], v[144:145], v[168:169]
	v_pk_mul_f32 v[146:147], v[146:147], v[170:171]
	v_lshlrev_b32_e32 v148, 16, v208
	v_and_b32_e32 v149, 0xffff0000, v208
	v_lshlrev_b32_e32 v150, 16, v209
	v_and_b32_e32 v151, 0xffff0000, v209
	v_lshlrev_b32_e32 v168, 16, v210
	v_and_b32_e32 v169, 0xffff0000, v210
	v_lshlrev_b32_e32 v170, 16, v211
	v_and_b32_e32 v171, 0xffff0000, v211
	v_pk_add_f32 v[140:141], v[140:141], v[148:149]
	v_pk_add_f32 v[142:143], v[142:143], v[150:151]
	v_pk_add_f32 v[144:145], v[144:145], v[168:169]
	v_pk_add_f32 v[146:147], v[146:147], v[170:171]
	v_cvt_pk_bf16_f32 v176, v140, v141
	v_cvt_pk_bf16_f32 v177, v142, v143
	v_cvt_pk_bf16_f32 v178, v144, v145
	v_cvt_pk_bf16_f32 v179, v146, v147
	s_add_u32 s10, s16, 0x1e000
	s_addc_u32 s11, s17, 0
	global_load_dwordx4 v[204:207], v138, s[10:11]
	s_add_u32 s6, s98, 0x58000
	s_addc_u32 s7, s99, 0
	global_load_dwordx4 v[208:211], v139, s[6:7] offset:256
	s_add_u32 s8, s98, 0x40000
	s_addc_u32 s9, s99, 0
	global_store_dwordx4 v139, v[176:179], s[8:9] offset:256
	v_pk_mul_f32 v[140:141], v[54:55], s[4:5] op_sel_hi:[1,0]
	v_pk_mul_f32 v[142:143], v[56:57], s[4:5] op_sel_hi:[1,0]
	v_pk_mul_f32 v[144:145], v[46:47], s[4:5] op_sel_hi:[1,0]
	v_pk_mul_f32 v[146:147], v[48:49], s[4:5] op_sel_hi:[1,0]
	v_exp_f32_e32 v140, v140
	v_exp_f32_e32 v141, v141
	v_exp_f32_e32 v142, v142
	v_exp_f32_e32 v143, v143
	v_exp_f32_e32 v144, v144
	v_exp_f32_e32 v145, v145
	v_exp_f32_e32 v146, v146
	v_exp_f32_e32 v147, v147
	v_pk_add_f32 v[140:141], v[140:141], 1.0 op_sel_hi:[1,0]
	v_pk_add_f32 v[142:143], v[142:143], 1.0 op_sel_hi:[1,0]
	v_pk_add_f32 v[144:145], v[144:145], 1.0 op_sel_hi:[1,0]
	v_pk_add_f32 v[146:147], v[146:147], 1.0 op_sel_hi:[1,0]
	v_rcp_f32_e32 v140, v140
	v_rcp_f32_e32 v141, v141
	v_rcp_f32_e32 v142, v142
	v_rcp_f32_e32 v143, v143
	v_rcp_f32_e32 v144, v144
	v_rcp_f32_e32 v145, v145
	v_rcp_f32_e32 v146, v146
	v_rcp_f32_e32 v147, v147
	s_waitcnt vmcnt(16)
	v_lshlrev_b32_e32 v148, 16, v212
	v_and_b32_e32 v149, 0xffff0000, v212
	v_lshlrev_b32_e32 v150, 16, v213
	v_and_b32_e32 v151, 0xffff0000, v213
	v_lshlrev_b32_e32 v168, 16, v214
	v_and_b32_e32 v169, 0xffff0000, v214
	v_lshlrev_b32_e32 v170, 16, v215
	v_and_b32_e32 v171, 0xffff0000, v215
	v_pk_mul_f32 v[140:141], v[140:141], v[148:149]
	v_pk_mul_f32 v[142:143], v[142:143], v[150:151]
	v_pk_mul_f32 v[144:145], v[144:145], v[168:169]
	v_pk_mul_f32 v[146:147], v[146:147], v[170:171]
	v_lshlrev_b32_e32 v148, 16, v216
	v_and_b32_e32 v149, 0xffff0000, v216
	v_lshlrev_b32_e32 v150, 16, v217
	v_and_b32_e32 v151, 0xffff0000, v217
	v_lshlrev_b32_e32 v168, 16, v218
	v_and_b32_e32 v169, 0xffff0000, v218
	v_lshlrev_b32_e32 v170, 16, v219
	v_and_b32_e32 v171, 0xffff0000, v219
	v_pk_add_f32 v[140:141], v[140:141], v[148:149]
	v_pk_add_f32 v[142:143], v[142:143], v[150:151]
	v_pk_add_f32 v[144:145], v[144:145], v[168:169]
	v_pk_add_f32 v[146:147], v[146:147], v[170:171]
	v_cvt_pk_bf16_f32 v172, v140, v141
	v_cvt_pk_bf16_f32 v173, v142, v143
	v_cvt_pk_bf16_f32 v174, v144, v145
	v_cvt_pk_bf16_f32 v175, v146, v147
	s_add_u32 s8, s98, 0x48000
	s_addc_u32 s9, s99, 0
	global_store_dwordx4 v139, v[172:175], s[8:9]
	v_pk_mul_f32 v[140:141], v[34:35], s[4:5] op_sel_hi:[1,0]
	v_pk_mul_f32 v[142:143], v[36:37], s[4:5] op_sel_hi:[1,0]
	v_pk_mul_f32 v[144:145], v[26:27], s[4:5] op_sel_hi:[1,0]
	v_pk_mul_f32 v[146:147], v[28:29], s[4:5] op_sel_hi:[1,0]
	v_exp_f32_e32 v140, v140
	v_exp_f32_e32 v141, v141
	v_exp_f32_e32 v142, v142
	v_exp_f32_e32 v143, v143
	v_exp_f32_e32 v144, v144
	v_exp_f32_e32 v145, v145
	v_exp_f32_e32 v146, v146
	v_exp_f32_e32 v147, v147
	v_pk_add_f32 v[140:141], v[140:141], 1.0 op_sel_hi:[1,0]
	v_pk_add_f32 v[142:143], v[142:143], 1.0 op_sel_hi:[1,0]
	v_pk_add_f32 v[144:145], v[144:145], 1.0 op_sel_hi:[1,0]
	v_pk_add_f32 v[146:147], v[146:147], 1.0 op_sel_hi:[1,0]
	v_rcp_f32_e32 v140, v140
	v_rcp_f32_e32 v141, v141
	v_rcp_f32_e32 v142, v142
	v_rcp_f32_e32 v143, v143
	v_rcp_f32_e32 v144, v144
	v_rcp_f32_e32 v145, v145
	v_rcp_f32_e32 v146, v146
	v_rcp_f32_e32 v147, v147
	s_waitcnt vmcnt(14)
	v_lshlrev_b32_e32 v148, 16, v220
	v_and_b32_e32 v149, 0xffff0000, v220
	v_lshlrev_b32_e32 v150, 16, v221
	v_and_b32_e32 v151, 0xffff0000, v221
	v_lshlrev_b32_e32 v168, 16, v222
	v_and_b32_e32 v169, 0xffff0000, v222
	v_lshlrev_b32_e32 v170, 16, v223
	v_and_b32_e32 v171, 0xffff0000, v223
	v_pk_mul_f32 v[140:141], v[140:141], v[148:149]
	v_pk_mul_f32 v[142:143], v[142:143], v[150:151]
	v_pk_mul_f32 v[144:145], v[144:145], v[168:169]
	v_pk_mul_f32 v[146:147], v[146:147], v[170:171]
	v_lshlrev_b32_e32 v148, 16, v224
	v_and_b32_e32 v149, 0xffff0000, v224
	v_lshlrev_b32_e32 v150, 16, v225
	v_and_b32_e32 v151, 0xffff0000, v225
	v_lshlrev_b32_e32 v168, 16, v226
	v_and_b32_e32 v169, 0xffff0000, v226
	v_lshlrev_b32_e32 v170, 16, v227
	v_and_b32_e32 v171, 0xffff0000, v227
	v_pk_add_f32 v[140:141], v[140:141], v[148:149]
	v_pk_add_f32 v[142:143], v[142:143], v[150:151]
	v_pk_add_f32 v[144:145], v[144:145], v[168:169]
	v_pk_add_f32 v[146:147], v[146:147], v[170:171]
	v_cvt_pk_bf16_f32 v176, v140, v141
	v_cvt_pk_bf16_f32 v177, v142, v143
	v_cvt_pk_bf16_f32 v178, v144, v145
	v_cvt_pk_bf16_f32 v179, v146, v147
	s_add_u32 s8, s98, 0x48000
	s_addc_u32 s9, s99, 0
	global_store_dwordx4 v139, v[176:179], s[8:9] offset:256
	v_pk_mul_f32 v[140:141], v[38:39], s[4:5] op_sel_hi:[1,0]
	v_pk_mul_f32 v[142:143], v[40:41], s[4:5] op_sel_hi:[1,0]
	v_pk_mul_f32 v[144:145], v[30:31], s[4:5] op_sel_hi:[1,0]
	v_pk_mul_f32 v[146:147], v[32:33], s[4:5] op_sel_hi:[1,0]
	v_exp_f32_e32 v140, v140
	v_exp_f32_e32 v141, v141
	v_exp_f32_e32 v142, v142
	v_exp_f32_e32 v143, v143
	v_exp_f32_e32 v144, v144
	v_exp_f32_e32 v145, v145
	v_exp_f32_e32 v146, v146
	v_exp_f32_e32 v147, v147
	v_pk_add_f32 v[140:141], v[140:141], 1.0 op_sel_hi:[1,0]
	v_pk_add_f32 v[142:143], v[142:143], 1.0 op_sel_hi:[1,0]
	v_pk_add_f32 v[144:145], v[144:145], 1.0 op_sel_hi:[1,0]
	v_pk_add_f32 v[146:147], v[146:147], 1.0 op_sel_hi:[1,0]
	v_rcp_f32_e32 v140, v140
	v_rcp_f32_e32 v141, v141
	v_rcp_f32_e32 v142, v142
	v_rcp_f32_e32 v143, v143
	v_rcp_f32_e32 v144, v144
	v_rcp_f32_e32 v145, v145
	v_rcp_f32_e32 v146, v146
	v_rcp_f32_e32 v147, v147
	s_waitcnt vmcnt(12)
; __device__ __forceinline__ float sigmoidf_(float x) { return 1.f / (1.f + __expf(-x)); }
; __device__ __forceinline__ pg8::u32x4 pack8(const f32x4 a, const f32x4 b) { pg8::u32x4 w; w.x = pg8::cvt_pk_bf16(a[0], a[1]); w.y = pg8::cvt_pk_bf16(a[2], a[3]); w.z = pg8::cvt_pk_bf16(b[0], b[1]); w.w = pg8::cvt_pk_bf16(b[2], b[3]); return w; }
; #define EPI_FOREACH(...) _Pragma("unroll") for (int ai = 0; ai < 2; ++ai) _Pragma("unroll") for (int m = 0; m < 4; ++m) _Pragma("unroll") for (int bj = 0; bj < 2; ++bj) { \
;         const int row = u.pm * 256 + ai * 128 + wr * 64 + m * 16 + fr, col = u.pn * 256 + bj * 128 + wc * 32 + 8 * fq; const f32x4 v0 = acc[ai][bj][m][0], v1 = acc[ai][bj][m][1]; (void)row; (void)col; __VA_ARGS__ }
;     __device__ __forceinline__ void operator()(const f32x4 (&acc)[2][2][4][2], const pg8::Unit& u, int wr, int wc, int fr, int fq) const {
;     ...
;         else { EPI_FOREACH( f32x4 y0, y1; unpack8(stash[((ai * 4 + m) * 2 + bj) * NT + tid], y0, y1); f32x4 t0, t1;
;                 _Pragma("unroll") for (int q = 0; q < 4; ++q) { t0[q] = sigmoidf_(v0[q]) * y0[q]; t1[q] = sigmoidf_(v1[q]) * y1[q]; }
;                 pg8::u32x4* mp = (pg8::u32x4*)((u.kind == 2 && u.aux != 0 ? PMp + (size_t)(u.aux - 1) * RC * DM - (size_t)RL * DM : MMp) + (size_t)row * DM + col);
;                 if (u.kind == 1 && u.aux != 0) { f32x4 p0, p1; unpack8(*mp, p0, p1); t0 += p0; t1 += p1; }
;                 *mp = pack8(t0, t1); ) }
	v_lshlrev_b32_e32 v148, 16, v180
	v_and_b32_e32 v149, 0xffff0000, v180
	v_lshlrev_b32_e32 v150, 16, v181
	v_and_b32_e32 v151, 0xffff0000, v181
	v_lshlrev_b32_e32 v168, 16, v182
	v_and_b32_e32 v169, 0xffff0000, v182
	v_lshlrev_b32_e32 v170, 16, v183
	v_and_b32_e32 v171, 0xffff0000, v183
	v_pk_mul_f32 v[140:141], v[140:141], v[148:149]
	v_pk_mul_f32 v[142:143], v[142:143], v[150:151]
	v_pk_mul_f32 v[144:145], v[144:145], v[168:169]
	v_pk_mul_f32 v[146:147], v[146:147], v[170:171]
	v_lshlrev_b32_e32 v148, 16, v184
	v_and_b32_e32 v149, 0xffff0000, v184
	v_lshlrev_b32_e32 v150, 16, v185
	v_and_b32_e32 v151, 0xffff0000, v185
	v_lshlrev_b32_e32 v168, 16, v186
	v_and_b32_e32 v169, 0xffff0000, v186
	v_lshlrev_b32_e32 v170, 16, v187
	v_and_b32_e32 v171, 0xffff0000, v187
	v_pk_add_f32 v[140:141], v[140:141], v[148:149]
	v_pk_add_f32 v[142:143], v[142:143], v[150:151]
	v_pk_add_f32 v[144:145], v[144:145], v[168:169]
	v_pk_add_f32 v[146:147], v[146:147], v[170:171]
	v_cvt_pk_bf16_f32 v172, v140, v141
	v_cvt_pk_bf16_f32 v173, v142, v143
	v_cvt_pk_bf16_f32 v174, v144, v145
	v_cvt_pk_bf16_f32 v175, v146, v147
	s_add_u32 s8, s98, 0x50000
	s_addc_u32 s9, s99, 0
	global_store_dwordx4 v139, v[172:175], s[8:9]
	v_pk_mul_f32 v[140:141], v[18:19], s[4:5] op_sel_hi:[1,0]
	v_pk_mul_f32 v[142:143], v[20:21], s[4:5] op_sel_hi:[1,0]
	v_pk_mul_f32 v[144:145], v[10:11], s[4:5] op_sel_hi:[1,0]
	v_pk_mul_f32 v[146:147], v[12:13], s[4:5] op_sel_hi:[1,0]
	v_exp_f32_e32 v140, v140
	v_exp_f32_e32 v141, v141
	v_exp_f32_e32 v142, v142
	v_exp_f32_e32 v143, v143
	v_exp_f32_e32 v144, v144
	v_exp_f32_e32 v145, v145
	v_exp_f32_e32 v146, v146
	v_exp_f32_e32 v147, v147
	v_pk_add_f32 v[140:141], v[140:141], 1.0 op_sel_hi:[1,0]
	v_pk_add_f32 v[142:143], v[142:143], 1.0 op_sel_hi:[1,0]
	v_pk_add_f32 v[144:145], v[144:145], 1.0 op_sel_hi:[1,0]
	v_pk_add_f32 v[146:147], v[146:147], 1.0 op_sel_hi:[1,0]
	v_rcp_f32_e32 v140, v140
	v_rcp_f32_e32 v141, v141
	v_rcp_f32_e32 v142, v142
	v_rcp_f32_e32 v143, v143
	v_rcp_f32_e32 v144, v144
	v_rcp_f32_e32 v145, v145
	v_rcp_f32_e32 v146, v146
	v_rcp_f32_e32 v147, v147
	s_waitcnt vmcnt(10)
	v_lshlrev_b32_e32 v148, 16, v188
	v_and_b32_e32 v149, 0xffff0000, v188
	v_lshlrev_b32_e32 v150, 16, v189
	v_and_b32_e32 v151, 0xffff0000, v189
	v_lshlrev_b32_e32 v168, 16, v190
	v_and_b32_e32 v169, 0xffff0000, v190
	v_lshlrev_b32_e32 v170, 16, v191
	v_and_b32_e32 v171, 0xffff0000, v191
	v_pk_mul_f32 v[140:141], v[140:141], v[148:149]
	v_pk_mul_f32 v[142:143], v[142:143], v[150:151]
	v_pk_mul_f32 v[144:145], v[144:145], v[168:169]
	v_pk_mul_f32 v[146:147], v[146:147], v[170:171]
	v_lshlrev_b32_e32 v148, 16, v192
	v_and_b32_e32 v149, 0xffff0000, v192
	v_lshlrev_b32_e32 v150, 16, v193
	v_and_b32_e32 v151, 0xffff0000, v193
	v_lshlrev_b32_e32 v168, 16, v194
	v_and_b32_e32 v169, 0xffff0000, v194
	v_lshlrev_b32_e32 v170, 16, v195
	v_and_b32_e32 v171, 0xffff0000, v195
	v_pk_add_f32 v[140:141], v[140:141], v[148:149]
	v_pk_add_f32 v[142:143], v[142:143], v[150:151]
	v_pk_add_f32 v[144:145], v[144:145], v[168:169]
	v_pk_add_f32 v[146:147], v[146:147], v[170:171]
	v_cvt_pk_bf16_f32 v176, v140, v141
	v_cvt_pk_bf16_f32 v177, v142, v143
	v_cvt_pk_bf16_f32 v178, v144, v145
	v_cvt_pk_bf16_f32 v179, v146, v147
	s_add_u32 s8, s98, 0x50000
	s_addc_u32 s9, s99, 0
	global_store_dwordx4 v139, v[176:179], s[8:9] offset:256
	v_pk_mul_f32 v[140:141], v[22:23], s[4:5] op_sel_hi:[1,0]
	v_pk_mul_f32 v[142:143], v[24:25], s[4:5] op_sel_hi:[1,0]
	v_pk_mul_f32 v[144:145], v[14:15], s[4:5] op_sel_hi:[1,0]
	v_pk_mul_f32 v[146:147], v[16:17], s[4:5] op_sel_hi:[1,0]
	v_exp_f32_e32 v140, v140
	v_exp_f32_e32 v141, v141
	v_exp_f32_e32 v142, v142
	v_exp_f32_e32 v143, v143
	v_exp_f32_e32 v144, v144
	v_exp_f32_e32 v145, v145
	v_exp_f32_e32 v146, v146
	v_exp_f32_e32 v147, v147
	v_pk_add_f32 v[140:141], v[140:141], 1.0 op_sel_hi:[1,0]
	v_pk_add_f32 v[142:143], v[142:143], 1.0 op_sel_hi:[1,0]
	v_pk_add_f32 v[144:145], v[144:145], 1.0 op_sel_hi:[1,0]
	v_pk_add_f32 v[146:147], v[146:147], 1.0 op_sel_hi:[1,0]
	v_rcp_f32_e32 v140, v140
	v_rcp_f32_e32 v141, v141
	v_rcp_f32_e32 v142, v142
	v_rcp_f32_e32 v143, v143
	v_rcp_f32_e32 v144, v144
	v_rcp_f32_e32 v145, v145
	v_rcp_f32_e32 v146, v146
	v_rcp_f32_e32 v147, v147
	s_waitcnt vmcnt(8)
	v_lshlrev_b32_e32 v148, 16, v196
	v_and_b32_e32 v149, 0xffff0000, v196
	v_lshlrev_b32_e32 v150, 16, v197
	v_and_b32_e32 v151, 0xffff0000, v197
	v_lshlrev_b32_e32 v168, 16, v198
	v_and_b32_e32 v169, 0xffff0000, v198
	v_lshlrev_b32_e32 v170, 16, v199
	v_and_b32_e32 v171, 0xffff0000, v199
	v_pk_mul_f32 v[140:141], v[140:141], v[148:149]
	v_pk_mul_f32 v[142:143], v[142:143], v[150:151]
	v_pk_mul_f32 v[144:145], v[144:145], v[168:169]
	v_pk_mul_f32 v[146:147], v[146:147], v[170:171]
	v_lshlrev_b32_e32 v148, 16, v200
	v_and_b32_e32 v149, 0xffff0000, v200
	v_lshlrev_b32_e32 v150, 16, v201
	v_and_b32_e32 v151, 0xffff0000, v201
	v_lshlrev_b32_e32 v168, 16, v202
	v_and_b32_e32 v169, 0xffff0000, v202
	v_lshlrev_b32_e32 v170, 16, v203
	v_and_b32_e32 v171, 0xffff0000, v203
	v_pk_add_f32 v[140:141], v[140:141], v[148:149]
	v_pk_add_f32 v[142:143], v[142:143], v[150:151]
	v_pk_add_f32 v[144:145], v[144:145], v[168:169]
	v_pk_add_f32 v[146:147], v[146:147], v[170:171]
	v_cvt_pk_bf16_f32 v172, v140, v141
	v_cvt_pk_bf16_f32 v173, v142, v143
	v_cvt_pk_bf16_f32 v174, v144, v145
	v_cvt_pk_bf16_f32 v175, v146, v147
	s_add_u32 s8, s98, 0x58000
	s_addc_u32 s9, s99, 0
	global_store_dwordx4 v139, v[172:175], s[8:9]
	v_pk_mul_f32 v[140:141], v[6:7], s[4:5] op_sel_hi:[1,0]
	v_pk_mul_f32 v[142:143], v[8:9], s[4:5] op_sel_hi:[1,0]
	v_pk_mul_f32 v[144:145], v[2:3], s[4:5] op_sel_hi:[1,0]
	v_pk_mul_f32 v[146:147], v[4:5], s[4:5] op_sel_hi:[1,0]
	v_exp_f32_e32 v140, v140
	v_exp_f32_e32 v141, v141
	v_exp_f32_e32 v142, v142
	v_exp_f32_e32 v143, v143
	v_exp_f32_e32 v144, v144
	v_exp_f32_e32 v145, v145
	v_exp_f32_e32 v146, v146
	v_exp_f32_e32 v147, v147
	v_pk_add_f32 v[140:141], v[140:141], 1.0 op_sel_hi:[1,0]
	v_pk_add_f32 v[142:143], v[142:143], 1.0 op_sel_hi:[1,0]
	v_pk_add_f32 v[144:145], v[144:145], 1.0 op_sel_hi:[1,0]
	v_pk_add_f32 v[146:147], v[146:147], 1.0 op_sel_hi:[1,0]
	v_rcp_f32_e32 v140, v140
	v_rcp_f32_e32 v141, v141
	v_rcp_f32_e32 v142, v142
	v_rcp_f32_e32 v143, v143
	v_rcp_f32_e32 v144, v144
	v_rcp_f32_e32 v145, v145
	v_rcp_f32_e32 v146, v146
	v_rcp_f32_e32 v147, v147
	s_waitcnt vmcnt(6)
; __device__ __forceinline__ float sigmoidf_(float x) { return 1.f / (1.f + __expf(-x)); }
; __device__ __forceinline__ pg8::u32x4 pack8(const f32x4 a, const f32x4 b) { pg8::u32x4 w; w.x = pg8::cvt_pk_bf16(a[0], a[1]); w.y = pg8::cvt_pk_bf16(a[2], a[3]); w.z = pg8::cvt_pk_bf16(b[0], b[1]); w.w = pg8::cvt_pk_bf16(b[2], b[3]); return w; }
; #define EPI_FOREACH(...) _Pragma("unroll") for (int ai = 0; ai < 2; ++ai) _Pragma("unroll") for (int m = 0; m < 4; ++m) _Pragma("unroll") for (int bj = 0; bj < 2; ++bj) { \
;         const int row = u.pm * 256 + ai * 128 + wr * 64 + m * 16 + fr, col = u.pn * 256 + bj * 128 + wc * 32 + 8 * fq; const f32x4 v0 = acc[ai][bj][m][0], v1 = acc[ai][bj][m][1]; (void)row; (void)col; __VA_ARGS__ }
;     __device__ __forceinline__ void operator()(const f32x4 (&acc)[2][2][4][2], const pg8::Unit& u, int wr, int wc, int fr, int fq) const {
;     ...
;         else { EPI_FOREACH( f32x4 y0, y1; unpack8(stash[((ai * 4 + m) * 2 + bj) * NT + tid], y0, y1); f32x4 t0, t1;
;                 _Pragma("unroll") for (int q = 0; q < 4; ++q) { t0[q] = sigmoidf_(v0[q]) * y0[q]; t1[q] = sigmoidf_(v1[q]) * y1[q]; }
;                 pg8::u32x4* mp = (pg8::u32x4*)((u.kind == 2 && u.aux != 0 ? PMp + (size_t)(u.aux - 1) * RC * DM - (size_t)RL * DM : MMp) + (size_t)row * DM + col);
;                 if (u.kind == 1 && u.aux != 0) { f32x4 p0, p1; unpack8(*mp, p0, p1); t0 += p0; t1 += p1; }
;                 *mp = pack8(t0, t1); ) }
	v_lshlrev_b32_e32 v148, 16, v204
	v_and_b32_e32 v149, 0xffff0000, v204
	v_lshlrev_b32_e32 v150, 16, v205
	v_and_b32_e32 v151, 0xffff0000, v205
	v_lshlrev_b32_e32 v168, 16, v206
	v_and_b32_e32 v169, 0xffff0000, v206
	v_lshlrev_b32_e32 v170, 16, v207
	v_and_b32_e32 v171, 0xffff0000, v207
	v_pk_mul_f32 v[140:141], v[140:141], v[148:149]
	v_pk_mul_f32 v[142:143], v[142:143], v[150:151]
	v_pk_mul_f32 v[144:145], v[144:145], v[168:169]
	v_pk_mul_f32 v[146:147], v[146:147], v[170:171]
	v_lshlrev_b32_e32 v148, 16, v208
	v_and_b32_e32 v149, 0xffff0000, v208
	v_lshlrev_b32_e32 v150, 16, v209
	v_and_b32_e32 v151, 0xffff0000, v209
	v_lshlrev_b32_e32 v168, 16, v210
	v_and_b32_e32 v169, 0xffff0000, v210
	v_lshlrev_b32_e32 v170, 16, v211
	v_and_b32_e32 v171, 0xffff0000, v211
	v_pk_add_f32 v[140:141], v[140:141], v[148:149]
	v_pk_add_f32 v[142:143], v[142:143], v[150:151]
	v_pk_add_f32 v[144:145], v[144:145], v[168:169]
	v_pk_add_f32 v[146:147], v[146:147], v[170:171]
	v_cvt_pk_bf16_f32 v176, v140, v141
	v_cvt_pk_bf16_f32 v177, v142, v143
	v_cvt_pk_bf16_f32 v178, v144, v145
	v_cvt_pk_bf16_f32 v179, v146, v147
	s_add_u32 s8, s98, 0x58000
	s_addc_u32 s9, s99, 0
	global_store_dwordx4 v139, v[176:179], s[8:9] offset:256
	s_branch .Lmrg0_done
.Lmrg0_plain:
	s_add_u32 s10, s16, 0x0
	s_addc_u32 s11, s17, 0
	global_load_dwordx4 v[180:183], v138, s[10:11]
	s_add_u32 s10, s16, 0x2000
	s_addc_u32 s11, s17, 0
	global_load_dwordx4 v[184:187], v138, s[10:11]
	s_add_u32 s10, s16, 0x4000
	s_addc_u32 s11, s17, 0
	global_load_dwordx4 v[188:191], v138, s[10:11]
	s_add_u32 s10, s16, 0x6000
	s_addc_u32 s11, s17, 0
	global_load_dwordx4 v[192:195], v138, s[10:11]
	s_add_u32 s10, s16, 0x8000
	s_addc_u32 s11, s17, 0
	global_load_dwordx4 v[196:199], v138, s[10:11]
	s_add_u32 s10, s16, 0xa000
	s_addc_u32 s11, s17, 0
	global_load_dwordx4 v[200:203], v138, s[10:11]
	s_add_u32 s10, s16, 0xc000
	s_addc_u32 s11, s17, 0
	global_load_dwordx4 v[204:207], v138, s[10:11]
	s_add_u32 s10, s16, 0xe000
	s_addc_u32 s11, s17, 0
	global_load_dwordx4 v[208:211], v138, s[10:11]
	s_add_u32 s10, s16, 0x10000
	s_addc_u32 s11, s17, 0
	global_load_dwordx4 v[212:215], v138, s[10:11]
	s_add_u32 s10, s16, 0x12000
	s_addc_u32 s11, s17, 0
	global_load_dwordx4 v[216:219], v138, s[10:11]
	s_add_u32 s10, s16, 0x14000
	s_addc_u32 s11, s17, 0
	global_load_dwordx4 v[220:223], v138, s[10:11]
	s_add_u32 s10, s16, 0x16000
	s_addc_u32 s11, s17, 0
	global_load_dwordx4 v[224:227], v138, s[10:11]
	v_pk_mul_f32 v[140:141], v[126:127], s[4:5] op_sel_hi:[1,0]
	v_pk_mul_f32 v[142:143], v[128:129], s[4:5] op_sel_hi:[1,0]
	v_pk_mul_f32 v[144:145], v[122:123], s[4:5] op_sel_hi:[1,0]
	v_pk_mul_f32 v[146:147], v[124:125], s[4:5] op_sel_hi:[1,0]
	v_exp_f32_e32 v140, v140
	v_exp_f32_e32 v141, v141
	v_exp_f32_e32 v142, v142
	v_exp_f32_e32 v143, v143
	v_exp_f32_e32 v144, v144
	v_exp_f32_e32 v145, v145
	v_exp_f32_e32 v146, v146
	v_exp_f32_e32 v147, v147
	v_pk_add_f32 v[140:141], v[140:141], 1.0 op_sel_hi:[1,0]
	v_pk_add_f32 v[142:143], v[142:143], 1.0 op_sel_hi:[1,0]
	v_pk_add_f32 v[144:145], v[144:145], 1.0 op_sel_hi:[1,0]
	v_pk_add_f32 v[146:147], v[146:147], 1.0 op_sel_hi:[1,0]
	v_rcp_f32_e32 v140, v140
	v_rcp_f32_e32 v141, v141
	v_rcp_f32_e32 v142, v142
	v_rcp_f32_e32 v143, v143
	v_rcp_f32_e32 v144, v144
	v_rcp_f32_e32 v145, v145
	v_rcp_f32_e32 v146, v146
	v_rcp_f32_e32 v147, v147
	s_waitcnt vmcnt(11)
	v_lshlrev_b32_e32 v148, 16, v180
	v_and_b32_e32 v149, 0xffff0000, v180
	v_lshlrev_b32_e32 v150, 16, v181
	v_and_b32_e32 v151, 0xffff0000, v181
	v_lshlrev_b32_e32 v168, 16, v182
	v_and_b32_e32 v169, 0xffff0000, v182
	v_lshlrev_b32_e32 v170, 16, v183
	v_and_b32_e32 v171, 0xffff0000, v183
	v_pk_mul_f32 v[140:141], v[140:141], v[148:149]
	v_pk_mul_f32 v[142:143], v[142:143], v[150:151]
	v_pk_mul_f32 v[144:145], v[144:145], v[168:169]
	v_pk_mul_f32 v[146:147], v[146:147], v[170:171]
	v_cvt_pk_bf16_f32 v172, v140, v141
	v_cvt_pk_bf16_f32 v173, v142, v143
	v_cvt_pk_bf16_f32 v174, v144, v145
	v_cvt_pk_bf16_f32 v175, v146, v147
	s_add_u32 s10, s16, 0x18000
	s_addc_u32 s11, s17, 0
	global_load_dwordx4 v[180:183], v138, s[10:11]
	s_add_u32 s8, s98, 0x0
	s_addc_u32 s9, s99, 0
	global_store_dwordx4 v139, v[172:175], s[8:9]
	v_pk_mul_f32 v[140:141], v[114:115], s[4:5] op_sel_hi:[1,0]
	v_pk_mul_f32 v[142:143], v[116:117], s[4:5] op_sel_hi:[1,0]
	v_pk_mul_f32 v[144:145], v[106:107], s[4:5] op_sel_hi:[1,0]
	v_pk_mul_f32 v[146:147], v[108:109], s[4:5] op_sel_hi:[1,0]
	v_exp_f32_e32 v140, v140
	v_exp_f32_e32 v141, v141
	v_exp_f32_e32 v142, v142
	v_exp_f32_e32 v143, v143
	v_exp_f32_e32 v144, v144
	v_exp_f32_e32 v145, v145
	v_exp_f32_e32 v146, v146
	v_exp_f32_e32 v147, v147
	v_pk_add_f32 v[140:141], v[140:141], 1.0 op_sel_hi:[1,0]
	v_pk_add_f32 v[142:143], v[142:143], 1.0 op_sel_hi:[1,0]
	v_pk_add_f32 v[144:145], v[144:145], 1.0 op_sel_hi:[1,0]
	v_pk_add_f32 v[146:147], v[146:147], 1.0 op_sel_hi:[1,0]
	v_rcp_f32_e32 v140, v140
	v_rcp_f32_e32 v141, v141
	v_rcp_f32_e32 v142, v142
	v_rcp_f32_e32 v143, v143
	v_rcp_f32_e32 v144, v144
	v_rcp_f32_e32 v145, v145
	v_rcp_f32_e32 v146, v146
	v_rcp_f32_e32 v147, v147
	s_waitcnt vmcnt(12)
; __device__ __forceinline__ float sigmoidf_(float x) { return 1.f / (1.f + __expf(-x)); }
; __device__ __forceinline__ pg8::u32x4 pack8(const f32x4 a, const f32x4 b) { pg8::u32x4 w; w.x = pg8::cvt_pk_bf16(a[0], a[1]); w.y = pg8::cvt_pk_bf16(a[2], a[3]); w.z = pg8::cvt_pk_bf16(b[0], b[1]); w.w = pg8::cvt_pk_bf16(b[2], b[3]); return w; }
; #define EPI_FOREACH(...) _Pragma("unroll") for (int ai = 0; ai < 2; ++ai) _Pragma("unroll") for (int m = 0; m < 4; ++m) _Pragma("unroll") for (int bj = 0; bj < 2; ++bj) { \
;         const int row = u.pm * 256 + ai * 128 + wr * 64 + m * 16 + fr, col = u.pn * 256 + bj * 128 + wc * 32 + 8 * fq; const f32x4 v0 = acc[ai][bj][m][0], v1 = acc[ai][bj][m][1]; (void)row; (void)col; __VA_ARGS__ }
;     __device__ __forceinline__ void operator()(const f32x4 (&acc)[2][2][4][2], const pg8::Unit& u, int wr, int wc, int fr, int fq) const {
;     ...
;         else { EPI_FOREACH( f32x4 y0, y1; unpack8(stash[((ai * 4 + m) * 2 + bj) * NT + tid], y0, y1); f32x4 t0, t1;
;                 _Pragma("unroll") for (int q = 0; q < 4; ++q) { t0[q] = sigmoidf_(v0[q]) * y0[q]; t1[q] = sigmoidf_(v1[q]) * y1[q]; }
;                 pg8::u32x4* mp = (pg8::u32x4*)((u.kind == 2 && u.aux != 0 ? PMp + (size_t)(u.aux - 1) * RC * DM - (size_t)RL * DM : MMp) + (size_t)row * DM + col);
;                 if (u.kind == 1 && u.aux != 0) { f32x4 p0, p1; unpack8(*mp, p0, p1); t0 += p0; t1 += p1; }
;                 *mp = pack8(t0, t1); ) }
	v_lshlrev_b32_e32 v148, 16, v184
	v_and_b32_e32 v149, 0xffff0000, v184
	v_lshlrev_b32_e32 v150, 16, v185
	v_and_b32_e32 v151, 0xffff0000, v185
	v_lshlrev_b32_e32 v168, 16, v186
	v_and_b32_e32 v169, 0xffff0000, v186
	v_lshlrev_b32_e32 v170, 16, v187
	v_and_b32_e32 v171, 0xffff0000, v187
	v_pk_mul_f32 v[140:141], v[140:141], v[148:149]
	v_pk_mul_f32 v[142:143], v[142:143], v[150:151]
	v_pk_mul_f32 v[144:145], v[144:145], v[168:169]
	v_pk_mul_f32 v[146:147], v[146:147], v[170:171]
	v_cvt_pk_bf16_f32 v176, v140, v141
	v_cvt_pk_bf16_f32 v177, v142, v143
	v_cvt_pk_bf16_f32 v178, v144, v145
	v_cvt_pk_bf16_f32 v179, v146, v147
	s_add_u32 s10, s16, 0x1a000
	s_addc_u32 s11, s17, 0
	global_load_dwordx4 v[184:187], v138, s[10:11]
	s_add_u32 s8, s98, 0x0
	s_addc_u32 s9, s99, 0
	global_store_dwordx4 v139, v[176:179], s[8:9] offset:256
	v_pk_mul_f32 v[140:141], v[118:119], s[4:5] op_sel_hi:[1,0]
	v_pk_mul_f32 v[142:143], v[120:121], s[4:5] op_sel_hi:[1,0]
	v_pk_mul_f32 v[144:145], v[110:111], s[4:5] op_sel_hi:[1,0]
	v_pk_mul_f32 v[146:147], v[112:113], s[4:5] op_sel_hi:[1,0]
	v_exp_f32_e32 v140, v140
	v_exp_f32_e32 v141, v141
	v_exp_f32_e32 v142, v142
	v_exp_f32_e32 v143, v143
	v_exp_f32_e32 v144, v144
	v_exp_f32_e32 v145, v145
	v_exp_f32_e32 v146, v146
	v_exp_f32_e32 v147, v147
	v_pk_add_f32 v[140:141], v[140:141], 1.0 op_sel_hi:[1,0]
	v_pk_add_f32 v[142:143], v[142:143], 1.0 op_sel_hi:[1,0]
	v_pk_add_f32 v[144:145], v[144:145], 1.0 op_sel_hi:[1,0]
	v_pk_add_f32 v[146:147], v[146:147], 1.0 op_sel_hi:[1,0]
	v_rcp_f32_e32 v140, v140
	v_rcp_f32_e32 v141, v141
	v_rcp_f32_e32 v142, v142
	v_rcp_f32_e32 v143, v143
	v_rcp_f32_e32 v144, v144
	v_rcp_f32_e32 v145, v145
	v_rcp_f32_e32 v146, v146
	v_rcp_f32_e32 v147, v147
	s_waitcnt vmcnt(13)
	v_lshlrev_b32_e32 v148, 16, v188
	v_and_b32_e32 v149, 0xffff0000, v188
	v_lshlrev_b32_e32 v150, 16, v189
	v_and_b32_e32 v151, 0xffff0000, v189
	v_lshlrev_b32_e32 v168, 16, v190
	v_and_b32_e32 v169, 0xffff0000, v190
	v_lshlrev_b32_e32 v170, 16, v191
	v_and_b32_e32 v171, 0xffff0000, v191
	v_pk_mul_f32 v[140:141], v[140:141], v[148:149]
	v_pk_mul_f32 v[142:143], v[142:143], v[150:151]
	v_pk_mul_f32 v[144:145], v[144:145], v[168:169]
	v_pk_mul_f32 v[146:147], v[146:147], v[170:171]
	v_cvt_pk_bf16_f32 v172, v140, v141
	v_cvt_pk_bf16_f32 v173, v142, v143
	v_cvt_pk_bf16_f32 v174, v144, v145
	v_cvt_pk_bf16_f32 v175, v146, v147
	s_add_u32 s10, s16, 0x1c000
	s_addc_u32 s11, s17, 0
	global_load_dwordx4 v[188:191], v138, s[10:11]
	s_add_u32 s8, s98, 0x8000
	s_addc_u32 s9, s99, 0
	global_store_dwordx4 v139, v[172:175], s[8:9]
	v_pk_mul_f32 v[140:141], v[98:99], s[4:5] op_sel_hi:[1,0]
	v_pk_mul_f32 v[142:143], v[100:101], s[4:5] op_sel_hi:[1,0]
	v_pk_mul_f32 v[144:145], v[90:91], s[4:5] op_sel_hi:[1,0]
	v_pk_mul_f32 v[146:147], v[92:93], s[4:5] op_sel_hi:[1,0]
	v_exp_f32_e32 v140, v140
	v_exp_f32_e32 v141, v141
	v_exp_f32_e32 v142, v142
	v_exp_f32_e32 v143, v143
	v_exp_f32_e32 v144, v144
	v_exp_f32_e32 v145, v145
	v_exp_f32_e32 v146, v146
	v_exp_f32_e32 v147, v147
	v_pk_add_f32 v[140:141], v[140:141], 1.0 op_sel_hi:[1,0]
	v_pk_add_f32 v[142:143], v[142:143], 1.0 op_sel_hi:[1,0]
	v_pk_add_f32 v[144:145], v[144:145], 1.0 op_sel_hi:[1,0]
	v_pk_add_f32 v[146:147], v[146:147], 1.0 op_sel_hi:[1,0]
	v_rcp_f32_e32 v140, v140
	v_rcp_f32_e32 v141, v141
	v_rcp_f32_e32 v142, v142
	v_rcp_f32_e32 v143, v143
	v_rcp_f32_e32 v144, v144
	v_rcp_f32_e32 v145, v145
	v_rcp_f32_e32 v146, v146
	v_rcp_f32_e32 v147, v147
	s_waitcnt vmcnt(14)
	v_lshlrev_b32_e32 v148, 16, v192
	v_and_b32_e32 v149, 0xffff0000, v192
	v_lshlrev_b32_e32 v150, 16, v193
	v_and_b32_e32 v151, 0xffff0000, v193
	v_lshlrev_b32_e32 v168, 16, v194
	v_and_b32_e32 v169, 0xffff0000, v194
	v_lshlrev_b32_e32 v170, 16, v195
	v_and_b32_e32 v171, 0xffff0000, v195
	v_pk_mul_f32 v[140:141], v[140:141], v[148:149]
	v_pk_mul_f32 v[142:143], v[142:143], v[150:151]
	v_pk_mul_f32 v[144:145], v[144:145], v[168:169]
	v_pk_mul_f32 v[146:147], v[146:147], v[170:171]
	v_cvt_pk_bf16_f32 v176, v140, v141
	v_cvt_pk_bf16_f32 v177, v142, v143
	v_cvt_pk_bf16_f32 v178, v144, v145
	v_cvt_pk_bf16_f32 v179, v146, v147
	s_add_u32 s10, s16, 0x1e000
	s_addc_u32 s11, s17, 0
	global_load_dwordx4 v[192:195], v138, s[10:11]
	s_add_u32 s8, s98, 0x8000
	s_addc_u32 s9, s99, 0
	global_store_dwordx4 v139, v[176:179], s[8:9] offset:256
	v_pk_mul_f32 v[140:141], v[102:103], s[4:5] op_sel_hi:[1,0]
	v_pk_mul_f32 v[142:143], v[104:105], s[4:5] op_sel_hi:[1,0]
	v_pk_mul_f32 v[144:145], v[94:95], s[4:5] op_sel_hi:[1,0]
	v_pk_mul_f32 v[146:147], v[96:97], s[4:5] op_sel_hi:[1,0]
	v_exp_f32_e32 v140, v140
	v_exp_f32_e32 v141, v141
	v_exp_f32_e32 v142, v142
	v_exp_f32_e32 v143, v143
	v_exp_f32_e32 v144, v144
	v_exp_f32_e32 v145, v145
	v_exp_f32_e32 v146, v146
	v_exp_f32_e32 v147, v147
	v_pk_add_f32 v[140:141], v[140:141], 1.0 op_sel_hi:[1,0]
	v_pk_add_f32 v[142:143], v[142:143], 1.0 op_sel_hi:[1,0]
	v_pk_add_f32 v[144:145], v[144:145], 1.0 op_sel_hi:[1,0]
	v_pk_add_f32 v[146:147], v[146:147], 1.0 op_sel_hi:[1,0]
	v_rcp_f32_e32 v140, v140
	v_rcp_f32_e32 v141, v141
	v_rcp_f32_e32 v142, v142
	v_rcp_f32_e32 v143, v143
	v_rcp_f32_e32 v144, v144
	v_rcp_f32_e32 v145, v145
	v_rcp_f32_e32 v146, v146
	v_rcp_f32_e32 v147, v147
	s_waitcnt vmcnt(15)
; __device__ __forceinline__ float sigmoidf_(float x) { return 1.f / (1.f + __expf(-x)); }
; __device__ __forceinline__ pg8::u32x4 pack8(const f32x4 a, const f32x4 b) { pg8::u32x4 w; w.x = pg8::cvt_pk_bf16(a[0], a[1]); w.y = pg8::cvt_pk_bf16(a[2], a[3]); w.z = pg8::cvt_pk_bf16(b[0], b[1]); w.w = pg8::cvt_pk_bf16(b[2], b[3]); return w; }
; #define EPI_FOREACH(...) _Pragma("unroll") for (int ai = 0; ai < 2; ++ai) _Pragma("unroll") for (int m = 0; m < 4; ++m) _Pragma("unroll") for (int bj = 0; bj < 2; ++bj) { \
;         const int row = u.pm * 256 + ai * 128 + wr * 64 + m * 16 + fr, col = u.pn * 256 + bj * 128 + wc * 32 + 8 * fq; const f32x4 v0 = acc[ai][bj][m][0], v1 = acc[ai][bj][m][1]; (void)row; (void)col; __VA_ARGS__ }
;     __device__ __forceinline__ void operator()(const f32x4 (&acc)[2][2][4][2], const pg8::Unit& u, int wr, int wc, int fr, int fq) const {
;     ...
;         else { EPI_FOREACH( f32x4 y0, y1; unpack8(stash[((ai * 4 + m) * 2 + bj) * NT + tid], y0, y1); f32x4 t0, t1;
;                 _Pragma("unroll") for (int q = 0; q < 4; ++q) { t0[q] = sigmoidf_(v0[q]) * y0[q]; t1[q] = sigmoidf_(v1[q]) * y1[q]; }
;                 pg8::u32x4* mp = (pg8::u32x4*)((u.kind == 2 && u.aux != 0 ? PMp + (size_t)(u.aux - 1) * RC * DM - (size_t)RL * DM : MMp) + (size_t)row * DM + col);
;                 if (u.kind == 1 && u.aux != 0) { f32x4 p0, p1; unpack8(*mp, p0, p1); t0 += p0; t1 += p1; }
;                 *mp = pack8(t0, t1); ) }
	v_lshlrev_b32_e32 v148, 16, v196
	v_and_b32_e32 v149, 0xffff0000, v196
	v_lshlrev_b32_e32 v150, 16, v197
	v_and_b32_e32 v151, 0xffff0000, v197
	v_lshlrev_b32_e32 v168, 16, v198
	v_and_b32_e32 v169, 0xffff0000, v198
	v_lshlrev_b32_e32 v170, 16, v199
	v_and_b32_e32 v171, 0xffff0000, v199
	v_pk_mul_f32 v[140:141], v[140:141], v[148:149]
	v_pk_mul_f32 v[142:143], v[142:143], v[150:151]
	v_pk_mul_f32 v[144:145], v[144:145], v[168:169]
	v_pk_mul_f32 v[146:147], v[146:147], v[170:171]
	v_cvt_pk_bf16_f32 v172, v140, v141
	v_cvt_pk_bf16_f32 v173, v142, v143
	v_cvt_pk_bf16_f32 v174, v144, v145
	v_cvt_pk_bf16_f32 v175, v146, v147
	s_add_u32 s8, s98, 0x10000
	s_addc_u32 s9, s99, 0
	global_store_dwordx4 v139, v[172:175], s[8:9]
	v_pk_mul_f32 v[140:141], v[82:83], s[4:5] op_sel_hi:[1,0]
	v_pk_mul_f32 v[142:143], v[84:85], s[4:5] op_sel_hi:[1,0]
	v_pk_mul_f32 v[144:145], v[74:75], s[4:5] op_sel_hi:[1,0]
	v_pk_mul_f32 v[146:147], v[76:77], s[4:5] op_sel_hi:[1,0]
	v_exp_f32_e32 v140, v140
	v_exp_f32_e32 v141, v141
	v_exp_f32_e32 v142, v142
	v_exp_f32_e32 v143, v143
	v_exp_f32_e32 v144, v144
	v_exp_f32_e32 v145, v145
	v_exp_f32_e32 v146, v146
	v_exp_f32_e32 v147, v147
	v_pk_add_f32 v[140:141], v[140:141], 1.0 op_sel_hi:[1,0]
	v_pk_add_f32 v[142:143], v[142:143], 1.0 op_sel_hi:[1,0]
	v_pk_add_f32 v[144:145], v[144:145], 1.0 op_sel_hi:[1,0]
	v_pk_add_f32 v[146:147], v[146:147], 1.0 op_sel_hi:[1,0]
	v_rcp_f32_e32 v140, v140
	v_rcp_f32_e32 v141, v141
	v_rcp_f32_e32 v142, v142
	v_rcp_f32_e32 v143, v143
	v_rcp_f32_e32 v144, v144
	v_rcp_f32_e32 v145, v145
	v_rcp_f32_e32 v146, v146
	v_rcp_f32_e32 v147, v147
	s_waitcnt vmcnt(15)
	v_lshlrev_b32_e32 v148, 16, v200
	v_and_b32_e32 v149, 0xffff0000, v200
	v_lshlrev_b32_e32 v150, 16, v201
	v_and_b32_e32 v151, 0xffff0000, v201
	v_lshlrev_b32_e32 v168, 16, v202
	v_and_b32_e32 v169, 0xffff0000, v202
	v_lshlrev_b32_e32 v170, 16, v203
	v_and_b32_e32 v171, 0xffff0000, v203
	v_pk_mul_f32 v[140:141], v[140:141], v[148:149]
	v_pk_mul_f32 v[142:143], v[142:143], v[150:151]
	v_pk_mul_f32 v[144:145], v[144:145], v[168:169]
	v_pk_mul_f32 v[146:147], v[146:147], v[170:171]
	v_cvt_pk_bf16_f32 v176, v140, v141
	v_cvt_pk_bf16_f32 v177, v142, v143
	v_cvt_pk_bf16_f32 v178, v144, v145
	v_cvt_pk_bf16_f32 v179, v146, v147
	s_add_u32 s8, s98, 0x10000
	s_addc_u32 s9, s99, 0
	global_store_dwordx4 v139, v[176:179], s[8:9] offset:256
	v_pk_mul_f32 v[140:141], v[86:87], s[4:5] op_sel_hi:[1,0]
	v_pk_mul_f32 v[142:143], v[88:89], s[4:5] op_sel_hi:[1,0]
	v_pk_mul_f32 v[144:145], v[78:79], s[4:5] op_sel_hi:[1,0]
	v_pk_mul_f32 v[146:147], v[80:81], s[4:5] op_sel_hi:[1,0]
	v_exp_f32_e32 v140, v140
	v_exp_f32_e32 v141, v141
	v_exp_f32_e32 v142, v142
	v_exp_f32_e32 v143, v143
	v_exp_f32_e32 v144, v144
	v_exp_f32_e32 v145, v145
	v_exp_f32_e32 v146, v146
	v_exp_f32_e32 v147, v147
	v_pk_add_f32 v[140:141], v[140:141], 1.0 op_sel_hi:[1,0]
	v_pk_add_f32 v[142:143], v[142:143], 1.0 op_sel_hi:[1,0]
	v_pk_add_f32 v[144:145], v[144:145], 1.0 op_sel_hi:[1,0]
	v_pk_add_f32 v[146:147], v[146:147], 1.0 op_sel_hi:[1,0]
	v_rcp_f32_e32 v140, v140
	v_rcp_f32_e32 v141, v141
	v_rcp_f32_e32 v142, v142
	v_rcp_f32_e32 v143, v143
	v_rcp_f32_e32 v144, v144
	v_rcp_f32_e32 v145, v145
	v_rcp_f32_e32 v146, v146
	v_rcp_f32_e32 v147, v147
	s_waitcnt vmcnt(15)
	v_lshlrev_b32_e32 v148, 16, v204
	v_and_b32_e32 v149, 0xffff0000, v204
	v_lshlrev_b32_e32 v150, 16, v205
	v_and_b32_e32 v151, 0xffff0000, v205
	v_lshlrev_b32_e32 v168, 16, v206
	v_and_b32_e32 v169, 0xffff0000, v206
	v_lshlrev_b32_e32 v170, 16, v207
	v_and_b32_e32 v171, 0xffff0000, v207
	v_pk_mul_f32 v[140:141], v[140:141], v[148:149]
	v_pk_mul_f32 v[142:143], v[142:143], v[150:151]
	v_pk_mul_f32 v[144:145], v[144:145], v[168:169]
	v_pk_mul_f32 v[146:147], v[146:147], v[170:171]
	v_cvt_pk_bf16_f32 v172, v140, v141
	v_cvt_pk_bf16_f32 v173, v142, v143
	v_cvt_pk_bf16_f32 v174, v144, v145
	v_cvt_pk_bf16_f32 v175, v146, v147
	s_add_u32 s8, s98, 0x18000
	s_addc_u32 s9, s99, 0
	global_store_dwordx4 v139, v[172:175], s[8:9]
	v_pk_mul_f32 v[140:141], v[70:71], s[4:5] op_sel_hi:[1,0]
	v_pk_mul_f32 v[142:143], v[72:73], s[4:5] op_sel_hi:[1,0]
	v_pk_mul_f32 v[144:145], v[66:67], s[4:5] op_sel_hi:[1,0]
	v_pk_mul_f32 v[146:147], v[68:69], s[4:5] op_sel_hi:[1,0]
	v_exp_f32_e32 v140, v140
	v_exp_f32_e32 v141, v141
	v_exp_f32_e32 v142, v142
	v_exp_f32_e32 v143, v143
	v_exp_f32_e32 v144, v144
	v_exp_f32_e32 v145, v145
	v_exp_f32_e32 v146, v146
	v_exp_f32_e32 v147, v147
	v_pk_add_f32 v[140:141], v[140:141], 1.0 op_sel_hi:[1,0]
	v_pk_add_f32 v[142:143], v[142:143], 1.0 op_sel_hi:[1,0]
	v_pk_add_f32 v[144:145], v[144:145], 1.0 op_sel_hi:[1,0]
	v_pk_add_f32 v[146:147], v[146:147], 1.0 op_sel_hi:[1,0]
	v_rcp_f32_e32 v140, v140
	v_rcp_f32_e32 v141, v141
	v_rcp_f32_e32 v142, v142
	v_rcp_f32_e32 v143, v143
	v_rcp_f32_e32 v144, v144
	v_rcp_f32_e32 v145, v145
	v_rcp_f32_e32 v146, v146
	v_rcp_f32_e32 v147, v147
	s_waitcnt vmcnt(15)
; __device__ __forceinline__ float sigmoidf_(float x) { return 1.f / (1.f + __expf(-x)); }
; __device__ __forceinline__ pg8::u32x4 pack8(const f32x4 a, const f32x4 b) { pg8::u32x4 w; w.x = pg8::cvt_pk_bf16(a[0], a[1]); w.y = pg8::cvt_pk_bf16(a[2], a[3]); w.z = pg8::cvt_pk_bf16(b[0], b[1]); w.w = pg8::cvt_pk_bf16(b[2], b[3]); return w; }
; #define EPI_FOREACH(...) _Pragma("unroll") for (int ai = 0; ai < 2; ++ai) _Pragma("unroll") for (int m = 0; m < 4; ++m) _Pragma("unroll") for (int bj = 0; bj < 2; ++bj) { \
;         const int row = u.pm * 256 + ai * 128 + wr * 64 + m * 16 + fr, col = u.pn * 256 + bj * 128 + wc * 32 + 8 * fq; const f32x4 v0 = acc[ai][bj][m][0], v1 = acc[ai][bj][m][1]; (void)row; (void)col; __VA_ARGS__ }
;     __device__ __forceinline__ void operator()(const f32x4 (&acc)[2][2][4][2], const pg8::Unit& u, int wr, int wc, int fr, int fq) const {
;     ...
;         else { EPI_FOREACH( f32x4 y0, y1; unpack8(stash[((ai * 4 + m) * 2 + bj) * NT + tid], y0, y1); f32x4 t0, t1;
;                 _Pragma("unroll") for (int q = 0; q < 4; ++q) { t0[q] = sigmoidf_(v0[q]) * y0[q]; t1[q] = sigmoidf_(v1[q]) * y1[q]; }
;                 pg8::u32x4* mp = (pg8::u32x4*)((u.kind == 2 && u.aux != 0 ? PMp + (size_t)(u.aux - 1) * RC * DM - (size_t)RL * DM : MMp) + (size_t)row * DM + col);
;                 if (u.kind == 1 && u.aux != 0) { f32x4 p0, p1; unpack8(*mp, p0, p1); t0 += p0; t1 += p1; }
;                 *mp = pack8(t0, t1); ) }
	v_lshlrev_b32_e32 v148, 16, v208
	v_and_b32_e32 v149, 0xffff0000, v208
	v_lshlrev_b32_e32 v150, 16, v209
	v_and_b32_e32 v151, 0xffff0000, v209
	v_lshlrev_b32_e32 v168, 16, v210
	v_and_b32_e32 v169, 0xffff0000, v210
	v_lshlrev_b32_e32 v170, 16, v211
	v_and_b32_e32 v171, 0xffff0000, v211
	v_pk_mul_f32 v[140:141], v[140:141], v[148:149]
	v_pk_mul_f32 v[142:143], v[142:143], v[150:151]
	v_pk_mul_f32 v[144:145], v[144:145], v[168:169]
	v_pk_mul_f32 v[146:147], v[146:147], v[170:171]
	v_cvt_pk_bf16_f32 v176, v140, v141
	v_cvt_pk_bf16_f32 v177, v142, v143
	v_cvt_pk_bf16_f32 v178, v144, v145
	v_cvt_pk_bf16_f32 v179, v146, v147
	s_add_u32 s8, s98, 0x18000
	s_addc_u32 s9, s99, 0
	global_store_dwordx4 v139, v[176:179], s[8:9] offset:256
	v_pk_mul_f32 v[140:141], v[62:63], s[4:5] op_sel_hi:[1,0]
	v_pk_mul_f32 v[142:143], v[64:65], s[4:5] op_sel_hi:[1,0]
	v_pk_mul_f32 v[144:145], v[58:59], s[4:5] op_sel_hi:[1,0]
	v_pk_mul_f32 v[146:147], v[60:61], s[4:5] op_sel_hi:[1,0]
	v_exp_f32_e32 v140, v140
	v_exp_f32_e32 v141, v141
	v_exp_f32_e32 v142, v142
	v_exp_f32_e32 v143, v143
	v_exp_f32_e32 v144, v144
	v_exp_f32_e32 v145, v145
	v_exp_f32_e32 v146, v146
	v_exp_f32_e32 v147, v147
	v_pk_add_f32 v[140:141], v[140:141], 1.0 op_sel_hi:[1,0]
	v_pk_add_f32 v[142:143], v[142:143], 1.0 op_sel_hi:[1,0]
	v_pk_add_f32 v[144:145], v[144:145], 1.0 op_sel_hi:[1,0]
	v_pk_add_f32 v[146:147], v[146:147], 1.0 op_sel_hi:[1,0]
	v_rcp_f32_e32 v140, v140
	v_rcp_f32_e32 v141, v141
	v_rcp_f32_e32 v142, v142
	v_rcp_f32_e32 v143, v143
	v_rcp_f32_e32 v144, v144
	v_rcp_f32_e32 v145, v145
	v_rcp_f32_e32 v146, v146
	v_rcp_f32_e32 v147, v147
	s_waitcnt vmcnt(15)
	v_lshlrev_b32_e32 v148, 16, v212
	v_and_b32_e32 v149, 0xffff0000, v212
	v_lshlrev_b32_e32 v150, 16, v213
	v_and_b32_e32 v151, 0xffff0000, v213
	v_lshlrev_b32_e32 v168, 16, v214
	v_and_b32_e32 v169, 0xffff0000, v214
	v_lshlrev_b32_e32 v170, 16, v215
	v_and_b32_e32 v171, 0xffff0000, v215
	v_pk_mul_f32 v[140:141], v[140:141], v[148:149]
	v_pk_mul_f32 v[142:143], v[142:143], v[150:151]
	v_pk_mul_f32 v[144:145], v[144:145], v[168:169]
	v_pk_mul_f32 v[146:147], v[146:147], v[170:171]
	v_cvt_pk_bf16_f32 v172, v140, v141
	v_cvt_pk_bf16_f32 v173, v142, v143
	v_cvt_pk_bf16_f32 v174, v144, v145
	v_cvt_pk_bf16_f32 v175, v146, v147
	s_add_u32 s8, s98, 0x40000
	s_addc_u32 s9, s99, 0
	global_store_dwordx4 v139, v[172:175], s[8:9]
	v_pk_mul_f32 v[140:141], v[50:51], s[4:5] op_sel_hi:[1,0]
	v_pk_mul_f32 v[142:143], v[52:53], s[4:5] op_sel_hi:[1,0]
	v_pk_mul_f32 v[144:145], v[42:43], s[4:5] op_sel_hi:[1,0]
	v_pk_mul_f32 v[146:147], v[44:45], s[4:5] op_sel_hi:[1,0]
	v_exp_f32_e32 v140, v140
	v_exp_f32_e32 v141, v141
	v_exp_f32_e32 v142, v142
	v_exp_f32_e32 v143, v143
	v_exp_f32_e32 v144, v144
	v_exp_f32_e32 v145, v145
	v_exp_f32_e32 v146, v146
	v_exp_f32_e32 v147, v147
	v_pk_add_f32 v[140:141], v[140:141], 1.0 op_sel_hi:[1,0]
	v_pk_add_f32 v[142:143], v[142:143], 1.0 op_sel_hi:[1,0]
	v_pk_add_f32 v[144:145], v[144:145], 1.0 op_sel_hi:[1,0]
	v_pk_add_f32 v[146:147], v[146:147], 1.0 op_sel_hi:[1,0]
	v_rcp_f32_e32 v140, v140
	v_rcp_f32_e32 v141, v141
	v_rcp_f32_e32 v142, v142
	v_rcp_f32_e32 v143, v143
	v_rcp_f32_e32 v144, v144
	v_rcp_f32_e32 v145, v145
	v_rcp_f32_e32 v146, v146
	v_rcp_f32_e32 v147, v147
	s_waitcnt vmcnt(15)
	v_lshlrev_b32_e32 v148, 16, v216
	v_and_b32_e32 v149, 0xffff0000, v216
	v_lshlrev_b32_e32 v150, 16, v217
	v_and_b32_e32 v151, 0xffff0000, v217
	v_lshlrev_b32_e32 v168, 16, v218
	v_and_b32_e32 v169, 0xffff0000, v218
	v_lshlrev_b32_e32 v170, 16, v219
	v_and_b32_e32 v171, 0xffff0000, v219
	v_pk_mul_f32 v[140:141], v[140:141], v[148:149]
	v_pk_mul_f32 v[142:143], v[142:143], v[150:151]
	v_pk_mul_f32 v[144:145], v[144:145], v[168:169]
	v_pk_mul_f32 v[146:147], v[146:147], v[170:171]
	v_cvt_pk_bf16_f32 v176, v140, v141
	v_cvt_pk_bf16_f32 v177, v142, v143
	v_cvt_pk_bf16_f32 v178, v144, v145
	v_cvt_pk_bf16_f32 v179, v146, v147
	s_add_u32 s8, s98, 0x40000
	s_addc_u32 s9, s99, 0
	global_store_dwordx4 v139, v[176:179], s[8:9] offset:256
	v_pk_mul_f32 v[140:141], v[54:55], s[4:5] op_sel_hi:[1,0]
	v_pk_mul_f32 v[142:143], v[56:57], s[4:5] op_sel_hi:[1,0]
	v_pk_mul_f32 v[144:145], v[46:47], s[4:5] op_sel_hi:[1,0]
	v_pk_mul_f32 v[146:147], v[48:49], s[4:5] op_sel_hi:[1,0]
	v_exp_f32_e32 v140, v140
	v_exp_f32_e32 v141, v141
	v_exp_f32_e32 v142, v142
	v_exp_f32_e32 v143, v143
	v_exp_f32_e32 v144, v144
	v_exp_f32_e32 v145, v145
	v_exp_f32_e32 v146, v146
	v_exp_f32_e32 v147, v147
	v_pk_add_f32 v[140:141], v[140:141], 1.0 op_sel_hi:[1,0]
	v_pk_add_f32 v[142:143], v[142:143], 1.0 op_sel_hi:[1,0]
	v_pk_add_f32 v[144:145], v[144:145], 1.0 op_sel_hi:[1,0]
	v_pk_add_f32 v[146:147], v[146:147], 1.0 op_sel_hi:[1,0]
	v_rcp_f32_e32 v140, v140
	v_rcp_f32_e32 v141, v141
	v_rcp_f32_e32 v142, v142
	v_rcp_f32_e32 v143, v143
	v_rcp_f32_e32 v144, v144
	v_rcp_f32_e32 v145, v145
	v_rcp_f32_e32 v146, v146
	v_rcp_f32_e32 v147, v147
	s_waitcnt vmcnt(15)
; __device__ __forceinline__ float sigmoidf_(float x) { return 1.f / (1.f + __expf(-x)); }
; __device__ __forceinline__ pg8::u32x4 pack8(const f32x4 a, const f32x4 b) { pg8::u32x4 w; w.x = pg8::cvt_pk_bf16(a[0], a[1]); w.y = pg8::cvt_pk_bf16(a[2], a[3]); w.z = pg8::cvt_pk_bf16(b[0], b[1]); w.w = pg8::cvt_pk_bf16(b[2], b[3]); return w; }
; #define EPI_FOREACH(...) _Pragma("unroll") for (int ai = 0; ai < 2; ++ai) _Pragma("unroll") for (int m = 0; m < 4; ++m) _Pragma("unroll") for (int bj = 0; bj < 2; ++bj) { \
;         const int row = u.pm * 256 + ai * 128 + wr * 64 + m * 16 + fr, col = u.pn * 256 + bj * 128 + wc * 32 + 8 * fq; const f32x4 v0 = acc[ai][bj][m][0], v1 = acc[ai][bj][m][1]; (void)row; (void)col; __VA_ARGS__ }
;     __device__ __forceinline__ void operator()(const f32x4 (&acc)[2][2][4][2], const pg8::Unit& u, int wr, int wc, int fr, int fq) const {
;     ...
;         else { EPI_FOREACH( f32x4 y0, y1; unpack8(stash[((ai * 4 + m) * 2 + bj) * NT + tid], y0, y1); f32x4 t0, t1;
;                 _Pragma("unroll") for (int q = 0; q < 4; ++q) { t0[q] = sigmoidf_(v0[q]) * y0[q]; t1[q] = sigmoidf_(v1[q]) * y1[q]; }
;                 pg8::u32x4* mp = (pg8::u32x4*)((u.kind == 2 && u.aux != 0 ? PMp + (size_t)(u.aux - 1) * RC * DM - (size_t)RL * DM : MMp) + (size_t)row * DM + col);
;                 if (u.kind == 1 && u.aux != 0) { f32x4 p0, p1; unpack8(*mp, p0, p1); t0 += p0; t1 += p1; }
;                 *mp = pack8(t0, t1); ) }
	v_lshlrev_b32_e32 v148, 16, v220
	v_and_b32_e32 v149, 0xffff0000, v220
	v_lshlrev_b32_e32 v150, 16, v221
	v_and_b32_e32 v151, 0xffff0000, v221
	v_lshlrev_b32_e32 v168, 16, v222
	v_and_b32_e32 v169, 0xffff0000, v222
	v_lshlrev_b32_e32 v170, 16, v223
	v_and_b32_e32 v171, 0xffff0000, v223
	v_pk_mul_f32 v[140:141], v[140:141], v[148:149]
	v_pk_mul_f32 v[142:143], v[142:143], v[150:151]
	v_pk_mul_f32 v[144:145], v[144:145], v[168:169]
	v_pk_mul_f32 v[146:147], v[146:147], v[170:171]
	v_cvt_pk_bf16_f32 v172, v140, v141
	v_cvt_pk_bf16_f32 v173, v142, v143
	v_cvt_pk_bf16_f32 v174, v144, v145
	v_cvt_pk_bf16_f32 v175, v146, v147
	s_add_u32 s8, s98, 0x48000
	s_addc_u32 s9, s99, 0
	global_store_dwordx4 v139, v[172:175], s[8:9]
	v_pk_mul_f32 v[140:141], v[34:35], s[4:5] op_sel_hi:[1,0]
	v_pk_mul_f32 v[142:143], v[36:37], s[4:5] op_sel_hi:[1,0]
	v_pk_mul_f32 v[144:145], v[26:27], s[4:5] op_sel_hi:[1,0]
	v_pk_mul_f32 v[146:147], v[28:29], s[4:5] op_sel_hi:[1,0]
	v_exp_f32_e32 v140, v140
	v_exp_f32_e32 v141, v141
	v_exp_f32_e32 v142, v142
	v_exp_f32_e32 v143, v143
	v_exp_f32_e32 v144, v144
	v_exp_f32_e32 v145, v145
	v_exp_f32_e32 v146, v146
	v_exp_f32_e32 v147, v147
	v_pk_add_f32 v[140:141], v[140:141], 1.0 op_sel_hi:[1,0]
	v_pk_add_f32 v[142:143], v[142:143], 1.0 op_sel_hi:[1,0]
	v_pk_add_f32 v[144:145], v[144:145], 1.0 op_sel_hi:[1,0]
	v_pk_add_f32 v[146:147], v[146:147], 1.0 op_sel_hi:[1,0]
	v_rcp_f32_e32 v140, v140
	v_rcp_f32_e32 v141, v141
	v_rcp_f32_e32 v142, v142
	v_rcp_f32_e32 v143, v143
	v_rcp_f32_e32 v144, v144
	v_rcp_f32_e32 v145, v145
	v_rcp_f32_e32 v146, v146
	v_rcp_f32_e32 v147, v147
	s_waitcnt vmcnt(15)
	v_lshlrev_b32_e32 v148, 16, v224
	v_and_b32_e32 v149, 0xffff0000, v224
	v_lshlrev_b32_e32 v150, 16, v225
	v_and_b32_e32 v151, 0xffff0000, v225
	v_lshlrev_b32_e32 v168, 16, v226
	v_and_b32_e32 v169, 0xffff0000, v226
	v_lshlrev_b32_e32 v170, 16, v227
	v_and_b32_e32 v171, 0xffff0000, v227
	v_pk_mul_f32 v[140:141], v[140:141], v[148:149]
	v_pk_mul_f32 v[142:143], v[142:143], v[150:151]
	v_pk_mul_f32 v[144:145], v[144:145], v[168:169]
	v_pk_mul_f32 v[146:147], v[146:147], v[170:171]
	v_cvt_pk_bf16_f32 v176, v140, v141
	v_cvt_pk_bf16_f32 v177, v142, v143
	v_cvt_pk_bf16_f32 v178, v144, v145
	v_cvt_pk_bf16_f32 v179, v146, v147
	s_add_u32 s8, s98, 0x48000
	s_addc_u32 s9, s99, 0
	global_store_dwordx4 v139, v[176:179], s[8:9] offset:256
	v_pk_mul_f32 v[140:141], v[38:39], s[4:5] op_sel_hi:[1,0]
	v_pk_mul_f32 v[142:143], v[40:41], s[4:5] op_sel_hi:[1,0]
	v_pk_mul_f32 v[144:145], v[30:31], s[4:5] op_sel_hi:[1,0]
	v_pk_mul_f32 v[146:147], v[32:33], s[4:5] op_sel_hi:[1,0]
	v_exp_f32_e32 v140, v140
	v_exp_f32_e32 v141, v141
	v_exp_f32_e32 v142, v142
	v_exp_f32_e32 v143, v143
	v_exp_f32_e32 v144, v144
	v_exp_f32_e32 v145, v145
	v_exp_f32_e32 v146, v146
	v_exp_f32_e32 v147, v147
	v_pk_add_f32 v[140:141], v[140:141], 1.0 op_sel_hi:[1,0]
	v_pk_add_f32 v[142:143], v[142:143], 1.0 op_sel_hi:[1,0]
	v_pk_add_f32 v[144:145], v[144:145], 1.0 op_sel_hi:[1,0]
	v_pk_add_f32 v[146:147], v[146:147], 1.0 op_sel_hi:[1,0]
	v_rcp_f32_e32 v140, v140
	v_rcp_f32_e32 v141, v141
	v_rcp_f32_e32 v142, v142
	v_rcp_f32_e32 v143, v143
	v_rcp_f32_e32 v144, v144
	v_rcp_f32_e32 v145, v145
	v_rcp_f32_e32 v146, v146
	v_rcp_f32_e32 v147, v147
	s_waitcnt vmcnt(15)
	v_lshlrev_b32_e32 v148, 16, v180
	v_and_b32_e32 v149, 0xffff0000, v180
	v_lshlrev_b32_e32 v150, 16, v181
	v_and_b32_e32 v151, 0xffff0000, v181
	v_lshlrev_b32_e32 v168, 16, v182
	v_and_b32_e32 v169, 0xffff0000, v182
	v_lshlrev_b32_e32 v170, 16, v183
	v_and_b32_e32 v171, 0xffff0000, v183
	v_pk_mul_f32 v[140:141], v[140:141], v[148:149]
	v_pk_mul_f32 v[142:143], v[142:143], v[150:151]
	v_pk_mul_f32 v[144:145], v[144:145], v[168:169]
	v_pk_mul_f32 v[146:147], v[146:147], v[170:171]
	v_cvt_pk_bf16_f32 v172, v140, v141
	v_cvt_pk_bf16_f32 v173, v142, v143
	v_cvt_pk_bf16_f32 v174, v144, v145
	v_cvt_pk_bf16_f32 v175, v146, v147
	s_add_u32 s8, s98, 0x50000
	s_addc_u32 s9, s99, 0
	global_store_dwordx4 v139, v[172:175], s[8:9]
	v_pk_mul_f32 v[140:141], v[18:19], s[4:5] op_sel_hi:[1,0]
	v_pk_mul_f32 v[142:143], v[20:21], s[4:5] op_sel_hi:[1,0]
	v_pk_mul_f32 v[144:145], v[10:11], s[4:5] op_sel_hi:[1,0]
	v_pk_mul_f32 v[146:147], v[12:13], s[4:5] op_sel_hi:[1,0]
	v_exp_f32_e32 v140, v140
	v_exp_f32_e32 v141, v141
	v_exp_f32_e32 v142, v142
	v_exp_f32_e32 v143, v143
	v_exp_f32_e32 v144, v144
	v_exp_f32_e32 v145, v145
	v_exp_f32_e32 v146, v146
	v_exp_f32_e32 v147, v147
	v_pk_add_f32 v[140:141], v[140:141], 1.0 op_sel_hi:[1,0]
	v_pk_add_f32 v[142:143], v[142:143], 1.0 op_sel_hi:[1,0]
	v_pk_add_f32 v[144:145], v[144:145], 1.0 op_sel_hi:[1,0]
	v_pk_add_f32 v[146:147], v[146:147], 1.0 op_sel_hi:[1,0]
	v_rcp_f32_e32 v140, v140
	v_rcp_f32_e32 v141, v141
	v_rcp_f32_e32 v142, v142
	v_rcp_f32_e32 v143, v143
	v_rcp_f32_e32 v144, v144
	v_rcp_f32_e32 v145, v145
	v_rcp_f32_e32 v146, v146
	v_rcp_f32_e32 v147, v147
	s_waitcnt vmcnt(14)
; __device__ __forceinline__ float sigmoidf_(float x) { return 1.f / (1.f + __expf(-x)); }
; __device__ __forceinline__ pg8::u32x4 pack8(const f32x4 a, const f32x4 b) { pg8::u32x4 w; w.x = pg8::cvt_pk_bf16(a[0], a[1]); w.y = pg8::cvt_pk_bf16(a[2], a[3]); w.z = pg8::cvt_pk_bf16(b[0], b[1]); w.w = pg8::cvt_pk_bf16(b[2], b[3]); return w; }
; #define EPI_FOREACH(...) _Pragma("unroll") for (int ai = 0; ai < 2; ++ai) _Pragma("unroll") for (int m = 0; m < 4; ++m) _Pragma("unroll") for (int bj = 0; bj < 2; ++bj) { \
;         const int row = u.pm * 256 + ai * 128 + wr * 64 + m * 16 + fr, col = u.pn * 256 + bj * 128 + wc * 32 + 8 * fq; const f32x4 v0 = acc[ai][bj][m][0], v1 = acc[ai][bj][m][1]; (void)row; (void)col; __VA_ARGS__ }
;     __device__ __forceinline__ void operator()(const f32x4 (&acc)[2][2][4][2], const pg8::Unit& u, int wr, int wc, int fr, int fq) const {
;     ...
;         else { EPI_FOREACH( f32x4 y0, y1; unpack8(stash[((ai * 4 + m) * 2 + bj) * NT + tid], y0, y1); f32x4 t0, t1;
;                 _Pragma("unroll") for (int q = 0; q < 4; ++q) { t0[q] = sigmoidf_(v0[q]) * y0[q]; t1[q] = sigmoidf_(v1[q]) * y1[q]; }
;                 pg8::u32x4* mp = (pg8::u32x4*)((u.kind == 2 && u.aux != 0 ? PMp + (size_t)(u.aux - 1) * RC * DM - (size_t)RL * DM : MMp) + (size_t)row * DM + col);
;                 if (u.kind == 1 && u.aux != 0) { f32x4 p0, p1; unpack8(*mp, p0, p1); t0 += p0; t1 += p1; }
;                 *mp = pack8(t0, t1); ) }
	v_lshlrev_b32_e32 v148, 16, v184
	v_and_b32_e32 v149, 0xffff0000, v184
	v_lshlrev_b32_e32 v150, 16, v185
	v_and_b32_e32 v151, 0xffff0000, v185
	v_lshlrev_b32_e32 v168, 16, v186
	v_and_b32_e32 v169, 0xffff0000, v186
	v_lshlrev_b32_e32 v170, 16, v187
	v_and_b32_e32 v171, 0xffff0000, v187
	v_pk_mul_f32 v[140:141], v[140:141], v[148:149]
	v_pk_mul_f32 v[142:143], v[142:143], v[150:151]
	v_pk_mul_f32 v[144:145], v[144:145], v[168:169]
	v_pk_mul_f32 v[146:147], v[146:147], v[170:171]
	v_cvt_pk_bf16_f32 v176, v140, v141
	v_cvt_pk_bf16_f32 v177, v142, v143
	v_cvt_pk_bf16_f32 v178, v144, v145
	v_cvt_pk_bf16_f32 v179, v146, v147
	s_add_u32 s8, s98, 0x50000
	s_addc_u32 s9, s99, 0
	global_store_dwordx4 v139, v[176:179], s[8:9] offset:256
	v_pk_mul_f32 v[140:141], v[22:23], s[4:5] op_sel_hi:[1,0]
	v_pk_mul_f32 v[142:143], v[24:25], s[4:5] op_sel_hi:[1,0]
	v_pk_mul_f32 v[144:145], v[14:15], s[4:5] op_sel_hi:[1,0]
	v_pk_mul_f32 v[146:147], v[16:17], s[4:5] op_sel_hi:[1,0]
	v_exp_f32_e32 v140, v140
	v_exp_f32_e32 v141, v141
	v_exp_f32_e32 v142, v142
	v_exp_f32_e32 v143, v143
	v_exp_f32_e32 v144, v144
	v_exp_f32_e32 v145, v145
	v_exp_f32_e32 v146, v146
	v_exp_f32_e32 v147, v147
	v_pk_add_f32 v[140:141], v[140:141], 1.0 op_sel_hi:[1,0]
	v_pk_add_f32 v[142:143], v[142:143], 1.0 op_sel_hi:[1,0]
	v_pk_add_f32 v[144:145], v[144:145], 1.0 op_sel_hi:[1,0]
	v_pk_add_f32 v[146:147], v[146:147], 1.0 op_sel_hi:[1,0]
	v_rcp_f32_e32 v140, v140
	v_rcp_f32_e32 v141, v141
	v_rcp_f32_e32 v142, v142
	v_rcp_f32_e32 v143, v143
	v_rcp_f32_e32 v144, v144
	v_rcp_f32_e32 v145, v145
	v_rcp_f32_e32 v146, v146
	v_rcp_f32_e32 v147, v147
	s_waitcnt vmcnt(13)
	v_lshlrev_b32_e32 v148, 16, v188
	v_and_b32_e32 v149, 0xffff0000, v188
	v_lshlrev_b32_e32 v150, 16, v189
	v_and_b32_e32 v151, 0xffff0000, v189
	v_lshlrev_b32_e32 v168, 16, v190
	v_and_b32_e32 v169, 0xffff0000, v190
	v_lshlrev_b32_e32 v170, 16, v191
	v_and_b32_e32 v171, 0xffff0000, v191
	v_pk_mul_f32 v[140:141], v[140:141], v[148:149]
	v_pk_mul_f32 v[142:143], v[142:143], v[150:151]
	v_pk_mul_f32 v[144:145], v[144:145], v[168:169]
	v_pk_mul_f32 v[146:147], v[146:147], v[170:171]
	v_cvt_pk_bf16_f32 v172, v140, v141
	v_cvt_pk_bf16_f32 v173, v142, v143
	v_cvt_pk_bf16_f32 v174, v144, v145
	v_cvt_pk_bf16_f32 v175, v146, v147
	s_add_u32 s8, s98, 0x58000
	s_addc_u32 s9, s99, 0
	global_store_dwordx4 v139, v[172:175], s[8:9]
	v_pk_mul_f32 v[140:141], v[6:7], s[4:5] op_sel_hi:[1,0]
	v_pk_mul_f32 v[142:143], v[8:9], s[4:5] op_sel_hi:[1,0]
	v_pk_mul_f32 v[144:145], v[2:3], s[4:5] op_sel_hi:[1,0]
	v_pk_mul_f32 v[146:147], v[4:5], s[4:5] op_sel_hi:[1,0]
	v_exp_f32_e32 v140, v140
	v_exp_f32_e32 v141, v141
	v_exp_f32_e32 v142, v142
	v_exp_f32_e32 v143, v143
	v_exp_f32_e32 v144, v144
	v_exp_f32_e32 v145, v145
	v_exp_f32_e32 v146, v146
	v_exp_f32_e32 v147, v147
	v_pk_add_f32 v[140:141], v[140:141], 1.0 op_sel_hi:[1,0]
	v_pk_add_f32 v[142:143], v[142:143], 1.0 op_sel_hi:[1,0]
	v_pk_add_f32 v[144:145], v[144:145], 1.0 op_sel_hi:[1,0]
	v_pk_add_f32 v[146:147], v[146:147], 1.0 op_sel_hi:[1,0]
	v_rcp_f32_e32 v140, v140
	v_rcp_f32_e32 v141, v141
	v_rcp_f32_e32 v142, v142
	v_rcp_f32_e32 v143, v143
	v_rcp_f32_e32 v144, v144
	v_rcp_f32_e32 v145, v145
	v_rcp_f32_e32 v146, v146
	v_rcp_f32_e32 v147, v147
	s_waitcnt vmcnt(12)
	v_lshlrev_b32_e32 v148, 16, v192
	v_and_b32_e32 v149, 0xffff0000, v192
	v_lshlrev_b32_e32 v150, 16, v193
	v_and_b32_e32 v151, 0xffff0000, v193
	v_lshlrev_b32_e32 v168, 16, v194
	v_and_b32_e32 v169, 0xffff0000, v194
	v_lshlrev_b32_e32 v170, 16, v195
	v_and_b32_e32 v171, 0xffff0000, v195
	v_pk_mul_f32 v[140:141], v[140:141], v[148:149]
	v_pk_mul_f32 v[142:143], v[142:143], v[150:151]
	v_pk_mul_f32 v[144:145], v[144:145], v[168:169]
	v_pk_mul_f32 v[146:147], v[146:147], v[170:171]
	v_cvt_pk_bf16_f32 v176, v140, v141
	v_cvt_pk_bf16_f32 v177, v142, v143
	v_cvt_pk_bf16_f32 v178, v144, v145
	v_cvt_pk_bf16_f32 v179, v146, v147
	s_add_u32 s8, s98, 0x58000
	s_addc_u32 s9, s99, 0
	global_store_dwordx4 v139, v[176:179], s[8:9] offset:256
.Lmrg0_done:
	s_branch .LBB0_1391
; __device__ __forceinline__ pg8::u32x4 pack8(const f32x4 a, const f32x4 b) { pg8::u32x4 w; w.x = pg8::cvt_pk_bf16(a[0], a[1]); w.y = pg8::cvt_pk_bf16(a[2], a[3]); w.z = pg8::cvt_pk_bf16(b[0], b[1]); w.w = pg8::cvt_pk_bf16(b[2], b[3]); return w; }
; #define EPI_FOREACH(...) _Pragma("unroll") for (int ai = 0; ai < 2; ++ai) _Pragma("unroll") for (int m = 0; m < 4; ++m) _Pragma("unroll") for (int bj = 0; bj < 2; ++bj) { \
;         const int row = u.pm * 256 + ai * 128 + wr * 64 + m * 16 + fr, col = u.pn * 256 + bj * 128 + wc * 32 + 8 * fq; const f32x4 v0 = acc[ai][bj][m][0], v1 = acc[ai][bj][m][1]; (void)row; (void)col; __VA_ARGS__ }
;     __device__ __forceinline__ void operator()(const f32x4 (&acc)[2][2][4][2], const pg8::Unit& u, int wr, int wc, int fr, int fq) const {
;     ...
;         if (u.kind == 0) { EPI_FOREACH( stash[((ai * 4 + m) * 2 + bj) * NT + tid] = pack8(v0, v1); if (bj && (m & 1)) asm volatile("" ::: "memory"); ) }
.LBB0_1390:
	v_cvt_pk_bf16_f32 v126, v126, v127
	v_cvt_pk_bf16_f32 v127, v128, v129
	v_cvt_pk_bf16_f32 v128, v122, v123
	v_lshl_add_u64 v[122:123], v[136:137], 4, s[16:17]
	v_cvt_pk_bf16_f32 v129, v124, v125
	global_store_dwordx4 v[122:123], v[126:129], off
	v_cvt_pk_bf16_f32 v114, v114, v115
	v_cvt_pk_bf16_f32 v115, v116, v117
	v_cvt_pk_bf16_f32 v116, v106, v107
	v_add_co_u32_e32 v106, vcc, s58, v122
	s_movk_i32 s4, 0x4000
	s_nop 0
	v_addc_co_u32_e32 v107, vcc, 0, v123, vcc
	v_cvt_pk_bf16_f32 v117, v108, v109
	global_store_dwordx4 v[106:107], v[114:117], off
	v_cvt_pk_bf16_f32 v106, v118, v119
	v_cvt_pk_bf16_f32 v107, v120, v121
	v_cvt_pk_bf16_f32 v108, v110, v111
	v_add_co_u32_e32 v110, vcc, s4, v122
	s_movk_i32 s4, 0x6000
	s_nop 0
	v_addc_co_u32_e32 v111, vcc, 0, v123, vcc
	v_cvt_pk_bf16_f32 v109, v112, v113
	global_store_dwordx4 v[110:111], v[106:109], off
	v_cvt_pk_bf16_f32 v98, v98, v99
	v_cvt_pk_bf16_f32 v99, v100, v101
	v_cvt_pk_bf16_f32 v100, v90, v91
	v_add_co_u32_e32 v90, vcc, s4, v122
	v_cvt_pk_bf16_f32 v101, v92, v93
	s_mov_b32 s4, 0x8000
	s_nop 0
	v_addc_co_u32_e32 v91, vcc, 0, v123, vcc
	global_store_dwordx4 v[90:91], v[98:101], off
	v_cvt_pk_bf16_f32 v90, v102, v103
	v_cvt_pk_bf16_f32 v91, v104, v105
	v_cvt_pk_bf16_f32 v92, v94, v95
	v_add_co_u32_e32 v94, vcc, s4, v122
	s_mov_b32 s4, 0xa000
	s_nop 0
	v_addc_co_u32_e32 v95, vcc, 0, v123, vcc
	v_cvt_pk_bf16_f32 v93, v96, v97
	global_store_dwordx4 v[94:95], v[90:93], off
	v_cvt_pk_bf16_f32 v82, v82, v83
	v_cvt_pk_bf16_f32 v83, v84, v85
	v_cvt_pk_bf16_f32 v84, v74, v75
	v_add_co_u32_e32 v74, vcc, s4, v122
	v_cvt_pk_bf16_f32 v85, v76, v77
	s_mov_b32 s4, 0x10000
	s_nop 0
	v_addc_co_u32_e32 v75, vcc, 0, v123, vcc
	global_store_dwordx4 v[74:75], v[82:85], off
	v_cvt_pk_bf16_f32 v74, v86, v87
	v_cvt_pk_bf16_f32 v75, v88, v89
	v_cvt_pk_bf16_f32 v76, v78, v79
	v_add_co_u32_e32 v78, vcc, s74, v122
	v_cvt_pk_bf16_f32 v77, v80, v81
	s_nop 1
	v_addc_co_u32_e32 v79, vcc, 0, v123, vcc
	global_store_dwordx4 v[78:79], v[74:77], off
	v_cvt_pk_bf16_f32 v70, v70, v71
	v_cvt_pk_bf16_f32 v71, v72, v73
	v_cvt_pk_bf16_f32 v72, v66, v67
	v_add_co_u32_e32 v66, vcc, s75, v122
	v_cvt_pk_bf16_f32 v73, v68, v69
	s_nop 1
	v_addc_co_u32_e32 v67, vcc, 0, v123, vcc
	global_store_dwordx4 v[66:67], v[70:73], off
	v_cvt_pk_bf16_f32 v62, v62, v63
	v_cvt_pk_bf16_f32 v63, v64, v65
	v_cvt_pk_bf16_f32 v64, v58, v59
	v_add_co_u32_e32 v58, vcc, s4, v122
	s_mov_b32 s4, 0x12000
	s_nop 0
	v_addc_co_u32_e32 v59, vcc, 0, v123, vcc
	v_cvt_pk_bf16_f32 v65, v60, v61
	global_store_dwordx4 v[58:59], v[62:65], off
	v_cvt_pk_bf16_f32 v50, v50, v51
	v_cvt_pk_bf16_f32 v51, v52, v53
	v_cvt_pk_bf16_f32 v52, v42, v43
	v_add_co_u32_e32 v42, vcc, s4, v122
	s_mov_b32 s4, 0x14000
	s_nop 0
	v_addc_co_u32_e32 v43, vcc, 0, v123, vcc
	v_cvt_pk_bf16_f32 v53, v44, v45
	global_store_dwordx4 v[42:43], v[50:53], off
	v_cvt_pk_bf16_f32 v42, v54, v55
	v_cvt_pk_bf16_f32 v43, v56, v57
	v_cvt_pk_bf16_f32 v44, v46, v47
	v_add_co_u32_e32 v46, vcc, s4, v122
	s_mov_b32 s4, 0x16000
	s_nop 0
	v_addc_co_u32_e32 v47, vcc, 0, v123, vcc
	v_cvt_pk_bf16_f32 v45, v48, v49
	global_store_dwordx4 v[46:47], v[42:45], off
	v_cvt_pk_bf16_f32 v34, v34, v35
	v_cvt_pk_bf16_f32 v35, v36, v37
	v_cvt_pk_bf16_f32 v36, v26, v27
	v_add_co_u32_e32 v26, vcc, s4, v122
	v_cvt_pk_bf16_f32 v37, v28, v29
	s_mov_b32 s4, 0x18000
	s_nop 0
	v_addc_co_u32_e32 v27, vcc, 0, v123, vcc
	global_store_dwordx4 v[26:27], v[34:37], off
	v_cvt_pk_bf16_f32 v26, v38, v39
	v_cvt_pk_bf16_f32 v27, v40, v41
	v_cvt_pk_bf16_f32 v28, v30, v31
	v_add_co_u32_e32 v30, vcc, s4, v122
	s_mov_b32 s4, 0x1a000
	s_nop 0
	v_addc_co_u32_e32 v31, vcc, 0, v123, vcc
	v_cvt_pk_bf16_f32 v29, v32, v33
	global_store_dwordx4 v[30:31], v[26:29], off
	v_cvt_pk_bf16_f32 v18, v18, v19
	v_cvt_pk_bf16_f32 v19, v20, v21
	v_cvt_pk_bf16_f32 v20, v10, v11
	v_add_co_u32_e32 v10, vcc, s4, v122
	s_mov_b32 s4, 0x1c000
	s_nop 0
	v_addc_co_u32_e32 v11, vcc, 0, v123, vcc
	v_cvt_pk_bf16_f32 v21, v12, v13
	global_store_dwordx4 v[10:11], v[18:21], off
	v_cvt_pk_bf16_f32 v10, v22, v23
	v_cvt_pk_bf16_f32 v11, v24, v25
	v_cvt_pk_bf16_f32 v12, v14, v15
	v_add_co_u32_e32 v14, vcc, s4, v122
	v_cvt_pk_bf16_f32 v13, v16, v17
	s_nop 1
	v_addc_co_u32_e32 v15, vcc, 0, v123, vcc
	global_store_dwordx4 v[14:15], v[10:13], off
	v_cvt_pk_bf16_f32 v6, v6, v7
	v_cvt_pk_bf16_f32 v7, v8, v9
	v_cvt_pk_bf16_f32 v8, v2, v3
	v_add_co_u32_e32 v2, vcc, 0x1e000, v122
	v_cvt_pk_bf16_f32 v9, v4, v5
	s_nop 1
	v_addc_co_u32_e32 v3, vcc, 0, v123, vcc
	global_store_dwordx4 v[2:3], v[6:9], off

; __device__ __forceinline__ float sigmoidf_(float x) { return 1.f / (1.f + __expf(-x)); }
; __device__ __forceinline__ pg8::u32x4 pack8(const f32x4 a, const f32x4 b) { pg8::u32x4 w; w.x = pg8::cvt_pk_bf16(a[0], a[1]); w.y = pg8::cvt_pk_bf16(a[2], a[3]); w.z = pg8::cvt_pk_bf16(b[0], b[1]); w.w = pg8::cvt_pk_bf16(b[2], b[3]); return w; }
; #define EPI_FOREACH(...) _Pragma("unroll") for (int ai = 0; ai < 2; ++ai) _Pragma("unroll") for (int m = 0; m < 4; ++m) _Pragma("unroll") for (int bj = 0; bj < 2; ++bj) { \
;         const int row = u.pm * 256 + ai * 128 + wr * 64 + m * 16 + fr, col = u.pn * 256 + bj * 128 + wc * 32 + 8 * fq; const f32x4 v0 = acc[ai][bj][m][0], v1 = acc[ai][bj][m][1]; (void)row; (void)col; __VA_ARGS__ }
;     __device__ __forceinline__ void operator()(const f32x4 (&acc)[2][2][4][2], const pg8::Unit& u, int wr, int wc, int fr, int fq) const {
;     ...
;         else { EPI_FOREACH( f32x4 y0, y1; unpack8(stash[((ai * 4 + m) * 2 + bj) * NT + tid], y0, y1); f32x4 t0, t1;
;                 _Pragma("unroll") for (int q = 0; q < 4; ++q) { t0[q] = sigmoidf_(v0[q]) * y0[q]; t1[q] = sigmoidf_(v1[q]) * y1[q]; }
;                 pg8::u32x4* mp = (pg8::u32x4*)((u.kind == 2 && u.aux != 0 ? PMp + (size_t)(u.aux - 1) * RC * DM - (size_t)RL * DM : MMp) + (size_t)row * DM + col);
;                 if (u.kind == 1 && u.aux != 0) { f32x4 p0, p1; unpack8(*mp, p0, p1); t0 += p0; t1 += p1; }
;                 *mp = pack8(t0, t1); ) }
.LBB0_3115:
	v_mov_b32_e32 v136, v0
	s_cmp_lg_u32 s5, 0
	v_ashrrev_i32_e32 v137, 31, v136
	s_cbranch_scc0 .LBB0_3153
	s_lshl_b32 s30, s4, 8
	v_lshlrev_b32_e32 v138, 4, v136
	v_add_u32_e32 v139, s30, v154
	v_lshl_or_b32 v132, s84, 8, v163
	v_lshlrev_b32_e32 v139, 11, v139
	v_lshl_add_u32 v139, v132, 1, v139
	s_mov_b64 s[98:99], s[12:13]
	s_mov_b32 s4, 0xbfb8aa3b
	s_cmp_lg_u32 s85, 0
	s_cbranch_scc0 .Lmrg1_plain
	s_add_u32 s10, s16, 0x0
	s_addc_u32 s11, s17, 0
	global_load_dwordx4 v[180:183], v138, s[10:11]
	s_add_u32 s6, s98, 0x0
	s_addc_u32 s7, s99, 0
	global_load_dwordx4 v[184:187], v139, s[6:7]
	s_add_u32 s10, s16, 0x2000
	s_addc_u32 s11, s17, 0
	global_load_dwordx4 v[188:191], v138, s[10:11]
	s_add_u32 s6, s98, 0x0
	s_addc_u32 s7, s99, 0
	global_load_dwordx4 v[192:195], v139, s[6:7] offset:256
	s_add_u32 s10, s16, 0x4000
	s_addc_u32 s11, s17, 0
	global_load_dwordx4 v[196:199], v138, s[10:11]
	s_add_u32 s6, s98, 0x8000
	s_addc_u32 s7, s99, 0
	global_load_dwordx4 v[200:203], v139, s[6:7]
	s_add_u32 s10, s16, 0x6000
	s_addc_u32 s11, s17, 0
	global_load_dwordx4 v[204:207], v138, s[10:11]
	s_add_u32 s6, s98, 0x8000
	s_addc_u32 s7, s99, 0
	global_load_dwordx4 v[208:211], v139, s[6:7] offset:256
	s_add_u32 s10, s16, 0x8000
	s_addc_u32 s11, s17, 0
	global_load_dwordx4 v[212:215], v138, s[10:11]
	s_add_u32 s6, s98, 0x10000
	s_addc_u32 s7, s99, 0
	global_load_dwordx4 v[216:219], v139, s[6:7]
	s_add_u32 s10, s16, 0xa000
	s_addc_u32 s11, s17, 0
	global_load_dwordx4 v[220:223], v138, s[10:11]
	s_add_u32 s6, s98, 0x10000
	s_addc_u32 s7, s99, 0
	global_load_dwordx4 v[224:227], v139, s[6:7] offset:256
	v_pk_mul_f32 v[140:141], v[126:127], s[4:5] op_sel_hi:[1,0]
	v_pk_mul_f32 v[142:143], v[128:129], s[4:5] op_sel_hi:[1,0]
	v_pk_mul_f32 v[144:145], v[122:123], s[4:5] op_sel_hi:[1,0]
	v_pk_mul_f32 v[146:147], v[124:125], s[4:5] op_sel_hi:[1,0]
	v_exp_f32_e32 v140, v140
	v_exp_f32_e32 v141, v141
	v_exp_f32_e32 v142, v142
	v_exp_f32_e32 v143, v143
	v_exp_f32_e32 v144, v144
	v_exp_f32_e32 v145, v145
	v_exp_f32_e32 v146, v146
	v_exp_f32_e32 v147, v147
	v_pk_add_f32 v[140:141], v[140:141], 1.0 op_sel_hi:[1,0]
	v_pk_add_f32 v[142:143], v[142:143], 1.0 op_sel_hi:[1,0]
	v_pk_add_f32 v[144:145], v[144:145], 1.0 op_sel_hi:[1,0]
	v_pk_add_f32 v[146:147], v[146:147], 1.0 op_sel_hi:[1,0]
	v_rcp_f32_e32 v140, v140
	v_rcp_f32_e32 v141, v141
	v_rcp_f32_e32 v142, v142
	v_rcp_f32_e32 v143, v143
	v_rcp_f32_e32 v144, v144
	v_rcp_f32_e32 v145, v145
	v_rcp_f32_e32 v146, v146
	v_rcp_f32_e32 v147, v147
	s_waitcnt vmcnt(10)
	v_lshlrev_b32_e32 v148, 16, v180
	v_and_b32_e32 v149, 0xffff0000, v180
	v_lshlrev_b32_e32 v150, 16, v181
	v_and_b32_e32 v151, 0xffff0000, v181
	v_lshlrev_b32_e32 v168, 16, v182
	v_and_b32_e32 v169, 0xffff0000, v182
	v_lshlrev_b32_e32 v170, 16, v183
	v_and_b32_e32 v171, 0xffff0000, v183
	v_pk_mul_f32 v[140:141], v[140:141], v[148:149]
	v_pk_mul_f32 v[142:143], v[142:143], v[150:151]
	v_pk_mul_f32 v[144:145], v[144:145], v[168:169]
	v_pk_mul_f32 v[146:147], v[146:147], v[170:171]
	v_lshlrev_b32_e32 v148, 16, v184
	v_and_b32_e32 v149, 0xffff0000, v184
	v_lshlrev_b32_e32 v150, 16, v185
	v_and_b32_e32 v151, 0xffff0000, v185
	v_lshlrev_b32_e32 v168, 16, v186
	v_and_b32_e32 v169, 0xffff0000, v186
	v_lshlrev_b32_e32 v170, 16, v187
	v_and_b32_e32 v171, 0xffff0000, v187
	v_pk_add_f32 v[140:141], v[140:141], v[148:149]
	v_pk_add_f32 v[142:143], v[142:143], v[150:151]
	v_pk_add_f32 v[144:145], v[144:145], v[168:169]
	v_pk_add_f32 v[146:147], v[146:147], v[170:171]
	v_cvt_pk_bf16_f32 v172, v140, v141
	v_cvt_pk_bf16_f32 v173, v142, v143
	v_cvt_pk_bf16_f32 v174, v144, v145
	v_cvt_pk_bf16_f32 v175, v146, v147
	s_add_u32 s10, s16, 0xc000
	s_addc_u32 s11, s17, 0
	global_load_dwordx4 v[180:183], v138, s[10:11]
	s_add_u32 s6, s98, 0x18000
	s_addc_u32 s7, s99, 0
	global_load_dwordx4 v[184:187], v139, s[6:7]
	s_add_u32 s8, s98, 0x0
	s_addc_u32 s9, s99, 0
	global_store_dwordx4 v139, v[172:175], s[8:9]
	v_pk_mul_f32 v[140:141], v[114:115], s[4:5] op_sel_hi:[1,0]
	v_pk_mul_f32 v[142:143], v[116:117], s[4:5] op_sel_hi:[1,0]
	v_pk_mul_f32 v[144:145], v[106:107], s[4:5] op_sel_hi:[1,0]
	v_pk_mul_f32 v[146:147], v[108:109], s[4:5] op_sel_hi:[1,0]
	v_exp_f32_e32 v140, v140
	v_exp_f32_e32 v141, v141
	v_exp_f32_e32 v142, v142
	v_exp_f32_e32 v143, v143
	v_exp_f32_e32 v144, v144
	v_exp_f32_e32 v145, v145
	v_exp_f32_e32 v146, v146
	v_exp_f32_e32 v147, v147
	v_pk_add_f32 v[140:141], v[140:141], 1.0 op_sel_hi:[1,0]
	v_pk_add_f32 v[142:143], v[142:143], 1.0 op_sel_hi:[1,0]
	v_pk_add_f32 v[144:145], v[144:145], 1.0 op_sel_hi:[1,0]
	v_pk_add_f32 v[146:147], v[146:147], 1.0 op_sel_hi:[1,0]
	v_rcp_f32_e32 v140, v140
	v_rcp_f32_e32 v141, v141
	v_rcp_f32_e32 v142, v142
	v_rcp_f32_e32 v143, v143
	v_rcp_f32_e32 v144, v144
	v_rcp_f32_e32 v145, v145
	v_rcp_f32_e32 v146, v146
	v_rcp_f32_e32 v147, v147
	s_waitcnt vmcnt(11)
; __device__ __forceinline__ float sigmoidf_(float x) { return 1.f / (1.f + __expf(-x)); }
; __device__ __forceinline__ pg8::u32x4 pack8(const f32x4 a, const f32x4 b) { pg8::u32x4 w; w.x = pg8::cvt_pk_bf16(a[0], a[1]); w.y = pg8::cvt_pk_bf16(a[2], a[3]); w.z = pg8::cvt_pk_bf16(b[0], b[1]); w.w = pg8::cvt_pk_bf16(b[2], b[3]); return w; }
; #define EPI_FOREACH(...) _Pragma("unroll") for (int ai = 0; ai < 2; ++ai) _Pragma("unroll") for (int m = 0; m < 4; ++m) _Pragma("unroll") for (int bj = 0; bj < 2; ++bj) { \
;         const int row = u.pm * 256 + ai * 128 + wr * 64 + m * 16 + fr, col = u.pn * 256 + bj * 128 + wc * 32 + 8 * fq; const f32x4 v0 = acc[ai][bj][m][0], v1 = acc[ai][bj][m][1]; (void)row; (void)col; __VA_ARGS__ }
;     __device__ __forceinline__ void operator()(const f32x4 (&acc)[2][2][4][2], const pg8::Unit& u, int wr, int wc, int fr, int fq) const {
;     ...
;         else { EPI_FOREACH( f32x4 y0, y1; unpack8(stash[((ai * 4 + m) * 2 + bj) * NT + tid], y0, y1); f32x4 t0, t1;
;                 _Pragma("unroll") for (int q = 0; q < 4; ++q) { t0[q] = sigmoidf_(v0[q]) * y0[q]; t1[q] = sigmoidf_(v1[q]) * y1[q]; }
;                 pg8::u32x4* mp = (pg8::u32x4*)((u.kind == 2 && u.aux != 0 ? PMp + (size_t)(u.aux - 1) * RC * DM - (size_t)RL * DM : MMp) + (size_t)row * DM + col);
;                 if (u.kind == 1 && u.aux != 0) { f32x4 p0, p1; unpack8(*mp, p0, p1); t0 += p0; t1 += p1; }
;                 *mp = pack8(t0, t1); ) }
	v_lshlrev_b32_e32 v148, 16, v188
	v_and_b32_e32 v149, 0xffff0000, v188
	v_lshlrev_b32_e32 v150, 16, v189
	v_and_b32_e32 v151, 0xffff0000, v189
	v_lshlrev_b32_e32 v168, 16, v190
	v_and_b32_e32 v169, 0xffff0000, v190
	v_lshlrev_b32_e32 v170, 16, v191
	v_and_b32_e32 v171, 0xffff0000, v191
	v_pk_mul_f32 v[140:141], v[140:141], v[148:149]
	v_pk_mul_f32 v[142:143], v[142:143], v[150:151]
	v_pk_mul_f32 v[144:145], v[144:145], v[168:169]
	v_pk_mul_f32 v[146:147], v[146:147], v[170:171]
	v_lshlrev_b32_e32 v148, 16, v192
	v_and_b32_e32 v149, 0xffff0000, v192
	v_lshlrev_b32_e32 v150, 16, v193
	v_and_b32_e32 v151, 0xffff0000, v193
	v_lshlrev_b32_e32 v168, 16, v194
	v_and_b32_e32 v169, 0xffff0000, v194
	v_lshlrev_b32_e32 v170, 16, v195
	v_and_b32_e32 v171, 0xffff0000, v195
	v_pk_add_f32 v[140:141], v[140:141], v[148:149]
	v_pk_add_f32 v[142:143], v[142:143], v[150:151]
	v_pk_add_f32 v[144:145], v[144:145], v[168:169]
	v_pk_add_f32 v[146:147], v[146:147], v[170:171]
	v_cvt_pk_bf16_f32 v176, v140, v141
	v_cvt_pk_bf16_f32 v177, v142, v143
	v_cvt_pk_bf16_f32 v178, v144, v145
	v_cvt_pk_bf16_f32 v179, v146, v147
	s_add_u32 s10, s16, 0xe000
	s_addc_u32 s11, s17, 0
	global_load_dwordx4 v[188:191], v138, s[10:11]
	s_add_u32 s6, s98, 0x18000
	s_addc_u32 s7, s99, 0
	global_load_dwordx4 v[192:195], v139, s[6:7] offset:256
	s_add_u32 s8, s98, 0x0
	s_addc_u32 s9, s99, 0
	global_store_dwordx4 v139, v[176:179], s[8:9] offset:256
	v_pk_mul_f32 v[140:141], v[118:119], s[4:5] op_sel_hi:[1,0]
	v_pk_mul_f32 v[142:143], v[120:121], s[4:5] op_sel_hi:[1,0]
	v_pk_mul_f32 v[144:145], v[110:111], s[4:5] op_sel_hi:[1,0]
	v_pk_mul_f32 v[146:147], v[112:113], s[4:5] op_sel_hi:[1,0]
	v_exp_f32_e32 v140, v140
	v_exp_f32_e32 v141, v141
	v_exp_f32_e32 v142, v142
	v_exp_f32_e32 v143, v143
	v_exp_f32_e32 v144, v144
	v_exp_f32_e32 v145, v145
	v_exp_f32_e32 v146, v146
	v_exp_f32_e32 v147, v147
	v_pk_add_f32 v[140:141], v[140:141], 1.0 op_sel_hi:[1,0]
	v_pk_add_f32 v[142:143], v[142:143], 1.0 op_sel_hi:[1,0]
	v_pk_add_f32 v[144:145], v[144:145], 1.0 op_sel_hi:[1,0]
	v_pk_add_f32 v[146:147], v[146:147], 1.0 op_sel_hi:[1,0]
	v_rcp_f32_e32 v140, v140
	v_rcp_f32_e32 v141, v141
	v_rcp_f32_e32 v142, v142
	v_rcp_f32_e32 v143, v143
	v_rcp_f32_e32 v144, v144
	v_rcp_f32_e32 v145, v145
	v_rcp_f32_e32 v146, v146
	v_rcp_f32_e32 v147, v147
	s_waitcnt vmcnt(12)
	v_lshlrev_b32_e32 v148, 16, v196
	v_and_b32_e32 v149, 0xffff0000, v196
	v_lshlrev_b32_e32 v150, 16, v197
	v_and_b32_e32 v151, 0xffff0000, v197
	v_lshlrev_b32_e32 v168, 16, v198
	v_and_b32_e32 v169, 0xffff0000, v198
	v_lshlrev_b32_e32 v170, 16, v199
	v_and_b32_e32 v171, 0xffff0000, v199
	v_pk_mul_f32 v[140:141], v[140:141], v[148:149]
	v_pk_mul_f32 v[142:143], v[142:143], v[150:151]
	v_pk_mul_f32 v[144:145], v[144:145], v[168:169]
	v_pk_mul_f32 v[146:147], v[146:147], v[170:171]
	v_lshlrev_b32_e32 v148, 16, v200
	v_and_b32_e32 v149, 0xffff0000, v200
	v_lshlrev_b32_e32 v150, 16, v201
	v_and_b32_e32 v151, 0xffff0000, v201
	v_lshlrev_b32_e32 v168, 16, v202
	v_and_b32_e32 v169, 0xffff0000, v202
	v_lshlrev_b32_e32 v170, 16, v203
	v_and_b32_e32 v171, 0xffff0000, v203
	v_pk_add_f32 v[140:141], v[140:141], v[148:149]
	v_pk_add_f32 v[142:143], v[142:143], v[150:151]
	v_pk_add_f32 v[144:145], v[144:145], v[168:169]
	v_pk_add_f32 v[146:147], v[146:147], v[170:171]
	v_cvt_pk_bf16_f32 v172, v140, v141
	v_cvt_pk_bf16_f32 v173, v142, v143
	v_cvt_pk_bf16_f32 v174, v144, v145
	v_cvt_pk_bf16_f32 v175, v146, v147
	s_add_u32 s10, s16, 0x10000
	s_addc_u32 s11, s17, 0
	global_load_dwordx4 v[196:199], v138, s[10:11]
	s_add_u32 s6, s98, 0x40000
	s_addc_u32 s7, s99, 0
	global_load_dwordx4 v[200:203], v139, s[6:7]
	s_add_u32 s8, s98, 0x8000
	s_addc_u32 s9, s99, 0
	global_store_dwordx4 v139, v[172:175], s[8:9]
	v_pk_mul_f32 v[140:141], v[98:99], s[4:5] op_sel_hi:[1,0]
	v_pk_mul_f32 v[142:143], v[100:101], s[4:5] op_sel_hi:[1,0]
	v_pk_mul_f32 v[144:145], v[90:91], s[4:5] op_sel_hi:[1,0]
	v_pk_mul_f32 v[146:147], v[92:93], s[4:5] op_sel_hi:[1,0]
	v_exp_f32_e32 v140, v140
	v_exp_f32_e32 v141, v141
	v_exp_f32_e32 v142, v142
	v_exp_f32_e32 v143, v143
	v_exp_f32_e32 v144, v144
	v_exp_f32_e32 v145, v145
	v_exp_f32_e32 v146, v146
	v_exp_f32_e32 v147, v147
	v_pk_add_f32 v[140:141], v[140:141], 1.0 op_sel_hi:[1,0]
	v_pk_add_f32 v[142:143], v[142:143], 1.0 op_sel_hi:[1,0]
	v_pk_add_f32 v[144:145], v[144:145], 1.0 op_sel_hi:[1,0]
	v_pk_add_f32 v[146:147], v[146:147], 1.0 op_sel_hi:[1,0]
	v_rcp_f32_e32 v140, v140
	v_rcp_f32_e32 v141, v141
	v_rcp_f32_e32 v142, v142
	v_rcp_f32_e32 v143, v143
	v_rcp_f32_e32 v144, v144
	v_rcp_f32_e32 v145, v145
	v_rcp_f32_e32 v146, v146
	v_rcp_f32_e32 v147, v147
	s_waitcnt vmcnt(13)
; __device__ __forceinline__ float sigmoidf_(float x) { return 1.f / (1.f + __expf(-x)); }
; __device__ __forceinline__ pg8::u32x4 pack8(const f32x4 a, const f32x4 b) { pg8::u32x4 w; w.x = pg8::cvt_pk_bf16(a[0], a[1]); w.y = pg8::cvt_pk_bf16(a[2], a[3]); w.z = pg8::cvt_pk_bf16(b[0], b[1]); w.w = pg8::cvt_pk_bf16(b[2], b[3]); return w; }
; #define EPI_FOREACH(...) _Pragma("unroll") for (int ai = 0; ai < 2; ++ai) _Pragma("unroll") for (int m = 0; m < 4; ++m) _Pragma("unroll") for (int bj = 0; bj < 2; ++bj) { \
;         const int row = u.pm * 256 + ai * 128 + wr * 64 + m * 16 + fr, col = u.pn * 256 + bj * 128 + wc * 32 + 8 * fq; const f32x4 v0 = acc[ai][bj][m][0], v1 = acc[ai][bj][m][1]; (void)row; (void)col; __VA_ARGS__ }
;     __device__ __forceinline__ void operator()(const f32x4 (&acc)[2][2][4][2], const pg8::Unit& u, int wr, int wc, int fr, int fq) const {
;     ...
;         else { EPI_FOREACH( f32x4 y0, y1; unpack8(stash[((ai * 4 + m) * 2 + bj) * NT + tid], y0, y1); f32x4 t0, t1;
;                 _Pragma("unroll") for (int q = 0; q < 4; ++q) { t0[q] = sigmoidf_(v0[q]) * y0[q]; t1[q] = sigmoidf_(v1[q]) * y1[q]; }
;                 pg8::u32x4* mp = (pg8::u32x4*)((u.kind == 2 && u.aux != 0 ? PMp + (size_t)(u.aux - 1) * RC * DM - (size_t)RL * DM : MMp) + (size_t)row * DM + col);
;                 if (u.kind == 1 && u.aux != 0) { f32x4 p0, p1; unpack8(*mp, p0, p1); t0 += p0; t1 += p1; }
;                 *mp = pack8(t0, t1); ) }
	v_lshlrev_b32_e32 v148, 16, v204
	v_and_b32_e32 v149, 0xffff0000, v204
	v_lshlrev_b32_e32 v150, 16, v205
	v_and_b32_e32 v151, 0xffff0000, v205
	v_lshlrev_b32_e32 v168, 16, v206
	v_and_b32_e32 v169, 0xffff0000, v206
	v_lshlrev_b32_e32 v170, 16, v207
	v_and_b32_e32 v171, 0xffff0000, v207
	v_pk_mul_f32 v[140:141], v[140:141], v[148:149]
	v_pk_mul_f32 v[142:143], v[142:143], v[150:151]
	v_pk_mul_f32 v[144:145], v[144:145], v[168:169]
	v_pk_mul_f32 v[146:147], v[146:147], v[170:171]
	v_lshlrev_b32_e32 v148, 16, v208
	v_and_b32_e32 v149, 0xffff0000, v208
	v_lshlrev_b32_e32 v150, 16, v209
	v_and_b32_e32 v151, 0xffff0000, v209
	v_lshlrev_b32_e32 v168, 16, v210
	v_and_b32_e32 v169, 0xffff0000, v210
	v_lshlrev_b32_e32 v170, 16, v211
	v_and_b32_e32 v171, 0xffff0000, v211
	v_pk_add_f32 v[140:141], v[140:141], v[148:149]
	v_pk_add_f32 v[142:143], v[142:143], v[150:151]
	v_pk_add_f32 v[144:145], v[144:145], v[168:169]
	v_pk_add_f32 v[146:147], v[146:147], v[170:171]
	v_cvt_pk_bf16_f32 v176, v140, v141
	v_cvt_pk_bf16_f32 v177, v142, v143
	v_cvt_pk_bf16_f32 v178, v144, v145
	v_cvt_pk_bf16_f32 v179, v146, v147
	s_add_u32 s10, s16, 0x12000
	s_addc_u32 s11, s17, 0
	global_load_dwordx4 v[204:207], v138, s[10:11]
	s_add_u32 s6, s98, 0x40000
	s_addc_u32 s7, s99, 0
	global_load_dwordx4 v[208:211], v139, s[6:7] offset:256
	s_add_u32 s8, s98, 0x8000
	s_addc_u32 s9, s99, 0
	global_store_dwordx4 v139, v[176:179], s[8:9] offset:256
	v_pk_mul_f32 v[140:141], v[102:103], s[4:5] op_sel_hi:[1,0]
	v_pk_mul_f32 v[142:143], v[104:105], s[4:5] op_sel_hi:[1,0]
	v_pk_mul_f32 v[144:145], v[94:95], s[4:5] op_sel_hi:[1,0]
	v_pk_mul_f32 v[146:147], v[96:97], s[4:5] op_sel_hi:[1,0]
	v_exp_f32_e32 v140, v140
	v_exp_f32_e32 v141, v141
	v_exp_f32_e32 v142, v142
	v_exp_f32_e32 v143, v143
	v_exp_f32_e32 v144, v144
	v_exp_f32_e32 v145, v145
	v_exp_f32_e32 v146, v146
	v_exp_f32_e32 v147, v147
	v_pk_add_f32 v[140:141], v[140:141], 1.0 op_sel_hi:[1,0]
	v_pk_add_f32 v[142:143], v[142:143], 1.0 op_sel_hi:[1,0]
	v_pk_add_f32 v[144:145], v[144:145], 1.0 op_sel_hi:[1,0]
	v_pk_add_f32 v[146:147], v[146:147], 1.0 op_sel_hi:[1,0]
	v_rcp_f32_e32 v140, v140
	v_rcp_f32_e32 v141, v141
	v_rcp_f32_e32 v142, v142
	v_rcp_f32_e32 v143, v143
	v_rcp_f32_e32 v144, v144
	v_rcp_f32_e32 v145, v145
	v_rcp_f32_e32 v146, v146
	v_rcp_f32_e32 v147, v147
	s_waitcnt vmcnt(14)
	v_lshlrev_b32_e32 v148, 16, v212
	v_and_b32_e32 v149, 0xffff0000, v212
	v_lshlrev_b32_e32 v150, 16, v213
	v_and_b32_e32 v151, 0xffff0000, v213
	v_lshlrev_b32_e32 v168, 16, v214
	v_and_b32_e32 v169, 0xffff0000, v214
	v_lshlrev_b32_e32 v170, 16, v215
	v_and_b32_e32 v171, 0xffff0000, v215
	v_pk_mul_f32 v[140:141], v[140:141], v[148:149]
	v_pk_mul_f32 v[142:143], v[142:143], v[150:151]
	v_pk_mul_f32 v[144:145], v[144:145], v[168:169]
	v_pk_mul_f32 v[146:147], v[146:147], v[170:171]
	v_lshlrev_b32_e32 v148, 16, v216
	v_and_b32_e32 v149, 0xffff0000, v216
	v_lshlrev_b32_e32 v150, 16, v217
	v_and_b32_e32 v151, 0xffff0000, v217
	v_lshlrev_b32_e32 v168, 16, v218
	v_and_b32_e32 v169, 0xffff0000, v218
	v_lshlrev_b32_e32 v170, 16, v219
	v_and_b32_e32 v171, 0xffff0000, v219
	v_pk_add_f32 v[140:141], v[140:141], v[148:149]
	v_pk_add_f32 v[142:143], v[142:143], v[150:151]
	v_pk_add_f32 v[144:145], v[144:145], v[168:169]
	v_pk_add_f32 v[146:147], v[146:147], v[170:171]
	v_cvt_pk_bf16_f32 v172, v140, v141
	v_cvt_pk_bf16_f32 v173, v142, v143
	v_cvt_pk_bf16_f32 v174, v144, v145
	v_cvt_pk_bf16_f32 v175, v146, v147
	s_add_u32 s10, s16, 0x14000
	s_addc_u32 s11, s17, 0
	global_load_dwordx4 v[212:215], v138, s[10:11]
	s_add_u32 s6, s98, 0x48000
	s_addc_u32 s7, s99, 0
	global_load_dwordx4 v[216:219], v139, s[6:7]
	s_add_u32 s8, s98, 0x10000
	s_addc_u32 s9, s99, 0
	global_store_dwordx4 v139, v[172:175], s[8:9]
	v_pk_mul_f32 v[140:141], v[82:83], s[4:5] op_sel_hi:[1,0]
	v_pk_mul_f32 v[142:143], v[84:85], s[4:5] op_sel_hi:[1,0]
	v_pk_mul_f32 v[144:145], v[74:75], s[4:5] op_sel_hi:[1,0]
	v_pk_mul_f32 v[146:147], v[76:77], s[4:5] op_sel_hi:[1,0]
	v_exp_f32_e32 v140, v140
	v_exp_f32_e32 v141, v141
	v_exp_f32_e32 v142, v142
	v_exp_f32_e32 v143, v143
	v_exp_f32_e32 v144, v144
	v_exp_f32_e32 v145, v145
	v_exp_f32_e32 v146, v146
	v_exp_f32_e32 v147, v147
	v_pk_add_f32 v[140:141], v[140:141], 1.0 op_sel_hi:[1,0]
	v_pk_add_f32 v[142:143], v[142:143], 1.0 op_sel_hi:[1,0]
	v_pk_add_f32 v[144:145], v[144:145], 1.0 op_sel_hi:[1,0]
	v_pk_add_f32 v[146:147], v[146:147], 1.0 op_sel_hi:[1,0]
	v_rcp_f32_e32 v140, v140
	v_rcp_f32_e32 v141, v141
	v_rcp_f32_e32 v142, v142
	v_rcp_f32_e32 v143, v143
	v_rcp_f32_e32 v144, v144
	v_rcp_f32_e32 v145, v145
	v_rcp_f32_e32 v146, v146
	v_rcp_f32_e32 v147, v147
	s_waitcnt vmcnt(15)
; __device__ __forceinline__ float sigmoidf_(float x) { return 1.f / (1.f + __expf(-x)); }
; __device__ __forceinline__ pg8::u32x4 pack8(const f32x4 a, const f32x4 b) { pg8::u32x4 w; w.x = pg8::cvt_pk_bf16(a[0], a[1]); w.y = pg8::cvt_pk_bf16(a[2], a[3]); w.z = pg8::cvt_pk_bf16(b[0], b[1]); w.w = pg8::cvt_pk_bf16(b[2], b[3]); return w; }
; #define EPI_FOREACH(...) _Pragma("unroll") for (int ai = 0; ai < 2; ++ai) _Pragma("unroll") for (int m = 0; m < 4; ++m) _Pragma("unroll") for (int bj = 0; bj < 2; ++bj) { \
;         const int row = u.pm * 256 + ai * 128 + wr * 64 + m * 16 + fr, col = u.pn * 256 + bj * 128 + wc * 32 + 8 * fq; const f32x4 v0 = acc[ai][bj][m][0], v1 = acc[ai][bj][m][1]; (void)row; (void)col; __VA_ARGS__ }
;     __device__ __forceinline__ void operator()(const f32x4 (&acc)[2][2][4][2], const pg8::Unit& u, int wr, int wc, int fr, int fq) const {
;     ...
;         else { EPI_FOREACH( f32x4 y0, y1; unpack8(stash[((ai * 4 + m) * 2 + bj) * NT + tid], y0, y1); f32x4 t0, t1;
;                 _Pragma("unroll") for (int q = 0; q < 4; ++q) { t0[q] = sigmoidf_(v0[q]) * y0[q]; t1[q] = sigmoidf_(v1[q]) * y1[q]; }
;                 pg8::u32x4* mp = (pg8::u32x4*)((u.kind == 2 && u.aux != 0 ? PMp + (size_t)(u.aux - 1) * RC * DM - (size_t)RL * DM : MMp) + (size_t)row * DM + col);
;                 if (u.kind == 1 && u.aux != 0) { f32x4 p0, p1; unpack8(*mp, p0, p1); t0 += p0; t1 += p1; }
;                 *mp = pack8(t0, t1); ) }
	v_lshlrev_b32_e32 v148, 16, v220
	v_and_b32_e32 v149, 0xffff0000, v220
	v_lshlrev_b32_e32 v150, 16, v221
	v_and_b32_e32 v151, 0xffff0000, v221
	v_lshlrev_b32_e32 v168, 16, v222
	v_and_b32_e32 v169, 0xffff0000, v222
	v_lshlrev_b32_e32 v170, 16, v223
	v_and_b32_e32 v171, 0xffff0000, v223
	v_pk_mul_f32 v[140:141], v[140:141], v[148:149]
	v_pk_mul_f32 v[142:143], v[142:143], v[150:151]
	v_pk_mul_f32 v[144:145], v[144:145], v[168:169]
	v_pk_mul_f32 v[146:147], v[146:147], v[170:171]
	v_lshlrev_b32_e32 v148, 16, v224
	v_and_b32_e32 v149, 0xffff0000, v224
	v_lshlrev_b32_e32 v150, 16, v225
	v_and_b32_e32 v151, 0xffff0000, v225
	v_lshlrev_b32_e32 v168, 16, v226
	v_and_b32_e32 v169, 0xffff0000, v226
	v_lshlrev_b32_e32 v170, 16, v227
	v_and_b32_e32 v171, 0xffff0000, v227
	v_pk_add_f32 v[140:141], v[140:141], v[148:149]
	v_pk_add_f32 v[142:143], v[142:143], v[150:151]
	v_pk_add_f32 v[144:145], v[144:145], v[168:169]
	v_pk_add_f32 v[146:147], v[146:147], v[170:171]
	v_cvt_pk_bf16_f32 v176, v140, v141
	v_cvt_pk_bf16_f32 v177, v142, v143
	v_cvt_pk_bf16_f32 v178, v144, v145
	v_cvt_pk_bf16_f32 v179, v146, v147
	s_add_u32 s10, s16, 0x16000
	s_addc_u32 s11, s17, 0
	global_load_dwordx4 v[220:223], v138, s[10:11]
	s_add_u32 s6, s98, 0x48000
	s_addc_u32 s7, s99, 0
	global_load_dwordx4 v[224:227], v139, s[6:7] offset:256
	s_add_u32 s8, s98, 0x10000
	s_addc_u32 s9, s99, 0
	global_store_dwordx4 v139, v[176:179], s[8:9] offset:256
	v_pk_mul_f32 v[140:141], v[86:87], s[4:5] op_sel_hi:[1,0]
	v_pk_mul_f32 v[142:143], v[88:89], s[4:5] op_sel_hi:[1,0]
	v_pk_mul_f32 v[144:145], v[78:79], s[4:5] op_sel_hi:[1,0]
	v_pk_mul_f32 v[146:147], v[80:81], s[4:5] op_sel_hi:[1,0]
	v_exp_f32_e32 v140, v140
	v_exp_f32_e32 v141, v141
	v_exp_f32_e32 v142, v142
	v_exp_f32_e32 v143, v143
	v_exp_f32_e32 v144, v144
	v_exp_f32_e32 v145, v145
	v_exp_f32_e32 v146, v146
	v_exp_f32_e32 v147, v147
	v_pk_add_f32 v[140:141], v[140:141], 1.0 op_sel_hi:[1,0]
	v_pk_add_f32 v[142:143], v[142:143], 1.0 op_sel_hi:[1,0]
	v_pk_add_f32 v[144:145], v[144:145], 1.0 op_sel_hi:[1,0]
	v_pk_add_f32 v[146:147], v[146:147], 1.0 op_sel_hi:[1,0]
	v_rcp_f32_e32 v140, v140
	v_rcp_f32_e32 v141, v141
	v_rcp_f32_e32 v142, v142
	v_rcp_f32_e32 v143, v143
	v_rcp_f32_e32 v144, v144
	v_rcp_f32_e32 v145, v145
	v_rcp_f32_e32 v146, v146
	v_rcp_f32_e32 v147, v147
	s_waitcnt vmcnt(16)
	v_lshlrev_b32_e32 v148, 16, v180
	v_and_b32_e32 v149, 0xffff0000, v180
	v_lshlrev_b32_e32 v150, 16, v181
	v_and_b32_e32 v151, 0xffff0000, v181
	v_lshlrev_b32_e32 v168, 16, v182
	v_and_b32_e32 v169, 0xffff0000, v182
	v_lshlrev_b32_e32 v170, 16, v183
	v_and_b32_e32 v171, 0xffff0000, v183
	v_pk_mul_f32 v[140:141], v[140:141], v[148:149]
	v_pk_mul_f32 v[142:143], v[142:143], v[150:151]
	v_pk_mul_f32 v[144:145], v[144:145], v[168:169]
	v_pk_mul_f32 v[146:147], v[146:147], v[170:171]
	v_lshlrev_b32_e32 v148, 16, v184
	v_and_b32_e32 v149, 0xffff0000, v184
	v_lshlrev_b32_e32 v150, 16, v185
	v_and_b32_e32 v151, 0xffff0000, v185
	v_lshlrev_b32_e32 v168, 16, v186
	v_and_b32_e32 v169, 0xffff0000, v186
	v_lshlrev_b32_e32 v170, 16, v187
	v_and_b32_e32 v171, 0xffff0000, v187
	v_pk_add_f32 v[140:141], v[140:141], v[148:149]
	v_pk_add_f32 v[142:143], v[142:143], v[150:151]
	v_pk_add_f32 v[144:145], v[144:145], v[168:169]
	v_pk_add_f32 v[146:147], v[146:147], v[170:171]
	v_cvt_pk_bf16_f32 v172, v140, v141
	v_cvt_pk_bf16_f32 v173, v142, v143
	v_cvt_pk_bf16_f32 v174, v144, v145
	v_cvt_pk_bf16_f32 v175, v146, v147
	s_add_u32 s10, s16, 0x18000
	s_addc_u32 s11, s17, 0
	global_load_dwordx4 v[180:183], v138, s[10:11]
	s_add_u32 s6, s98, 0x50000
	s_addc_u32 s7, s99, 0
	global_load_dwordx4 v[184:187], v139, s[6:7]
	s_add_u32 s8, s98, 0x18000
	s_addc_u32 s9, s99, 0
	global_store_dwordx4 v139, v[172:175], s[8:9]
	v_pk_mul_f32 v[140:141], v[70:71], s[4:5] op_sel_hi:[1,0]
	v_pk_mul_f32 v[142:143], v[72:73], s[4:5] op_sel_hi:[1,0]
	v_pk_mul_f32 v[144:145], v[66:67], s[4:5] op_sel_hi:[1,0]
	v_pk_mul_f32 v[146:147], v[68:69], s[4:5] op_sel_hi:[1,0]
	v_exp_f32_e32 v140, v140
	v_exp_f32_e32 v141, v141
	v_exp_f32_e32 v142, v142
	v_exp_f32_e32 v143, v143
	v_exp_f32_e32 v144, v144
	v_exp_f32_e32 v145, v145
	v_exp_f32_e32 v146, v146
	v_exp_f32_e32 v147, v147
	v_pk_add_f32 v[140:141], v[140:141], 1.0 op_sel_hi:[1,0]
	v_pk_add_f32 v[142:143], v[142:143], 1.0 op_sel_hi:[1,0]
	v_pk_add_f32 v[144:145], v[144:145], 1.0 op_sel_hi:[1,0]
	v_pk_add_f32 v[146:147], v[146:147], 1.0 op_sel_hi:[1,0]
	v_rcp_f32_e32 v140, v140
	v_rcp_f32_e32 v141, v141
	v_rcp_f32_e32 v142, v142
	v_rcp_f32_e32 v143, v143
	v_rcp_f32_e32 v144, v144
	v_rcp_f32_e32 v145, v145
	v_rcp_f32_e32 v146, v146
	v_rcp_f32_e32 v147, v147
	s_waitcnt vmcnt(16)
; __device__ __forceinline__ float sigmoidf_(float x) { return 1.f / (1.f + __expf(-x)); }
; __device__ __forceinline__ pg8::u32x4 pack8(const f32x4 a, const f32x4 b) { pg8::u32x4 w; w.x = pg8::cvt_pk_bf16(a[0], a[1]); w.y = pg8::cvt_pk_bf16(a[2], a[3]); w.z = pg8::cvt_pk_bf16(b[0], b[1]); w.w = pg8::cvt_pk_bf16(b[2], b[3]); return w; }
; #define EPI_FOREACH(...) _Pragma("unroll") for (int ai = 0; ai < 2; ++ai) _Pragma("unroll") for (int m = 0; m < 4; ++m) _Pragma("unroll") for (int bj = 0; bj < 2; ++bj) { \
;         const int row = u.pm * 256 + ai * 128 + wr * 64 + m * 16 + fr, col = u.pn * 256 + bj * 128 + wc * 32 + 8 * fq; const f32x4 v0 = acc[ai][bj][m][0], v1 = acc[ai][bj][m][1]; (void)row; (void)col; __VA_ARGS__ }
;     __device__ __forceinline__ void operator()(const f32x4 (&acc)[2][2][4][2], const pg8::Unit& u, int wr, int wc, int fr, int fq) const {
;     ...
;         else { EPI_FOREACH( f32x4 y0, y1; unpack8(stash[((ai * 4 + m) * 2 + bj) * NT + tid], y0, y1); f32x4 t0, t1;
;                 _Pragma("unroll") for (int q = 0; q < 4; ++q) { t0[q] = sigmoidf_(v0[q]) * y0[q]; t1[q] = sigmoidf_(v1[q]) * y1[q]; }
;                 pg8::u32x4* mp = (pg8::u32x4*)((u.kind == 2 && u.aux != 0 ? PMp + (size_t)(u.aux - 1) * RC * DM - (size_t)RL * DM : MMp) + (size_t)row * DM + col);
;                 if (u.kind == 1 && u.aux != 0) { f32x4 p0, p1; unpack8(*mp, p0, p1); t0 += p0; t1 += p1; }
;                 *mp = pack8(t0, t1); ) }
	v_lshlrev_b32_e32 v148, 16, v188
	v_and_b32_e32 v149, 0xffff0000, v188
	v_lshlrev_b32_e32 v150, 16, v189
	v_and_b32_e32 v151, 0xffff0000, v189
	v_lshlrev_b32_e32 v168, 16, v190
	v_and_b32_e32 v169, 0xffff0000, v190
	v_lshlrev_b32_e32 v170, 16, v191
	v_and_b32_e32 v171, 0xffff0000, v191
	v_pk_mul_f32 v[140:141], v[140:141], v[148:149]
	v_pk_mul_f32 v[142:143], v[142:143], v[150:151]
	v_pk_mul_f32 v[144:145], v[144:145], v[168:169]
	v_pk_mul_f32 v[146:147], v[146:147], v[170:171]
	v_lshlrev_b32_e32 v148, 16, v192
	v_and_b32_e32 v149, 0xffff0000, v192
	v_lshlrev_b32_e32 v150, 16, v193
	v_and_b32_e32 v151, 0xffff0000, v193
	v_lshlrev_b32_e32 v168, 16, v194
	v_and_b32_e32 v169, 0xffff0000, v194
	v_lshlrev_b32_e32 v170, 16, v195
	v_and_b32_e32 v171, 0xffff0000, v195
	v_pk_add_f32 v[140:141], v[140:141], v[148:149]
	v_pk_add_f32 v[142:143], v[142:143], v[150:151]
	v_pk_add_f32 v[144:145], v[144:145], v[168:169]
	v_pk_add_f32 v[146:147], v[146:147], v[170:171]
	v_cvt_pk_bf16_f32 v176, v140, v141
	v_cvt_pk_bf16_f32 v177, v142, v143
	v_cvt_pk_bf16_f32 v178, v144, v145
	v_cvt_pk_bf16_f32 v179, v146, v147
	s_add_u32 s10, s16, 0x1a000
	s_addc_u32 s11, s17, 0
	global_load_dwordx4 v[188:191], v138, s[10:11]
	s_add_u32 s6, s98, 0x50000
	s_addc_u32 s7, s99, 0
	global_load_dwordx4 v[192:195], v139, s[6:7] offset:256
	s_add_u32 s8, s98, 0x18000
	s_addc_u32 s9, s99, 0
	global_store_dwordx4 v139, v[176:179], s[8:9] offset:256
	v_pk_mul_f32 v[140:141], v[62:63], s[4:5] op_sel_hi:[1,0]
	v_pk_mul_f32 v[142:143], v[64:65], s[4:5] op_sel_hi:[1,0]
	v_pk_mul_f32 v[144:145], v[58:59], s[4:5] op_sel_hi:[1,0]
	v_pk_mul_f32 v[146:147], v[60:61], s[4:5] op_sel_hi:[1,0]
	v_exp_f32_e32 v140, v140
	v_exp_f32_e32 v141, v141
	v_exp_f32_e32 v142, v142
	v_exp_f32_e32 v143, v143
	v_exp_f32_e32 v144, v144
	v_exp_f32_e32 v145, v145
	v_exp_f32_e32 v146, v146
	v_exp_f32_e32 v147, v147
	v_pk_add_f32 v[140:141], v[140:141], 1.0 op_sel_hi:[1,0]
	v_pk_add_f32 v[142:143], v[142:143], 1.0 op_sel_hi:[1,0]
	v_pk_add_f32 v[144:145], v[144:145], 1.0 op_sel_hi:[1,0]
	v_pk_add_f32 v[146:147], v[146:147], 1.0 op_sel_hi:[1,0]
	v_rcp_f32_e32 v140, v140
	v_rcp_f32_e32 v141, v141
	v_rcp_f32_e32 v142, v142
	v_rcp_f32_e32 v143, v143
	v_rcp_f32_e32 v144, v144
	v_rcp_f32_e32 v145, v145
	v_rcp_f32_e32 v146, v146
	v_rcp_f32_e32 v147, v147
	s_waitcnt vmcnt(16)
	v_lshlrev_b32_e32 v148, 16, v196
	v_and_b32_e32 v149, 0xffff0000, v196
	v_lshlrev_b32_e32 v150, 16, v197
	v_and_b32_e32 v151, 0xffff0000, v197
	v_lshlrev_b32_e32 v168, 16, v198
	v_and_b32_e32 v169, 0xffff0000, v198
	v_lshlrev_b32_e32 v170, 16, v199
	v_and_b32_e32 v171, 0xffff0000, v199
	v_pk_mul_f32 v[140:141], v[140:141], v[148:149]
	v_pk_mul_f32 v[142:143], v[142:143], v[150:151]
	v_pk_mul_f32 v[144:145], v[144:145], v[168:169]
	v_pk_mul_f32 v[146:147], v[146:147], v[170:171]
	v_lshlrev_b32_e32 v148, 16, v200
	v_and_b32_e32 v149, 0xffff0000, v200
	v_lshlrev_b32_e32 v150, 16, v201
	v_and_b32_e32 v151, 0xffff0000, v201
	v_lshlrev_b32_e32 v168, 16, v202
	v_and_b32_e32 v169, 0xffff0000, v202
	v_lshlrev_b32_e32 v170, 16, v203
	v_and_b32_e32 v171, 0xffff0000, v203
	v_pk_add_f32 v[140:141], v[140:141], v[148:149]
	v_pk_add_f32 v[142:143], v[142:143], v[150:151]
	v_pk_add_f32 v[144:145], v[144:145], v[168:169]
	v_pk_add_f32 v[146:147], v[146:147], v[170:171]
	v_cvt_pk_bf16_f32 v172, v140, v141
	v_cvt_pk_bf16_f32 v173, v142, v143
	v_cvt_pk_bf16_f32 v174, v144, v145
	v_cvt_pk_bf16_f32 v175, v146, v147
	s_add_u32 s10, s16, 0x1c000
	s_addc_u32 s11, s17, 0
	global_load_dwordx4 v[196:199], v138, s[10:11]
	s_add_u32 s6, s98, 0x58000
	s_addc_u32 s7, s99, 0
	global_load_dwordx4 v[200:203], v139, s[6:7]
	s_add_u32 s8, s98, 0x40000
	s_addc_u32 s9, s99, 0
	global_store_dwordx4 v139, v[172:175], s[8:9]
	v_pk_mul_f32 v[140:141], v[50:51], s[4:5] op_sel_hi:[1,0]
	v_pk_mul_f32 v[142:143], v[52:53], s[4:5] op_sel_hi:[1,0]
	v_pk_mul_f32 v[144:145], v[42:43], s[4:5] op_sel_hi:[1,0]
	v_pk_mul_f32 v[146:147], v[44:45], s[4:5] op_sel_hi:[1,0]
	v_exp_f32_e32 v140, v140
	v_exp_f32_e32 v141, v141
	v_exp_f32_e32 v142, v142
	v_exp_f32_e32 v143, v143
	v_exp_f32_e32 v144, v144
	v_exp_f32_e32 v145, v145
	v_exp_f32_e32 v146, v146
	v_exp_f32_e32 v147, v147
	v_pk_add_f32 v[140:141], v[140:141], 1.0 op_sel_hi:[1,0]
	v_pk_add_f32 v[142:143], v[142:143], 1.0 op_sel_hi:[1,0]
	v_pk_add_f32 v[144:145], v[144:145], 1.0 op_sel_hi:[1,0]
	v_pk_add_f32 v[146:147], v[146:147], 1.0 op_sel_hi:[1,0]
	v_rcp_f32_e32 v140, v140
	v_rcp_f32_e32 v141, v141
	v_rcp_f32_e32 v142, v142
	v_rcp_f32_e32 v143, v143
	v_rcp_f32_e32 v144, v144
	v_rcp_f32_e32 v145, v145
	v_rcp_f32_e32 v146, v146
	v_rcp_f32_e32 v147, v147
	s_waitcnt vmcnt(16)
; __device__ __forceinline__ float sigmoidf_(float x) { return 1.f / (1.f + __expf(-x)); }
; __device__ __forceinline__ pg8::u32x4 pack8(const f32x4 a, const f32x4 b) { pg8::u32x4 w; w.x = pg8::cvt_pk_bf16(a[0], a[1]); w.y = pg8::cvt_pk_bf16(a[2], a[3]); w.z = pg8::cvt_pk_bf16(b[0], b[1]); w.w = pg8::cvt_pk_bf16(b[2], b[3]); return w; }
; #define EPI_FOREACH(...) _Pragma("unroll") for (int ai = 0; ai < 2; ++ai) _Pragma("unroll") for (int m = 0; m < 4; ++m) _Pragma("unroll") for (int bj = 0; bj < 2; ++bj) { \
;         const int row = u.pm * 256 + ai * 128 + wr * 64 + m * 16 + fr, col = u.pn * 256 + bj * 128 + wc * 32 + 8 * fq; const f32x4 v0 = acc[ai][bj][m][0], v1 = acc[ai][bj][m][1]; (void)row; (void)col; __VA_ARGS__ }
;     __device__ __forceinline__ void operator()(const f32x4 (&acc)[2][2][4][2], const pg8::Unit& u, int wr, int wc, int fr, int fq) const {
;     ...
;         else { EPI_FOREACH( f32x4 y0, y1; unpack8(stash[((ai * 4 + m) * 2 + bj) * NT + tid], y0, y1); f32x4 t0, t1;
;                 _Pragma("unroll") for (int q = 0; q < 4; ++q) { t0[q] = sigmoidf_(v0[q]) * y0[q]; t1[q] = sigmoidf_(v1[q]) * y1[q]; }
;                 pg8::u32x4* mp = (pg8::u32x4*)((u.kind == 2 && u.aux != 0 ? PMp + (size_t)(u.aux - 1) * RC * DM - (size_t)RL * DM : MMp) + (size_t)row * DM + col);
;                 if (u.kind == 1 && u.aux != 0) { f32x4 p0, p1; unpack8(*mp, p0, p1); t0 += p0; t1 += p1; }
;                 *mp = pack8(t0, t1); ) }
	v_lshlrev_b32_e32 v148, 16, v204
	v_and_b32_e32 v149, 0xffff0000, v204
	v_lshlrev_b32_e32 v150, 16, v205
	v_and_b32_e32 v151, 0xffff0000, v205
	v_lshlrev_b32_e32 v168, 16, v206
	v_and_b32_e32 v169, 0xffff0000, v206
	v_lshlrev_b32_e32 v170, 16, v207
	v_and_b32_e32 v171, 0xffff0000, v207
	v_pk_mul_f32 v[140:141], v[140:141], v[148:149]
	v_pk_mul_f32 v[142:143], v[142:143], v[150:151]
	v_pk_mul_f32 v[144:145], v[144:145], v[168:169]
	v_pk_mul_f32 v[146:147], v[146:147], v[170:171]
	v_lshlrev_b32_e32 v148, 16, v208
	v_and_b32_e32 v149, 0xffff0000, v208
	v_lshlrev_b32_e32 v150, 16, v209
	v_and_b32_e32 v151, 0xffff0000, v209
	v_lshlrev_b32_e32 v168, 16, v210
	v_and_b32_e32 v169, 0xffff0000, v210
	v_lshlrev_b32_e32 v170, 16, v211
	v_and_b32_e32 v171, 0xffff0000, v211
	v_pk_add_f32 v[140:141], v[140:141], v[148:149]
	v_pk_add_f32 v[142:143], v[142:143], v[150:151]
	v_pk_add_f32 v[144:145], v[144:145], v[168:169]
	v_pk_add_f32 v[146:147], v[146:147], v[170:171]
	v_cvt_pk_bf16_f32 v176, v140, v141
	v_cvt_pk_bf16_f32 v177, v142, v143
	v_cvt_pk_bf16_f32 v178, v144, v145
	v_cvt_pk_bf16_f32 v179, v146, v147
	s_add_u32 s10, s16, 0x1e000
	s_addc_u32 s11, s17, 0
	global_load_dwordx4 v[204:207], v138, s[10:11]
	s_add_u32 s6, s98, 0x58000
	s_addc_u32 s7, s99, 0
	global_load_dwordx4 v[208:211], v139, s[6:7] offset:256
	s_add_u32 s8, s98, 0x40000
	s_addc_u32 s9, s99, 0
	global_store_dwordx4 v139, v[176:179], s[8:9] offset:256
	v_pk_mul_f32 v[140:141], v[54:55], s[4:5] op_sel_hi:[1,0]
	v_pk_mul_f32 v[142:143], v[56:57], s[4:5] op_sel_hi:[1,0]
	v_pk_mul_f32 v[144:145], v[46:47], s[4:5] op_sel_hi:[1,0]
	v_pk_mul_f32 v[146:147], v[48:49], s[4:5] op_sel_hi:[1,0]
	v_exp_f32_e32 v140, v140
	v_exp_f32_e32 v141, v141
	v_exp_f32_e32 v142, v142
	v_exp_f32_e32 v143, v143
	v_exp_f32_e32 v144, v144
	v_exp_f32_e32 v145, v145
	v_exp_f32_e32 v146, v146
	v_exp_f32_e32 v147, v147
	v_pk_add_f32 v[140:141], v[140:141], 1.0 op_sel_hi:[1,0]
	v_pk_add_f32 v[142:143], v[142:143], 1.0 op_sel_hi:[1,0]
	v_pk_add_f32 v[144:145], v[144:145], 1.0 op_sel_hi:[1,0]
	v_pk_add_f32 v[146:147], v[146:147], 1.0 op_sel_hi:[1,0]
	v_rcp_f32_e32 v140, v140
	v_rcp_f32_e32 v141, v141
	v_rcp_f32_e32 v142, v142
	v_rcp_f32_e32 v143, v143
	v_rcp_f32_e32 v144, v144
	v_rcp_f32_e32 v145, v145
	v_rcp_f32_e32 v146, v146
	v_rcp_f32_e32 v147, v147
	s_waitcnt vmcnt(16)
	v_lshlrev_b32_e32 v148, 16, v212
	v_and_b32_e32 v149, 0xffff0000, v212
	v_lshlrev_b32_e32 v150, 16, v213
	v_and_b32_e32 v151, 0xffff0000, v213
	v_lshlrev_b32_e32 v168, 16, v214
	v_and_b32_e32 v169, 0xffff0000, v214
	v_lshlrev_b32_e32 v170, 16, v215
	v_and_b32_e32 v171, 0xffff0000, v215
	v_pk_mul_f32 v[140:141], v[140:141], v[148:149]
	v_pk_mul_f32 v[142:143], v[142:143], v[150:151]
	v_pk_mul_f32 v[144:145], v[144:145], v[168:169]
	v_pk_mul_f32 v[146:147], v[146:147], v[170:171]
	v_lshlrev_b32_e32 v148, 16, v216
	v_and_b32_e32 v149, 0xffff0000, v216
	v_lshlrev_b32_e32 v150, 16, v217
	v_and_b32_e32 v151, 0xffff0000, v217
	v_lshlrev_b32_e32 v168, 16, v218
	v_and_b32_e32 v169, 0xffff0000, v218
	v_lshlrev_b32_e32 v170, 16, v219
	v_and_b32_e32 v171, 0xffff0000, v219
	v_pk_add_f32 v[140:141], v[140:141], v[148:149]
	v_pk_add_f32 v[142:143], v[142:143], v[150:151]
	v_pk_add_f32 v[144:145], v[144:145], v[168:169]
	v_pk_add_f32 v[146:147], v[146:147], v[170:171]
	v_cvt_pk_bf16_f32 v172, v140, v141
	v_cvt_pk_bf16_f32 v173, v142, v143
	v_cvt_pk_bf16_f32 v174, v144, v145
	v_cvt_pk_bf16_f32 v175, v146, v147
	s_add_u32 s8, s98, 0x48000
	s_addc_u32 s9, s99, 0
	global_store_dwordx4 v139, v[172:175], s[8:9]
	v_pk_mul_f32 v[140:141], v[34:35], s[4:5] op_sel_hi:[1,0]
	v_pk_mul_f32 v[142:143], v[36:37], s[4:5] op_sel_hi:[1,0]
	v_pk_mul_f32 v[144:145], v[26:27], s[4:5] op_sel_hi:[1,0]
	v_pk_mul_f32 v[146:147], v[28:29], s[4:5] op_sel_hi:[1,0]
	v_exp_f32_e32 v140, v140
	v_exp_f32_e32 v141, v141
	v_exp_f32_e32 v142, v142
	v_exp_f32_e32 v143, v143
	v_exp_f32_e32 v144, v144
	v_exp_f32_e32 v145, v145
	v_exp_f32_e32 v146, v146
	v_exp_f32_e32 v147, v147
	v_pk_add_f32 v[140:141], v[140:141], 1.0 op_sel_hi:[1,0]
	v_pk_add_f32 v[142:143], v[142:143], 1.0 op_sel_hi:[1,0]
	v_pk_add_f32 v[144:145], v[144:145], 1.0 op_sel_hi:[1,0]
	v_pk_add_f32 v[146:147], v[146:147], 1.0 op_sel_hi:[1,0]
	v_rcp_f32_e32 v140, v140
	v_rcp_f32_e32 v141, v141
	v_rcp_f32_e32 v142, v142
	v_rcp_f32_e32 v143, v143
	v_rcp_f32_e32 v144, v144
	v_rcp_f32_e32 v145, v145
	v_rcp_f32_e32 v146, v146
	v_rcp_f32_e32 v147, v147
	s_waitcnt vmcnt(14)
	v_lshlrev_b32_e32 v148, 16, v220
	v_and_b32_e32 v149, 0xffff0000, v220
	v_lshlrev_b32_e32 v150, 16, v221
	v_and_b32_e32 v151, 0xffff0000, v221
	v_lshlrev_b32_e32 v168, 16, v222
	v_and_b32_e32 v169, 0xffff0000, v222
	v_lshlrev_b32_e32 v170, 16, v223
	v_and_b32_e32 v171, 0xffff0000, v223
	v_pk_mul_f32 v[140:141], v[140:141], v[148:149]
	v_pk_mul_f32 v[142:143], v[142:143], v[150:151]
	v_pk_mul_f32 v[144:145], v[144:145], v[168:169]
	v_pk_mul_f32 v[146:147], v[146:147], v[170:171]
	v_lshlrev_b32_e32 v148, 16, v224
	v_and_b32_e32 v149, 0xffff0000, v224
	v_lshlrev_b32_e32 v150, 16, v225
	v_and_b32_e32 v151, 0xffff0000, v225
	v_lshlrev_b32_e32 v168, 16, v226
	v_and_b32_e32 v169, 0xffff0000, v226
	v_lshlrev_b32_e32 v170, 16, v227
	v_and_b32_e32 v171, 0xffff0000, v227
	v_pk_add_f32 v[140:141], v[140:141], v[148:149]
	v_pk_add_f32 v[142:143], v[142:143], v[150:151]
	v_pk_add_f32 v[144:145], v[144:145], v[168:169]
	v_pk_add_f32 v[146:147], v[146:147], v[170:171]
	v_cvt_pk_bf16_f32 v176, v140, v141
	v_cvt_pk_bf16_f32 v177, v142, v143
	v_cvt_pk_bf16_f32 v178, v144, v145
	v_cvt_pk_bf16_f32 v179, v146, v147
	s_add_u32 s8, s98, 0x48000
	s_addc_u32 s9, s99, 0
	global_store_dwordx4 v139, v[176:179], s[8:9] offset:256
	v_pk_mul_f32 v[140:141], v[38:39], s[4:5] op_sel_hi:[1,0]
	v_pk_mul_f32 v[142:143], v[40:41], s[4:5] op_sel_hi:[1,0]
	v_pk_mul_f32 v[144:145], v[30:31], s[4:5] op_sel_hi:[1,0]
	v_pk_mul_f32 v[146:147], v[32:33], s[4:5] op_sel_hi:[1,0]
	v_exp_f32_e32 v140, v140
	v_exp_f32_e32 v141, v141
	v_exp_f32_e32 v142, v142
	v_exp_f32_e32 v143, v143
	v_exp_f32_e32 v144, v144
	v_exp_f32_e32 v145, v145
	v_exp_f32_e32 v146, v146
	v_exp_f32_e32 v147, v147
	v_pk_add_f32 v[140:141], v[140:141], 1.0 op_sel_hi:[1,0]
	v_pk_add_f32 v[142:143], v[142:143], 1.0 op_sel_hi:[1,0]
	v_pk_add_f32 v[144:145], v[144:145], 1.0 op_sel_hi:[1,0]
	v_pk_add_f32 v[146:147], v[146:147], 1.0 op_sel_hi:[1,0]
	v_rcp_f32_e32 v140, v140
	v_rcp_f32_e32 v141, v141
	v_rcp_f32_e32 v142, v142
	v_rcp_f32_e32 v143, v143
	v_rcp_f32_e32 v144, v144
	v_rcp_f32_e32 v145, v145
	v_rcp_f32_e32 v146, v146
	v_rcp_f32_e32 v147, v147
	s_waitcnt vmcnt(12)
; __device__ __forceinline__ float sigmoidf_(float x) { return 1.f / (1.f + __expf(-x)); }
; __device__ __forceinline__ pg8::u32x4 pack8(const f32x4 a, const f32x4 b) { pg8::u32x4 w; w.x = pg8::cvt_pk_bf16(a[0], a[1]); w.y = pg8::cvt_pk_bf16(a[2], a[3]); w.z = pg8::cvt_pk_bf16(b[0], b[1]); w.w = pg8::cvt_pk_bf16(b[2], b[3]); return w; }
; #define EPI_FOREACH(...) _Pragma("unroll") for (int ai = 0; ai < 2; ++ai) _Pragma("unroll") for (int m = 0; m < 4; ++m) _Pragma("unroll") for (int bj = 0; bj < 2; ++bj) { \
;         const int row = u.pm * 256 + ai * 128 + wr * 64 + m * 16 + fr, col = u.pn * 256 + bj * 128 + wc * 32 + 8 * fq; const f32x4 v0 = acc[ai][bj][m][0], v1 = acc[ai][bj][m][1]; (void)row; (void)col; __VA_ARGS__ }
;     __device__ __forceinline__ void operator()(const f32x4 (&acc)[2][2][4][2], const pg8::Unit& u, int wr, int wc, int fr, int fq) const {
;     ...
;         else { EPI_FOREACH( f32x4 y0, y1; unpack8(stash[((ai * 4 + m) * 2 + bj) * NT + tid], y0, y1); f32x4 t0, t1;
;                 _Pragma("unroll") for (int q = 0; q < 4; ++q) { t0[q] = sigmoidf_(v0[q]) * y0[q]; t1[q] = sigmoidf_(v1[q]) * y1[q]; }
;                 pg8::u32x4* mp = (pg8::u32x4*)((u.kind == 2 && u.aux != 0 ? PMp + (size_t)(u.aux - 1) * RC * DM - (size_t)RL * DM : MMp) + (size_t)row * DM + col);
;                 if (u.kind == 1 && u.aux != 0) { f32x4 p0, p1; unpack8(*mp, p0, p1); t0 += p0; t1 += p1; }
;                 *mp = pack8(t0, t1); ) }
	v_lshlrev_b32_e32 v148, 16, v180
	v_and_b32_e32 v149, 0xffff0000, v180
	v_lshlrev_b32_e32 v150, 16, v181
	v_and_b32_e32 v151, 0xffff0000, v181
	v_lshlrev_b32_e32 v168, 16, v182
	v_and_b32_e32 v169, 0xffff0000, v182
	v_lshlrev_b32_e32 v170, 16, v183
	v_and_b32_e32 v171, 0xffff0000, v183
	v_pk_mul_f32 v[140:141], v[140:141], v[148:149]
	v_pk_mul_f32 v[142:143], v[142:143], v[150:151]
	v_pk_mul_f32 v[144:145], v[144:145], v[168:169]
	v_pk_mul_f32 v[146:147], v[146:147], v[170:171]
	v_lshlrev_b32_e32 v148, 16, v184
	v_and_b32_e32 v149, 0xffff0000, v184
	v_lshlrev_b32_e32 v150, 16, v185
	v_and_b32_e32 v151, 0xffff0000, v185
	v_lshlrev_b32_e32 v168, 16, v186
	v_and_b32_e32 v169, 0xffff0000, v186
	v_lshlrev_b32_e32 v170, 16, v187
	v_and_b32_e32 v171, 0xffff0000, v187
	v_pk_add_f32 v[140:141], v[140:141], v[148:149]
	v_pk_add_f32 v[142:143], v[142:143], v[150:151]
	v_pk_add_f32 v[144:145], v[144:145], v[168:169]
	v_pk_add_f32 v[146:147], v[146:147], v[170:171]
	v_cvt_pk_bf16_f32 v172, v140, v141
	v_cvt_pk_bf16_f32 v173, v142, v143
	v_cvt_pk_bf16_f32 v174, v144, v145
	v_cvt_pk_bf16_f32 v175, v146, v147
	s_add_u32 s8, s98, 0x50000
	s_addc_u32 s9, s99, 0
	global_store_dwordx4 v139, v[172:175], s[8:9]
	v_pk_mul_f32 v[140:141], v[18:19], s[4:5] op_sel_hi:[1,0]
	v_pk_mul_f32 v[142:143], v[20:21], s[4:5] op_sel_hi:[1,0]
	v_pk_mul_f32 v[144:145], v[10:11], s[4:5] op_sel_hi:[1,0]
	v_pk_mul_f32 v[146:147], v[12:13], s[4:5] op_sel_hi:[1,0]
	v_exp_f32_e32 v140, v140
	v_exp_f32_e32 v141, v141
	v_exp_f32_e32 v142, v142
	v_exp_f32_e32 v143, v143
	v_exp_f32_e32 v144, v144
	v_exp_f32_e32 v145, v145
	v_exp_f32_e32 v146, v146
	v_exp_f32_e32 v147, v147
	v_pk_add_f32 v[140:141], v[140:141], 1.0 op_sel_hi:[1,0]
	v_pk_add_f32 v[142:143], v[142:143], 1.0 op_sel_hi:[1,0]
	v_pk_add_f32 v[144:145], v[144:145], 1.0 op_sel_hi:[1,0]
	v_pk_add_f32 v[146:147], v[146:147], 1.0 op_sel_hi:[1,0]
	v_rcp_f32_e32 v140, v140
	v_rcp_f32_e32 v141, v141
	v_rcp_f32_e32 v142, v142
	v_rcp_f32_e32 v143, v143
	v_rcp_f32_e32 v144, v144
	v_rcp_f32_e32 v145, v145
	v_rcp_f32_e32 v146, v146
	v_rcp_f32_e32 v147, v147
	s_waitcnt vmcnt(10)
	v_lshlrev_b32_e32 v148, 16, v188
	v_and_b32_e32 v149, 0xffff0000, v188
	v_lshlrev_b32_e32 v150, 16, v189
	v_and_b32_e32 v151, 0xffff0000, v189
	v_lshlrev_b32_e32 v168, 16, v190
	v_and_b32_e32 v169, 0xffff0000, v190
	v_lshlrev_b32_e32 v170, 16, v191
	v_and_b32_e32 v171, 0xffff0000, v191
	v_pk_mul_f32 v[140:141], v[140:141], v[148:149]
	v_pk_mul_f32 v[142:143], v[142:143], v[150:151]
	v_pk_mul_f32 v[144:145], v[144:145], v[168:169]
	v_pk_mul_f32 v[146:147], v[146:147], v[170:171]
	v_lshlrev_b32_e32 v148, 16, v192
	v_and_b32_e32 v149, 0xffff0000, v192
	v_lshlrev_b32_e32 v150, 16, v193
	v_and_b32_e32 v151, 0xffff0000, v193
	v_lshlrev_b32_e32 v168, 16, v194
	v_and_b32_e32 v169, 0xffff0000, v194
	v_lshlrev_b32_e32 v170, 16, v195
	v_and_b32_e32 v171, 0xffff0000, v195
	v_pk_add_f32 v[140:141], v[140:141], v[148:149]
	v_pk_add_f32 v[142:143], v[142:143], v[150:151]
	v_pk_add_f32 v[144:145], v[144:145], v[168:169]
	v_pk_add_f32 v[146:147], v[146:147], v[170:171]
	v_cvt_pk_bf16_f32 v176, v140, v141
	v_cvt_pk_bf16_f32 v177, v142, v143
	v_cvt_pk_bf16_f32 v178, v144, v145
	v_cvt_pk_bf16_f32 v179, v146, v147
	s_add_u32 s8, s98, 0x50000
	s_addc_u32 s9, s99, 0
	global_store_dwordx4 v139, v[176:179], s[8:9] offset:256
	v_pk_mul_f32 v[140:141], v[22:23], s[4:5] op_sel_hi:[1,0]
	v_pk_mul_f32 v[142:143], v[24:25], s[4:5] op_sel_hi:[1,0]
	v_pk_mul_f32 v[144:145], v[14:15], s[4:5] op_sel_hi:[1,0]
	v_pk_mul_f32 v[146:147], v[16:17], s[4:5] op_sel_hi:[1,0]
	v_exp_f32_e32 v140, v140
	v_exp_f32_e32 v141, v141
	v_exp_f32_e32 v142, v142
	v_exp_f32_e32 v143, v143
	v_exp_f32_e32 v144, v144
	v_exp_f32_e32 v145, v145
	v_exp_f32_e32 v146, v146
	v_exp_f32_e32 v147, v147
	v_pk_add_f32 v[140:141], v[140:141], 1.0 op_sel_hi:[1,0]
	v_pk_add_f32 v[142:143], v[142:143], 1.0 op_sel_hi:[1,0]
	v_pk_add_f32 v[144:145], v[144:145], 1.0 op_sel_hi:[1,0]
	v_pk_add_f32 v[146:147], v[146:147], 1.0 op_sel_hi:[1,0]
	v_rcp_f32_e32 v140, v140
	v_rcp_f32_e32 v141, v141
	v_rcp_f32_e32 v142, v142
	v_rcp_f32_e32 v143, v143
	v_rcp_f32_e32 v144, v144
	v_rcp_f32_e32 v145, v145
	v_rcp_f32_e32 v146, v146
	v_rcp_f32_e32 v147, v147
	s_waitcnt vmcnt(8)
; __device__ __forceinline__ float sigmoidf_(float x) { return 1.f / (1.f + __expf(-x)); }
; __device__ __forceinline__ pg8::u32x4 pack8(const f32x4 a, const f32x4 b) { pg8::u32x4 w; w.x = pg8::cvt_pk_bf16(a[0], a[1]); w.y = pg8::cvt_pk_bf16(a[2], a[3]); w.z = pg8::cvt_pk_bf16(b[0], b[1]); w.w = pg8::cvt_pk_bf16(b[2], b[3]); return w; }
; #define EPI_FOREACH(...) _Pragma("unroll") for (int ai = 0; ai < 2; ++ai) _Pragma("unroll") for (int m = 0; m < 4; ++m) _Pragma("unroll") for (int bj = 0; bj < 2; ++bj) { \
;         const int row = u.pm * 256 + ai * 128 + wr * 64 + m * 16 + fr, col = u.pn * 256 + bj * 128 + wc * 32 + 8 * fq; const f32x4 v0 = acc[ai][bj][m][0], v1 = acc[ai][bj][m][1]; (void)row; (void)col; __VA_ARGS__ }
;     __device__ __forceinline__ void operator()(const f32x4 (&acc)[2][2][4][2], const pg8::Unit& u, int wr, int wc, int fr, int fq) const {
;     ...
;         else { EPI_FOREACH( f32x4 y0, y1; unpack8(stash[((ai * 4 + m) * 2 + bj) * NT + tid], y0, y1); f32x4 t0, t1;
;                 _Pragma("unroll") for (int q = 0; q < 4; ++q) { t0[q] = sigmoidf_(v0[q]) * y0[q]; t1[q] = sigmoidf_(v1[q]) * y1[q]; }
;                 pg8::u32x4* mp = (pg8::u32x4*)((u.kind == 2 && u.aux != 0 ? PMp + (size_t)(u.aux - 1) * RC * DM - (size_t)RL * DM : MMp) + (size_t)row * DM + col);
;                 if (u.kind == 1 && u.aux != 0) { f32x4 p0, p1; unpack8(*mp, p0, p1); t0 += p0; t1 += p1; }
;                 *mp = pack8(t0, t1); ) }
	v_lshlrev_b32_e32 v148, 16, v196
	v_and_b32_e32 v149, 0xffff0000, v196
	v_lshlrev_b32_e32 v150, 16, v197
	v_and_b32_e32 v151, 0xffff0000, v197
	v_lshlrev_b32_e32 v168, 16, v198
	v_and_b32_e32 v169, 0xffff0000, v198
	v_lshlrev_b32_e32 v170, 16, v199
	v_and_b32_e32 v171, 0xffff0000, v199
	v_pk_mul_f32 v[140:141], v[140:141], v[148:149]
	v_pk_mul_f32 v[142:143], v[142:143], v[150:151]
	v_pk_mul_f32 v[144:145], v[144:145], v[168:169]
	v_pk_mul_f32 v[146:147], v[146:147], v[170:171]
	v_lshlrev_b32_e32 v148, 16, v200
	v_and_b32_e32 v149, 0xffff0000, v200
	v_lshlrev_b32_e32 v150, 16, v201
	v_and_b32_e32 v151, 0xffff0000, v201
	v_lshlrev_b32_e32 v168, 16, v202
	v_and_b32_e32 v169, 0xffff0000, v202
	v_lshlrev_b32_e32 v170, 16, v203
	v_and_b32_e32 v171, 0xffff0000, v203
	v_pk_add_f32 v[140:141], v[140:141], v[148:149]
	v_pk_add_f32 v[142:143], v[142:143], v[150:151]
	v_pk_add_f32 v[144:145], v[144:145], v[168:169]
	v_pk_add_f32 v[146:147], v[146:147], v[170:171]
	v_cvt_pk_bf16_f32 v172, v140, v141
	v_cvt_pk_bf16_f32 v173, v142, v143
	v_cvt_pk_bf16_f32 v174, v144, v145
	v_cvt_pk_bf16_f32 v175, v146, v147
	s_add_u32 s8, s98, 0x58000
	s_addc_u32 s9, s99, 0
	global_store_dwordx4 v139, v[172:175], s[8:9]
	v_pk_mul_f32 v[140:141], v[6:7], s[4:5] op_sel_hi:[1,0]
	v_pk_mul_f32 v[142:143], v[8:9], s[4:5] op_sel_hi:[1,0]
	v_pk_mul_f32 v[144:145], v[2:3], s[4:5] op_sel_hi:[1,0]
	v_pk_mul_f32 v[146:147], v[4:5], s[4:5] op_sel_hi:[1,0]
	v_exp_f32_e32 v140, v140
	v_exp_f32_e32 v141, v141
	v_exp_f32_e32 v142, v142
	v_exp_f32_e32 v143, v143
	v_exp_f32_e32 v144, v144
	v_exp_f32_e32 v145, v145
	v_exp_f32_e32 v146, v146
	v_exp_f32_e32 v147, v147
	v_pk_add_f32 v[140:141], v[140:141], 1.0 op_sel_hi:[1,0]
	v_pk_add_f32 v[142:143], v[142:143], 1.0 op_sel_hi:[1,0]
	v_pk_add_f32 v[144:145], v[144:145], 1.0 op_sel_hi:[1,0]
	v_pk_add_f32 v[146:147], v[146:147], 1.0 op_sel_hi:[1,0]
	v_rcp_f32_e32 v140, v140
	v_rcp_f32_e32 v141, v141
	v_rcp_f32_e32 v142, v142
	v_rcp_f32_e32 v143, v143
	v_rcp_f32_e32 v144, v144
	v_rcp_f32_e32 v145, v145
	v_rcp_f32_e32 v146, v146
	v_rcp_f32_e32 v147, v147
	s_waitcnt vmcnt(6)
	v_lshlrev_b32_e32 v148, 16, v204
	v_and_b32_e32 v149, 0xffff0000, v204
	v_lshlrev_b32_e32 v150, 16, v205
	v_and_b32_e32 v151, 0xffff0000, v205
	v_lshlrev_b32_e32 v168, 16, v206
	v_and_b32_e32 v169, 0xffff0000, v206
	v_lshlrev_b32_e32 v170, 16, v207
	v_and_b32_e32 v171, 0xffff0000, v207
	v_pk_mul_f32 v[140:141], v[140:141], v[148:149]
	v_pk_mul_f32 v[142:143], v[142:143], v[150:151]
	v_pk_mul_f32 v[144:145], v[144:145], v[168:169]
	v_pk_mul_f32 v[146:147], v[146:147], v[170:171]
	v_lshlrev_b32_e32 v148, 16, v208
	v_and_b32_e32 v149, 0xffff0000, v208
	v_lshlrev_b32_e32 v150, 16, v209
	v_and_b32_e32 v151, 0xffff0000, v209
	v_lshlrev_b32_e32 v168, 16, v210
	v_and_b32_e32 v169, 0xffff0000, v210
	v_lshlrev_b32_e32 v170, 16, v211
	v_and_b32_e32 v171, 0xffff0000, v211
	v_pk_add_f32 v[140:141], v[140:141], v[148:149]
	v_pk_add_f32 v[142:143], v[142:143], v[150:151]
	v_pk_add_f32 v[144:145], v[144:145], v[168:169]
	v_pk_add_f32 v[146:147], v[146:147], v[170:171]
	v_cvt_pk_bf16_f32 v176, v140, v141
	v_cvt_pk_bf16_f32 v177, v142, v143
	v_cvt_pk_bf16_f32 v178, v144, v145
	v_cvt_pk_bf16_f32 v179, v146, v147
	s_add_u32 s8, s98, 0x58000
	s_addc_u32 s9, s99, 0
	global_store_dwordx4 v139, v[176:179], s[8:9] offset:256
	s_branch .Lmrg1_done

; __device__ __forceinline__ float sigmoidf_(float x) { return 1.f / (1.f + __expf(-x)); }
; __device__ __forceinline__ pg8::u32x4 pack8(const f32x4 a, const f32x4 b) { pg8::u32x4 w; w.x = pg8::cvt_pk_bf16(a[0], a[1]); w.y = pg8::cvt_pk_bf16(a[2], a[3]); w.z = pg8::cvt_pk_bf16(b[0], b[1]); w.w = pg8::cvt_pk_bf16(b[2], b[3]); return w; }
; #define EPI_FOREACH(...) _Pragma("unroll") for (int ai = 0; ai < 2; ++ai) _Pragma("unroll") for (int m = 0; m < 4; ++m) _Pragma("unroll") for (int bj = 0; bj < 2; ++bj) { \
;         const int row = u.pm * 256 + ai * 128 + wr * 64 + m * 16 + fr, col = u.pn * 256 + bj * 128 + wc * 32 + 8 * fq; const f32x4 v0 = acc[ai][bj][m][0], v1 = acc[ai][bj][m][1]; (void)row; (void)col; __VA_ARGS__ }
;     __device__ __forceinline__ void operator()(const f32x4 (&acc)[2][2][4][2], const pg8::Unit& u, int wr, int wc, int fr, int fq) const {
;     ...
;         if (u.kind == 0) { EPI_FOREACH( stash[((ai * 4 + m) * 2 + bj) * NT + tid] = pack8(v0, v1); if (bj && (m & 1)) asm volatile("" ::: "memory"); ) }
;         else { EPI_FOREACH( f32x4 y0, y1; unpack8(stash[((ai * 4 + m) * 2 + bj) * NT + tid], y0, y1); f32x4 t0, t1;
;                 _Pragma("unroll") for (int q = 0; q < 4; ++q) { t0[q] = sigmoidf_(v0[q]) * y0[q]; t1[q] = sigmoidf_(v1[q]) * y1[q]; }
;                 pg8::u32x4* mp = (pg8::u32x4*)((u.kind == 2 && u.aux != 0 ? PMp + (size_t)(u.aux - 1) * RC * DM - (size_t)RL * DM : MMp) + (size_t)row * DM + col);
;                 if (u.kind == 1 && u.aux != 0) { f32x4 p0, p1; unpack8(*mp, p0, p1); t0 += p0; t1 += p1; }
;                 *mp = pack8(t0, t1); ) }
.Lmrg1_done:
	s_branch .LBB0_3150
.LBB0_3149:
	v_cvt_pk_bf16_f32 v126, v126, v127
	v_cvt_pk_bf16_f32 v127, v128, v129
	v_cvt_pk_bf16_f32 v128, v122, v123
	v_lshl_add_u64 v[122:123], v[136:137], 4, s[16:17]
	v_cvt_pk_bf16_f32 v129, v124, v125
	global_store_dwordx4 v[122:123], v[126:129], off
	v_cvt_pk_bf16_f32 v114, v114, v115
	v_cvt_pk_bf16_f32 v115, v116, v117
	v_cvt_pk_bf16_f32 v116, v106, v107
	v_add_co_u32_e32 v106, vcc, s57, v122
	v_cvt_pk_bf16_f32 v117, v108, v109
	s_nop 1
	v_addc_co_u32_e32 v107, vcc, 0, v123, vcc
	global_store_dwordx4 v[106:107], v[114:117], off
	v_cvt_pk_bf16_f32 v106, v118, v119
	v_cvt_pk_bf16_f32 v107, v120, v121
	v_cvt_pk_bf16_f32 v108, v110, v111
	v_add_co_u32_e32 v110, vcc, s58, v122
	v_cvt_pk_bf16_f32 v109, v112, v113
	s_nop 1
	v_addc_co_u32_e32 v111, vcc, 0, v123, vcc
	global_store_dwordx4 v[110:111], v[106:109], off
	v_cvt_pk_bf16_f32 v98, v98, v99
	v_cvt_pk_bf16_f32 v99, v100, v101
	v_cvt_pk_bf16_f32 v100, v90, v91
	v_add_co_u32_e32 v90, vcc, s59, v122
	v_cvt_pk_bf16_f32 v101, v92, v93
	s_nop 1
	v_addc_co_u32_e32 v91, vcc, 0, v123, vcc
	global_store_dwordx4 v[90:91], v[98:101], off
	v_cvt_pk_bf16_f32 v90, v102, v103
	v_cvt_pk_bf16_f32 v91, v104, v105
	v_cvt_pk_bf16_f32 v92, v94, v95
	v_add_co_u32_e32 v94, vcc, s70, v122
	v_cvt_pk_bf16_f32 v93, v96, v97
	s_nop 1
	v_addc_co_u32_e32 v95, vcc, 0, v123, vcc
	global_store_dwordx4 v[94:95], v[90:93], off
	v_cvt_pk_bf16_f32 v82, v82, v83
	v_cvt_pk_bf16_f32 v83, v84, v85
	v_cvt_pk_bf16_f32 v84, v74, v75
	v_add_co_u32_e32 v74, vcc, s71, v122
	v_cvt_pk_bf16_f32 v85, v76, v77
	s_nop 1
	v_addc_co_u32_e32 v75, vcc, 0, v123, vcc
	global_store_dwordx4 v[74:75], v[82:85], off
	v_cvt_pk_bf16_f32 v74, v86, v87
	v_cvt_pk_bf16_f32 v75, v88, v89
	v_cvt_pk_bf16_f32 v76, v78, v79
	v_add_co_u32_e32 v78, vcc, s76, v122
	v_cvt_pk_bf16_f32 v77, v80, v81
	s_nop 1
	v_addc_co_u32_e32 v79, vcc, 0, v123, vcc
	global_store_dwordx4 v[78:79], v[74:77], off
	v_cvt_pk_bf16_f32 v70, v70, v71
	v_cvt_pk_bf16_f32 v71, v72, v73
	v_cvt_pk_bf16_f32 v72, v66, v67
	v_add_co_u32_e32 v66, vcc, s77, v122
	v_cvt_pk_bf16_f32 v73, v68, v69
	s_nop 1
	v_addc_co_u32_e32 v67, vcc, 0, v123, vcc
	global_store_dwordx4 v[66:67], v[70:73], off
	v_cvt_pk_bf16_f32 v62, v62, v63
	v_cvt_pk_bf16_f32 v63, v64, v65
	v_cvt_pk_bf16_f32 v64, v58, v59
	v_add_co_u32_e32 v58, vcc, s53, v122
	v_cvt_pk_bf16_f32 v65, v60, v61
	s_nop 1
	v_addc_co_u32_e32 v59, vcc, 0, v123, vcc
	global_store_dwordx4 v[58:59], v[62:65], off
	v_cvt_pk_bf16_f32 v50, v50, v51
	v_cvt_pk_bf16_f32 v51, v52, v53
	v_cvt_pk_bf16_f32 v52, v42, v43
	v_add_co_u32_e32 v42, vcc, s54, v122
	v_cvt_pk_bf16_f32 v53, v44, v45
	s_nop 1
	v_addc_co_u32_e32 v43, vcc, 0, v123, vcc
	global_store_dwordx4 v[42:43], v[50:53], off
	v_cvt_pk_bf16_f32 v42, v54, v55
	v_cvt_pk_bf16_f32 v43, v56, v57
	v_cvt_pk_bf16_f32 v44, v46, v47
	v_add_co_u32_e32 v46, vcc, s55, v122
	v_cvt_pk_bf16_f32 v45, v48, v49
	s_nop 1
	v_addc_co_u32_e32 v47, vcc, 0, v123, vcc
	global_store_dwordx4 v[46:47], v[42:45], off
	v_cvt_pk_bf16_f32 v34, v34, v35
	v_cvt_pk_bf16_f32 v35, v36, v37
	v_cvt_pk_bf16_f32 v36, v26, v27
	v_add_co_u32_e32 v26, vcc, s56, v122
	v_cvt_pk_bf16_f32 v37, v28, v29
	s_nop 1
	v_addc_co_u32_e32 v27, vcc, 0, v123, vcc
	global_store_dwordx4 v[26:27], v[34:37], off
	v_cvt_pk_bf16_f32 v26, v38, v39
	v_cvt_pk_bf16_f32 v27, v40, v41
	v_cvt_pk_bf16_f32 v28, v30, v31
	v_add_co_u32_e32 v30, vcc, s68, v122
	v_cvt_pk_bf16_f32 v29, v32, v33
	s_nop 1
	v_addc_co_u32_e32 v31, vcc, 0, v123, vcc
	global_store_dwordx4 v[30:31], v[26:29], off
	v_cvt_pk_bf16_f32 v18, v18, v19
	v_cvt_pk_bf16_f32 v19, v20, v21
	v_cvt_pk_bf16_f32 v20, v10, v11
	v_add_co_u32_e32 v10, vcc, s69, v122
	v_cvt_pk_bf16_f32 v21, v12, v13
	s_nop 1
	v_addc_co_u32_e32 v11, vcc, 0, v123, vcc
	global_store_dwordx4 v[10:11], v[18:21], off
	v_cvt_pk_bf16_f32 v10, v22, v23
	v_cvt_pk_bf16_f32 v11, v24, v25
	v_cvt_pk_bf16_f32 v12, v14, v15
	v_add_co_u32_e32 v14, vcc, s72, v122
	v_cvt_pk_bf16_f32 v13, v16, v17
	s_nop 1
	v_addc_co_u32_e32 v15, vcc, 0, v123, vcc
	global_store_dwordx4 v[14:15], v[10:13], off
	v_cvt_pk_bf16_f32 v6, v6, v7
	v_cvt_pk_bf16_f32 v7, v8, v9
	v_cvt_pk_bf16_f32 v8, v2, v3
	v_add_co_u32_e32 v2, vcc, 0x1e000, v122
	v_cvt_pk_bf16_f32 v9, v4, v5
	s_nop 1
	v_addc_co_u32_e32 v3, vcc, 0, v123, vcc
	global_store_dwordx4 v[2:3], v[6:9], off

; __global__ void __launch_bounds__(NT, 2) mega(Args a_unused) {
;     extern __shared__ __attribute__((aligned(16))) unsigned char lds[];
	.amdhsa_kernel _Z4mega4Args
		.amdhsa_group_segment_fixed_size 0
		.amdhsa_private_segment_fixed_size 0
		.amdhsa_kernarg_size 512
		.amdhsa_user_sgpr_count 2
		.amdhsa_user_sgpr_dispatch_ptr 0
		.amdhsa_user_sgpr_queue_ptr 0
		.amdhsa_user_sgpr_kernarg_segment_ptr 1
		.amdhsa_user_sgpr_dispatch_id 0
		.amdhsa_user_sgpr_kernarg_preload_length 0
		.amdhsa_user_sgpr_kernarg_preload_offset 0
		.amdhsa_user_sgpr_private_segment_size 0
		.amdhsa_uses_dynamic_stack 0
		.amdhsa_enable_private_segment 0
		.amdhsa_system_sgpr_workgroup_id_x 1
		.amdhsa_system_sgpr_workgroup_id_y 0
		.amdhsa_system_sgpr_workgroup_id_z 0
		.amdhsa_system_sgpr_workgroup_info 0
		.amdhsa_system_vgpr_workitem_id 0
		.amdhsa_next_free_vgpr 255
		.amdhsa_next_free_sgpr 102
		.amdhsa_accum_offset 256
		.amdhsa_reserve_vcc 1
		.amdhsa_float_round_mode_32 0
		.amdhsa_float_round_mode_16_64 0
		.amdhsa_float_denorm_mode_32 3
		.amdhsa_float_denorm_mode_16_64 3
		.amdhsa_dx10_clamp 1
		.amdhsa_ieee_mode 1
		.amdhsa_fp16_overflow 0
		.amdhsa_tg_split 0
		.amdhsa_exception_fp_ieee_invalid_op 0
		.amdhsa_exception_fp_denorm_src 0
		.amdhsa_exception_fp_ieee_div_zero 0
		.amdhsa_exception_fp_ieee_overflow 0
		.amdhsa_exception_fp_ieee_underflow 0
		.amdhsa_exception_fp_ieee_inexact 0
		.amdhsa_exception_int_div_zero 0
	.end_amdhsa_kernel

; __global__ void __launch_bounds__(NT, 2) mega(Args a_unused) {
;     extern __shared__ __attribute__((aligned(16))) unsigned char lds[];
amdhsa.kernels:
  - .agpr_count:     0
    .args:
      - .offset:         0
        .size:           256
        .value_kind:     by_value
      - .offset:         256
        .size:           4
        .value_kind:     hidden_block_count_x
      - .offset:         260
        .size:           4
        .value_kind:     hidden_block_count_y
      - .offset:         264
        .size:           4
        .value_kind:     hidden_block_count_z
      - .offset:         268
        .size:           2
        .value_kind:     hidden_group_size_x
      - .offset:         270
        .size:           2
        .value_kind:     hidden_group_size_y
      - .offset:         272
        .size:           2
        .value_kind:     hidden_group_size_z
      - .offset:         274
        .size:           2
        .value_kind:     hidden_remainder_x
      - .offset:         276
        .size:           2
        .value_kind:     hidden_remainder_y
      - .offset:         278
        .size:           2
        .value_kind:     hidden_remainder_z
      - .offset:         296
        .size:           8
        .value_kind:     hidden_global_offset_x
      - .offset:         304
        .size:           8
        .value_kind:     hidden_global_offset_y
      - .offset:         312
        .size:           8
        .value_kind:     hidden_global_offset_z
      - .offset:         320
        .size:           2
        .value_kind:     hidden_grid_dims
      - .offset:         376
        .size:           4
        .value_kind:     hidden_dynamic_lds_size
    .group_segment_fixed_size: 0
    .kernarg_segment_align: 8
    .kernarg_segment_size: 512
    .language:       OpenCL C
    .language_version:
      - 2
      - 0
    .max_flat_workgroup_size: 512
    .name:           _Z4mega4Args
    .private_segment_fixed_size: 0
    .sgpr_count: 108
    .sgpr_spill_count: 7
    .symbol:         _Z4mega4Args.kd
    .uniform_work_group_size: 1
    .uses_dynamic_stack: false
    .vgpr_count:     255
    .vgpr_spill_count: 0
    .wavefront_size: 64
